# setup phase: adaLN weight loads kept 4 iterations in flight; transpose tiles issue their 8 row loads together (one wait) instead of load-wait-store ladder; plus pipelined scan recurrence and hoisted s
# speedup vs baseline: 1.0209x; 1.0209x over previous
; #define BIDX() sgpr_opaque((int)__builtin_amdgcn_workgroup_id_x())
; DI void phase_setup(LAS unsigned char* lds) {
;     ...
;       for (int it = BIDX(); it < 4 * 48; it += G) {
;           const int l = it / 48, n0 = (it % 48) * 128; const int kp = tid >> 7, nn = tid & 127;
;           const float* w = adaw + (size_t)l * D * 6144 + n0 + nn;
;           float a[9];
; #pragma unroll
;           for (int i = 0; i < 9; ++i) a[i] = 0.f;
;           for (int k = kp * 256; k < kp * 256 + 256; ++k) { const float wv = w[(size_t)k * 6144];
; #pragma unroll
;               for (int i = 0; i < 9; ++i) a[i] = fmaf(sv[i * 1024 + k], wv, a[i]); }
.LBB0_819:
	s_mul_hi_i32 s2, s15, 0x2aaaaaab
	s_lshr_b32 s3, s2, 31
	s_ashr_i32 s16, s2, 3
	s_add_i32 s16, s16, s3
	s_mul_i32 s2, s16, 48
	s_sub_i32 s2, s15, s2
	s_lshl_b32 s10, s2, 7
	s_ashr_i32 s11, s10, 31
	s_mul_i32 s5, s16, 0x1800000
	s_lshl_b64 s[2:3], s[10:11], 2
	s_mul_hi_i32 s4, s16, 0x1800000
	s_add_u32 s2, s5, s2
	s_addc_u32 s3, s4, s3
	v_mov_b32_e32 v10, 0
	v_lshl_add_u64 v[8:9], v[6:7], 0, s[2:3]
	s_mov_b64 s[12:13], 0
	v_mov_b32_e32 v19, v0
	v_mov_b32_e32 v11, v10
	v_mov_b32_e32 v12, v10
	v_mov_b32_e32 v13, v10
	v_mov_b32_e32 v14, v10
	v_mov_b32_e32 v15, v10
	v_mov_b32_e32 v16, v10
	v_mov_b32_e32 v17, v10
	v_mov_b32_e32 v20, v10
	s_movk_i32 s3, 0x6000
	s_mov_b32 s17, 0xc000
	s_mov_b32 s4, 0x0
	s_mov_b32 s5, 0
	v_lshl_add_u64 v[22:23], v[8:9], 0, s[4:5]
	v_add_co_u32_e64 v26, s[4:5], s3, v22
	global_load_dword v74, v[22:23], off
	s_nop 0
	v_addc_co_u32_e64 v27, s[4:5], 0, v23, s[4:5]
	v_add_co_u32_e64 v28, s[4:5], s17, v22
	s_mov_b32 s2, 0x12000
	s_nop 0
	v_addc_co_u32_e64 v29, s[4:5], 0, v23, s[4:5]
	v_add_co_u32_e64 v22, s[4:5], s2, v22
	v_add_u32_e32 v21, 0x1000, v19
	s_nop 0
	v_addc_co_u32_e64 v23, s[4:5], 0, v23, s[4:5]
	global_load_dword v75, v[26:27], off
	s_nop 0
	global_load_dword v76, v[28:29], off
	s_nop 0
	global_load_dword v77, v[22:23], off
	s_mov_b32 s4, 0x18000
	s_mov_b32 s5, 0
	v_lshl_add_u64 v[22:23], v[8:9], 0, s[4:5]
	v_add_co_u32_e64 v26, s[4:5], s3, v22
	global_load_dword v86, v[22:23], off
	s_nop 0
	v_addc_co_u32_e64 v27, s[4:5], 0, v23, s[4:5]
	v_add_co_u32_e64 v28, s[4:5], s17, v22
	s_mov_b32 s2, 0x12000
	s_nop 0
	v_addc_co_u32_e64 v29, s[4:5], 0, v23, s[4:5]
	v_add_co_u32_e64 v22, s[4:5], s2, v22
	v_add_u32_e32 v21, 0x1000, v19
	s_nop 0
	v_addc_co_u32_e64 v23, s[4:5], 0, v23, s[4:5]
	global_load_dword v87, v[26:27], off
	s_nop 0
	global_load_dword v88, v[28:29], off
	s_nop 0
	global_load_dword v89, v[22:23], off
	s_mov_b32 s4, 0x30000
	s_mov_b32 s5, 0
	v_lshl_add_u64 v[22:23], v[8:9], 0, s[4:5]
	v_add_co_u32_e64 v26, s[4:5], s3, v22
	global_load_dword v90, v[22:23], off
	s_nop 0
	v_addc_co_u32_e64 v27, s[4:5], 0, v23, s[4:5]
	v_add_co_u32_e64 v28, s[4:5], s17, v22
	s_mov_b32 s2, 0x12000
	s_nop 0
	v_addc_co_u32_e64 v29, s[4:5], 0, v23, s[4:5]
	v_add_co_u32_e64 v22, s[4:5], s2, v22
	v_add_u32_e32 v21, 0x1000, v19
	s_nop 0
	v_addc_co_u32_e64 v23, s[4:5], 0, v23, s[4:5]
	global_load_dword v91, v[26:27], off
	s_nop 0
	global_load_dword v92, v[28:29], off
	s_nop 0
	global_load_dword v93, v[22:23], off
	s_mov_b32 s4, 0x48000
	s_mov_b32 s5, 0
	v_lshl_add_u64 v[22:23], v[8:9], 0, s[4:5]
	v_add_co_u32_e64 v26, s[4:5], s3, v22
	global_load_dword v94, v[22:23], off
	s_nop 0
	v_addc_co_u32_e64 v27, s[4:5], 0, v23, s[4:5]
	v_add_co_u32_e64 v28, s[4:5], s17, v22
	s_mov_b32 s2, 0x12000
	s_nop 0
	v_addc_co_u32_e64 v29, s[4:5], 0, v23, s[4:5]
	v_add_co_u32_e64 v22, s[4:5], s2, v22
	v_add_u32_e32 v21, 0x1000, v19
	s_nop 0
	v_addc_co_u32_e64 v23, s[4:5], 0, v23, s[4:5]
	global_load_dword v95, v[26:27], off
	s_nop 0
	global_load_dword v96, v[28:29], off
	s_nop 0
	global_load_dword v97, v[22:23], off
.LBB0_820:
	s_waitcnt vmcnt(12)
	v_mov_b32_e32 v78, v74
	v_mov_b32_e32 v80, v75
	v_mov_b32_e32 v82, v76
	v_mov_b32_e32 v84, v77
	s_add_u32 s4, s12, 0x60000
	s_min_u32 s4, s4, 0x5e8000
	s_mov_b32 s5, 0
	v_lshl_add_u64 v[22:23], v[8:9], 0, s[4:5]
	v_add_co_u32_e64 v26, s[4:5], s3, v22
	global_load_dword v74, v[22:23], off
	s_nop 0
	v_addc_co_u32_e64 v27, s[4:5], 0, v23, s[4:5]
	v_add_co_u32_e64 v28, s[4:5], s17, v22
	s_mov_b32 s2, 0x12000
	s_nop 0
	v_addc_co_u32_e64 v29, s[4:5], 0, v23, s[4:5]
	v_add_co_u32_e64 v22, s[4:5], s2, v22
	v_add_u32_e32 v21, 0x1000, v19
	s_nop 0
	v_addc_co_u32_e64 v23, s[4:5], 0, v23, s[4:5]
	global_load_dword v75, v[26:27], off
	s_nop 0
	global_load_dword v76, v[28:29], off
	s_nop 0
	global_load_dword v77, v[22:23], off
	ds_read2_b32 v[30:31], v19 offset1:1
	ds_read2_b32 v[32:33], v19 offset0:2 offset1:3
	v_add_u32_e32 v44, 0x6000, v19
	v_add_u32_e32 v46, 0x7000, v19
	v_add_u32_e32 v48, 0x8000, v19
	v_add_u32_e32 v50, 0x1008, v19
	v_add_u32_e32 v52, 0x2008, v19
	v_add_u32_e32 v54, 0x3008, v19
	v_add_u32_e32 v56, 0x4008, v19
	v_add_u32_e32 v58, 0x5008, v19
	v_add_u32_e32 v60, 0x6008, v19
	v_add_u32_e32 v62, 0x7008, v19
	v_add_u32_e32 v64, 0x8008, v19
	v_add_u32_e32 v25, 0x2000, v19
	v_add_u32_e32 v23, 0x3000, v19
	v_add_u32_e32 v27, 0x4000, v19
	v_add_u32_e32 v29, 0x5000, v19
	ds_read2_b32 v[34:35], v21 offset1:1
	ds_read2_b32 v[36:37], v25 offset1:1
	ds_read2_b32 v[38:39], v23 offset1:1
	ds_read2_b32 v[40:41], v27 offset1:1
	ds_read2_b32 v[42:43], v29 offset1:1
	ds_read2_b32 v[44:45], v44 offset1:1
	ds_read2_b32 v[46:47], v46 offset1:1
	ds_read2_b32 v[48:49], v48 offset1:1
	ds_read2_b32 v[50:51], v50 offset1:1
	ds_read2_b32 v[52:53], v52 offset1:1
	ds_read2_b32 v[54:55], v54 offset1:1
	ds_read2_b32 v[56:57], v56 offset1:1
	ds_read2_b32 v[58:59], v58 offset1:1
	ds_read2_b32 v[60:61], v60 offset1:1
	ds_read2_b32 v[62:63], v62 offset1:1
	ds_read2_b32 v[64:65], v64 offset1:1
	s_waitcnt lgkmcnt(14)
	v_mov_b32_e32 v66, v30
	v_mov_b32_e32 v67, v34
	v_mov_b32_e32 v68, v36
	s_waitcnt lgkmcnt(13)
	v_mov_b32_e32 v69, v38
	s_waitcnt lgkmcnt(12)
	v_mov_b32_e32 v70, v40
	s_waitcnt lgkmcnt(11)
	v_mov_b32_e32 v71, v42
	s_waitcnt lgkmcnt(10)
	v_mov_b32_e32 v72, v44
	s_waitcnt lgkmcnt(9)
	v_mov_b32_e32 v73, v46
	v_mov_b32_e32 v34, v31
	v_mov_b32_e32 v38, v37
	v_mov_b32_e32 v42, v41
	v_mov_b32_e32 v46, v45
	s_add_u32 s12, s12, 0x18000
	v_mov_b32_e32 v30, v32
	s_waitcnt lgkmcnt(7)
	v_mov_b32_e32 v31, v50
	s_waitcnt lgkmcnt(6)
	v_mov_b32_e32 v36, v52
	s_waitcnt lgkmcnt(5)
	v_mov_b32_e32 v37, v54
	s_waitcnt lgkmcnt(4)
; DI void phase_setup(LAS unsigned char* lds) {
;     ...
;           for (int k = kp * 256; k < kp * 256 + 256; ++k) { const float wv = w[(size_t)k * 6144];
; #pragma unroll
;               for (int i = 0; i < 9; ++i) a[i] = fmaf(sv[i * 1024 + k], wv, a[i]); }
	v_mov_b32_e32 v40, v56
	s_waitcnt lgkmcnt(3)
	v_mov_b32_e32 v41, v58
	s_waitcnt lgkmcnt(2)
	v_mov_b32_e32 v44, v60
	s_waitcnt lgkmcnt(1)
	v_mov_b32_e32 v45, v62
	s_addc_u32 s13, s13, 0
	v_mov_b32_e32 v50, v33
	v_mov_b32_e32 v54, v53
	v_mov_b32_e32 v58, v57
	v_mov_b32_e32 v62, v61
	v_add_u32_e32 v19, 16, v19
	s_cmp_eq_u32 s12, 0x600000
	v_pk_fma_f32 v[10:11], v[66:67], v[78:79], v[10:11] op_sel_hi:[1,0,1]
	v_pk_fma_f32 v[12:13], v[68:69], v[78:79], v[12:13] op_sel_hi:[1,0,1]
	v_pk_fma_f32 v[14:15], v[70:71], v[78:79], v[14:15] op_sel_hi:[1,0,1]
	v_pk_fma_f32 v[16:17], v[72:73], v[78:79], v[16:17] op_sel_hi:[1,0,1]
	v_fmac_f32_e32 v20, v48, v78
	v_pk_fma_f32 v[10:11], v[34:35], v[80:81], v[10:11] op_sel_hi:[1,0,1]
	v_pk_fma_f32 v[12:13], v[38:39], v[80:81], v[12:13] op_sel_hi:[1,0,1]
	v_pk_fma_f32 v[14:15], v[42:43], v[80:81], v[14:15] op_sel_hi:[1,0,1]
	v_pk_fma_f32 v[16:17], v[46:47], v[80:81], v[16:17] op_sel_hi:[1,0,1]
	v_fmac_f32_e32 v20, v49, v80
	v_pk_fma_f32 v[10:11], v[30:31], v[82:83], v[10:11] op_sel_hi:[1,0,1]
	v_pk_fma_f32 v[12:13], v[36:37], v[82:83], v[12:13] op_sel_hi:[1,0,1]
	v_pk_fma_f32 v[14:15], v[40:41], v[82:83], v[14:15] op_sel_hi:[1,0,1]
	v_pk_fma_f32 v[16:17], v[44:45], v[82:83], v[16:17] op_sel_hi:[1,0,1]
	s_waitcnt lgkmcnt(0)
	v_fmac_f32_e32 v20, v64, v82
	v_pk_fma_f32 v[10:11], v[50:51], v[84:85], v[10:11] op_sel_hi:[1,0,1]
	v_pk_fma_f32 v[12:13], v[54:55], v[84:85], v[12:13] op_sel_hi:[1,0,1]
	v_pk_fma_f32 v[14:15], v[58:59], v[84:85], v[14:15] op_sel_hi:[1,0,1]
	v_pk_fma_f32 v[16:17], v[62:63], v[84:85], v[16:17] op_sel_hi:[1,0,1]
	v_fmac_f32_e32 v20, v65, v84
	s_waitcnt vmcnt(12)
	v_mov_b32_e32 v78, v86
	v_mov_b32_e32 v80, v87
	v_mov_b32_e32 v82, v88
	v_mov_b32_e32 v84, v89
	s_add_u32 s4, s12, 0x60000
	s_min_u32 s4, s4, 0x5e8000
	s_mov_b32 s5, 0
	v_lshl_add_u64 v[22:23], v[8:9], 0, s[4:5]
	v_add_co_u32_e64 v26, s[4:5], s3, v22
	global_load_dword v86, v[22:23], off
	s_nop 0
	v_addc_co_u32_e64 v27, s[4:5], 0, v23, s[4:5]
	v_add_co_u32_e64 v28, s[4:5], s17, v22
	s_mov_b32 s2, 0x12000
	s_nop 0
	v_addc_co_u32_e64 v29, s[4:5], 0, v23, s[4:5]
	v_add_co_u32_e64 v22, s[4:5], s2, v22
	v_add_u32_e32 v21, 0x1000, v19
	s_nop 0
	v_addc_co_u32_e64 v23, s[4:5], 0, v23, s[4:5]
	global_load_dword v87, v[26:27], off
	s_nop 0
	global_load_dword v88, v[28:29], off
	s_nop 0
	global_load_dword v89, v[22:23], off
	ds_read2_b32 v[30:31], v19 offset1:1
	ds_read2_b32 v[32:33], v19 offset0:2 offset1:3
	v_add_u32_e32 v44, 0x6000, v19
	v_add_u32_e32 v46, 0x7000, v19
	v_add_u32_e32 v48, 0x8000, v19
	v_add_u32_e32 v50, 0x1008, v19
	v_add_u32_e32 v52, 0x2008, v19
	v_add_u32_e32 v54, 0x3008, v19
	v_add_u32_e32 v56, 0x4008, v19
	v_add_u32_e32 v58, 0x5008, v19
	v_add_u32_e32 v60, 0x6008, v19
	v_add_u32_e32 v62, 0x7008, v19
	v_add_u32_e32 v64, 0x8008, v19
	v_add_u32_e32 v25, 0x2000, v19
	v_add_u32_e32 v23, 0x3000, v19
	v_add_u32_e32 v27, 0x4000, v19
	v_add_u32_e32 v29, 0x5000, v19
	ds_read2_b32 v[34:35], v21 offset1:1
	ds_read2_b32 v[36:37], v25 offset1:1
	ds_read2_b32 v[38:39], v23 offset1:1
	ds_read2_b32 v[40:41], v27 offset1:1
	ds_read2_b32 v[42:43], v29 offset1:1
	ds_read2_b32 v[44:45], v44 offset1:1
	ds_read2_b32 v[46:47], v46 offset1:1
	ds_read2_b32 v[48:49], v48 offset1:1
	ds_read2_b32 v[50:51], v50 offset1:1
	ds_read2_b32 v[52:53], v52 offset1:1
	ds_read2_b32 v[54:55], v54 offset1:1
	ds_read2_b32 v[56:57], v56 offset1:1
	ds_read2_b32 v[58:59], v58 offset1:1
	ds_read2_b32 v[60:61], v60 offset1:1
	ds_read2_b32 v[62:63], v62 offset1:1
	ds_read2_b32 v[64:65], v64 offset1:1
	s_waitcnt lgkmcnt(14)
	v_mov_b32_e32 v66, v30
	v_mov_b32_e32 v67, v34
	v_mov_b32_e32 v68, v36
	s_waitcnt lgkmcnt(13)
	v_mov_b32_e32 v69, v38
	s_waitcnt lgkmcnt(12)
	v_mov_b32_e32 v70, v40
	s_waitcnt lgkmcnt(11)
	v_mov_b32_e32 v71, v42
	s_waitcnt lgkmcnt(10)
	v_mov_b32_e32 v72, v44
	s_waitcnt lgkmcnt(9)
	v_mov_b32_e32 v73, v46
	v_mov_b32_e32 v34, v31
	v_mov_b32_e32 v38, v37
	v_mov_b32_e32 v42, v41
	v_mov_b32_e32 v46, v45
	s_add_u32 s12, s12, 0x18000
	v_mov_b32_e32 v30, v32
	s_waitcnt lgkmcnt(7)
	v_mov_b32_e32 v31, v50
	s_waitcnt lgkmcnt(6)
	v_mov_b32_e32 v36, v52
	s_waitcnt lgkmcnt(5)
	v_mov_b32_e32 v37, v54
	s_waitcnt lgkmcnt(4)
	v_mov_b32_e32 v40, v56
	s_waitcnt lgkmcnt(3)
	v_mov_b32_e32 v41, v58
	s_waitcnt lgkmcnt(2)
	v_mov_b32_e32 v44, v60
	s_waitcnt lgkmcnt(1)
	v_mov_b32_e32 v45, v62
	s_addc_u32 s13, s13, 0
	v_mov_b32_e32 v50, v33
	v_mov_b32_e32 v54, v53
	v_mov_b32_e32 v58, v57
	v_mov_b32_e32 v62, v61
	v_add_u32_e32 v19, 16, v19
	s_cmp_eq_u32 s12, 0x600000
	v_pk_fma_f32 v[10:11], v[66:67], v[78:79], v[10:11] op_sel_hi:[1,0,1]
	v_pk_fma_f32 v[12:13], v[68:69], v[78:79], v[12:13] op_sel_hi:[1,0,1]
	v_pk_fma_f32 v[14:15], v[70:71], v[78:79], v[14:15] op_sel_hi:[1,0,1]
	v_pk_fma_f32 v[16:17], v[72:73], v[78:79], v[16:17] op_sel_hi:[1,0,1]
	v_fmac_f32_e32 v20, v48, v78
	v_pk_fma_f32 v[10:11], v[34:35], v[80:81], v[10:11] op_sel_hi:[1,0,1]
	v_pk_fma_f32 v[12:13], v[38:39], v[80:81], v[12:13] op_sel_hi:[1,0,1]
	v_pk_fma_f32 v[14:15], v[42:43], v[80:81], v[14:15] op_sel_hi:[1,0,1]
	v_pk_fma_f32 v[16:17], v[46:47], v[80:81], v[16:17] op_sel_hi:[1,0,1]
	v_fmac_f32_e32 v20, v49, v80
	v_pk_fma_f32 v[10:11], v[30:31], v[82:83], v[10:11] op_sel_hi:[1,0,1]
	v_pk_fma_f32 v[12:13], v[36:37], v[82:83], v[12:13] op_sel_hi:[1,0,1]
	v_pk_fma_f32 v[14:15], v[40:41], v[82:83], v[14:15] op_sel_hi:[1,0,1]
	v_pk_fma_f32 v[16:17], v[44:45], v[82:83], v[16:17] op_sel_hi:[1,0,1]
	s_waitcnt lgkmcnt(0)
	v_fmac_f32_e32 v20, v64, v82
	v_pk_fma_f32 v[10:11], v[50:51], v[84:85], v[10:11] op_sel_hi:[1,0,1]
	v_pk_fma_f32 v[12:13], v[54:55], v[84:85], v[12:13] op_sel_hi:[1,0,1]
	v_pk_fma_f32 v[14:15], v[58:59], v[84:85], v[14:15] op_sel_hi:[1,0,1]
	v_pk_fma_f32 v[16:17], v[62:63], v[84:85], v[16:17] op_sel_hi:[1,0,1]
	v_fmac_f32_e32 v20, v65, v84
	s_waitcnt vmcnt(12)
; DI void phase_setup(LAS unsigned char* lds) {
;     ...
;           for (int k = kp * 256; k < kp * 256 + 256; ++k) { const float wv = w[(size_t)k * 6144];
; #pragma unroll
;               for (int i = 0; i < 9; ++i) a[i] = fmaf(sv[i * 1024 + k], wv, a[i]); }
	v_mov_b32_e32 v78, v90
	v_mov_b32_e32 v80, v91
	v_mov_b32_e32 v82, v92
	v_mov_b32_e32 v84, v93
	s_add_u32 s4, s12, 0x60000
	s_min_u32 s4, s4, 0x5e8000
	s_mov_b32 s5, 0
	v_lshl_add_u64 v[22:23], v[8:9], 0, s[4:5]
	v_add_co_u32_e64 v26, s[4:5], s3, v22
	global_load_dword v90, v[22:23], off
	s_nop 0
	v_addc_co_u32_e64 v27, s[4:5], 0, v23, s[4:5]
	v_add_co_u32_e64 v28, s[4:5], s17, v22
	s_mov_b32 s2, 0x12000
	s_nop 0
	v_addc_co_u32_e64 v29, s[4:5], 0, v23, s[4:5]
	v_add_co_u32_e64 v22, s[4:5], s2, v22
	v_add_u32_e32 v21, 0x1000, v19
	s_nop 0
	v_addc_co_u32_e64 v23, s[4:5], 0, v23, s[4:5]
	global_load_dword v91, v[26:27], off
	s_nop 0
	global_load_dword v92, v[28:29], off
	s_nop 0
	global_load_dword v93, v[22:23], off
	ds_read2_b32 v[30:31], v19 offset1:1
	ds_read2_b32 v[32:33], v19 offset0:2 offset1:3
	v_add_u32_e32 v44, 0x6000, v19
	v_add_u32_e32 v46, 0x7000, v19
	v_add_u32_e32 v48, 0x8000, v19
	v_add_u32_e32 v50, 0x1008, v19
	v_add_u32_e32 v52, 0x2008, v19
	v_add_u32_e32 v54, 0x3008, v19
	v_add_u32_e32 v56, 0x4008, v19
	v_add_u32_e32 v58, 0x5008, v19
	v_add_u32_e32 v60, 0x6008, v19
	v_add_u32_e32 v62, 0x7008, v19
	v_add_u32_e32 v64, 0x8008, v19
	v_add_u32_e32 v25, 0x2000, v19
	v_add_u32_e32 v23, 0x3000, v19
	v_add_u32_e32 v27, 0x4000, v19
	v_add_u32_e32 v29, 0x5000, v19
	ds_read2_b32 v[34:35], v21 offset1:1
	ds_read2_b32 v[36:37], v25 offset1:1
	ds_read2_b32 v[38:39], v23 offset1:1
	ds_read2_b32 v[40:41], v27 offset1:1
	ds_read2_b32 v[42:43], v29 offset1:1
	ds_read2_b32 v[44:45], v44 offset1:1
	ds_read2_b32 v[46:47], v46 offset1:1
	ds_read2_b32 v[48:49], v48 offset1:1
	ds_read2_b32 v[50:51], v50 offset1:1
	ds_read2_b32 v[52:53], v52 offset1:1
	ds_read2_b32 v[54:55], v54 offset1:1
	ds_read2_b32 v[56:57], v56 offset1:1
	ds_read2_b32 v[58:59], v58 offset1:1
	ds_read2_b32 v[60:61], v60 offset1:1
	ds_read2_b32 v[62:63], v62 offset1:1
	ds_read2_b32 v[64:65], v64 offset1:1
	s_waitcnt lgkmcnt(14)
	v_mov_b32_e32 v66, v30
	v_mov_b32_e32 v67, v34
	v_mov_b32_e32 v68, v36
	s_waitcnt lgkmcnt(13)
	v_mov_b32_e32 v69, v38
	s_waitcnt lgkmcnt(12)
	v_mov_b32_e32 v70, v40
	s_waitcnt lgkmcnt(11)
	v_mov_b32_e32 v71, v42
	s_waitcnt lgkmcnt(10)
	v_mov_b32_e32 v72, v44
	s_waitcnt lgkmcnt(9)
	v_mov_b32_e32 v73, v46
	v_mov_b32_e32 v34, v31
	v_mov_b32_e32 v38, v37
	v_mov_b32_e32 v42, v41
	v_mov_b32_e32 v46, v45
	s_add_u32 s12, s12, 0x18000
	v_mov_b32_e32 v30, v32
	s_waitcnt lgkmcnt(7)
	v_mov_b32_e32 v31, v50
	s_waitcnt lgkmcnt(6)
	v_mov_b32_e32 v36, v52
	s_waitcnt lgkmcnt(5)
	v_mov_b32_e32 v37, v54
	s_waitcnt lgkmcnt(4)
	v_mov_b32_e32 v40, v56
	s_waitcnt lgkmcnt(3)
	v_mov_b32_e32 v41, v58
	s_waitcnt lgkmcnt(2)
	v_mov_b32_e32 v44, v60
	s_waitcnt lgkmcnt(1)
	v_mov_b32_e32 v45, v62
	s_addc_u32 s13, s13, 0
	v_mov_b32_e32 v50, v33
	v_mov_b32_e32 v54, v53
	v_mov_b32_e32 v58, v57
	v_mov_b32_e32 v62, v61
	v_add_u32_e32 v19, 16, v19
	s_cmp_eq_u32 s12, 0x600000
	v_pk_fma_f32 v[10:11], v[66:67], v[78:79], v[10:11] op_sel_hi:[1,0,1]
	v_pk_fma_f32 v[12:13], v[68:69], v[78:79], v[12:13] op_sel_hi:[1,0,1]
	v_pk_fma_f32 v[14:15], v[70:71], v[78:79], v[14:15] op_sel_hi:[1,0,1]
	v_pk_fma_f32 v[16:17], v[72:73], v[78:79], v[16:17] op_sel_hi:[1,0,1]
	v_fmac_f32_e32 v20, v48, v78
	v_pk_fma_f32 v[10:11], v[34:35], v[80:81], v[10:11] op_sel_hi:[1,0,1]
	v_pk_fma_f32 v[12:13], v[38:39], v[80:81], v[12:13] op_sel_hi:[1,0,1]
	v_pk_fma_f32 v[14:15], v[42:43], v[80:81], v[14:15] op_sel_hi:[1,0,1]
	v_pk_fma_f32 v[16:17], v[46:47], v[80:81], v[16:17] op_sel_hi:[1,0,1]
	v_fmac_f32_e32 v20, v49, v80
	v_pk_fma_f32 v[10:11], v[30:31], v[82:83], v[10:11] op_sel_hi:[1,0,1]
	v_pk_fma_f32 v[12:13], v[36:37], v[82:83], v[12:13] op_sel_hi:[1,0,1]
	v_pk_fma_f32 v[14:15], v[40:41], v[82:83], v[14:15] op_sel_hi:[1,0,1]
	v_pk_fma_f32 v[16:17], v[44:45], v[82:83], v[16:17] op_sel_hi:[1,0,1]
	s_waitcnt lgkmcnt(0)
	v_fmac_f32_e32 v20, v64, v82
	v_pk_fma_f32 v[10:11], v[50:51], v[84:85], v[10:11] op_sel_hi:[1,0,1]
	v_pk_fma_f32 v[12:13], v[54:55], v[84:85], v[12:13] op_sel_hi:[1,0,1]
	v_pk_fma_f32 v[14:15], v[58:59], v[84:85], v[14:15] op_sel_hi:[1,0,1]
	v_pk_fma_f32 v[16:17], v[62:63], v[84:85], v[16:17] op_sel_hi:[1,0,1]
	v_fmac_f32_e32 v20, v65, v84
	s_waitcnt vmcnt(12)
	v_mov_b32_e32 v78, v94
	v_mov_b32_e32 v80, v95
	v_mov_b32_e32 v82, v96
	v_mov_b32_e32 v84, v97
	s_add_u32 s4, s12, 0x60000
	s_min_u32 s4, s4, 0x5e8000
	s_mov_b32 s5, 0
	v_lshl_add_u64 v[22:23], v[8:9], 0, s[4:5]
	v_add_co_u32_e64 v26, s[4:5], s3, v22
	global_load_dword v94, v[22:23], off
	s_nop 0
	v_addc_co_u32_e64 v27, s[4:5], 0, v23, s[4:5]
	v_add_co_u32_e64 v28, s[4:5], s17, v22
	s_mov_b32 s2, 0x12000
	s_nop 0
	v_addc_co_u32_e64 v29, s[4:5], 0, v23, s[4:5]
	v_add_co_u32_e64 v22, s[4:5], s2, v22
	v_add_u32_e32 v21, 0x1000, v19
	s_nop 0
	v_addc_co_u32_e64 v23, s[4:5], 0, v23, s[4:5]
	global_load_dword v95, v[26:27], off
	s_nop 0
	global_load_dword v96, v[28:29], off
	s_nop 0
	global_load_dword v97, v[22:23], off
	ds_read2_b32 v[30:31], v19 offset1:1
	ds_read2_b32 v[32:33], v19 offset0:2 offset1:3
	v_add_u32_e32 v44, 0x6000, v19
	v_add_u32_e32 v46, 0x7000, v19
	v_add_u32_e32 v48, 0x8000, v19
	v_add_u32_e32 v50, 0x1008, v19
	v_add_u32_e32 v52, 0x2008, v19
	v_add_u32_e32 v54, 0x3008, v19
	v_add_u32_e32 v56, 0x4008, v19
	v_add_u32_e32 v58, 0x5008, v19
	v_add_u32_e32 v60, 0x6008, v19
	v_add_u32_e32 v62, 0x7008, v19
	v_add_u32_e32 v64, 0x8008, v19
	v_add_u32_e32 v25, 0x2000, v19
	v_add_u32_e32 v23, 0x3000, v19
	v_add_u32_e32 v27, 0x4000, v19
	v_add_u32_e32 v29, 0x5000, v19
	ds_read2_b32 v[34:35], v21 offset1:1
	ds_read2_b32 v[36:37], v25 offset1:1
	ds_read2_b32 v[38:39], v23 offset1:1
	ds_read2_b32 v[40:41], v27 offset1:1
	ds_read2_b32 v[42:43], v29 offset1:1
	ds_read2_b32 v[44:45], v44 offset1:1
	ds_read2_b32 v[46:47], v46 offset1:1
	ds_read2_b32 v[48:49], v48 offset1:1
	ds_read2_b32 v[50:51], v50 offset1:1
	ds_read2_b32 v[52:53], v52 offset1:1
	ds_read2_b32 v[54:55], v54 offset1:1
	ds_read2_b32 v[56:57], v56 offset1:1
	ds_read2_b32 v[58:59], v58 offset1:1
	ds_read2_b32 v[60:61], v60 offset1:1
	ds_read2_b32 v[62:63], v62 offset1:1
	ds_read2_b32 v[64:65], v64 offset1:1
	s_waitcnt lgkmcnt(14)
; DI void phase_setup(LAS unsigned char* lds) {
;     ...
;           for (int k = kp * 256; k < kp * 256 + 256; ++k) { const float wv = w[(size_t)k * 6144];
; #pragma unroll
;               for (int i = 0; i < 9; ++i) a[i] = fmaf(sv[i * 1024 + k], wv, a[i]); }
; #pragma unroll
;           for (int i = 0; i < 9; ++i) red[(kp * 9 + i) * 128 + nn] = a[i];
;           __syncthreads();
;           if (kp == 0) { const float bias = adab[l * 6144 + n0 + nn];
; #pragma unroll
;               for (int i = 0; i < 9; ++i) { const float s = red[i * 128 + nn] + red[(9 + i) * 128 + nn] + red[(18 + i) * 128 + nn] + red[(27 + i) * 128 + nn];
;                   ((float*)(ws + WS_MOD))[((size_t)(l * 9 + i)) * 6144 + n0 + nn] = s + bias; } }
;           __syncthreads();
	v_mov_b32_e32 v66, v30
	v_mov_b32_e32 v67, v34
	v_mov_b32_e32 v68, v36
	s_waitcnt lgkmcnt(13)
	v_mov_b32_e32 v69, v38
	s_waitcnt lgkmcnt(12)
	v_mov_b32_e32 v70, v40
	s_waitcnt lgkmcnt(11)
	v_mov_b32_e32 v71, v42
	s_waitcnt lgkmcnt(10)
	v_mov_b32_e32 v72, v44
	s_waitcnt lgkmcnt(9)
	v_mov_b32_e32 v73, v46
	v_mov_b32_e32 v34, v31
	v_mov_b32_e32 v38, v37
	v_mov_b32_e32 v42, v41
	v_mov_b32_e32 v46, v45
	s_add_u32 s12, s12, 0x18000
	v_mov_b32_e32 v30, v32
	s_waitcnt lgkmcnt(7)
	v_mov_b32_e32 v31, v50
	s_waitcnt lgkmcnt(6)
	v_mov_b32_e32 v36, v52
	s_waitcnt lgkmcnt(5)
	v_mov_b32_e32 v37, v54
	s_waitcnt lgkmcnt(4)
	v_mov_b32_e32 v40, v56
	s_waitcnt lgkmcnt(3)
	v_mov_b32_e32 v41, v58
	s_waitcnt lgkmcnt(2)
	v_mov_b32_e32 v44, v60
	s_waitcnt lgkmcnt(1)
	v_mov_b32_e32 v45, v62
	s_addc_u32 s13, s13, 0
	v_mov_b32_e32 v50, v33
	v_mov_b32_e32 v54, v53
	v_mov_b32_e32 v58, v57
	v_mov_b32_e32 v62, v61
	v_add_u32_e32 v19, 16, v19
	s_cmp_eq_u32 s12, 0x600000
	v_pk_fma_f32 v[10:11], v[66:67], v[78:79], v[10:11] op_sel_hi:[1,0,1]
	v_pk_fma_f32 v[12:13], v[68:69], v[78:79], v[12:13] op_sel_hi:[1,0,1]
	v_pk_fma_f32 v[14:15], v[70:71], v[78:79], v[14:15] op_sel_hi:[1,0,1]
	v_pk_fma_f32 v[16:17], v[72:73], v[78:79], v[16:17] op_sel_hi:[1,0,1]
	v_fmac_f32_e32 v20, v48, v78
	v_pk_fma_f32 v[10:11], v[34:35], v[80:81], v[10:11] op_sel_hi:[1,0,1]
	v_pk_fma_f32 v[12:13], v[38:39], v[80:81], v[12:13] op_sel_hi:[1,0,1]
	v_pk_fma_f32 v[14:15], v[42:43], v[80:81], v[14:15] op_sel_hi:[1,0,1]
	v_pk_fma_f32 v[16:17], v[46:47], v[80:81], v[16:17] op_sel_hi:[1,0,1]
	v_fmac_f32_e32 v20, v49, v80
	v_pk_fma_f32 v[10:11], v[30:31], v[82:83], v[10:11] op_sel_hi:[1,0,1]
	v_pk_fma_f32 v[12:13], v[36:37], v[82:83], v[12:13] op_sel_hi:[1,0,1]
	v_pk_fma_f32 v[14:15], v[40:41], v[82:83], v[14:15] op_sel_hi:[1,0,1]
	v_pk_fma_f32 v[16:17], v[44:45], v[82:83], v[16:17] op_sel_hi:[1,0,1]
	s_waitcnt lgkmcnt(0)
	v_fmac_f32_e32 v20, v64, v82
	v_pk_fma_f32 v[10:11], v[50:51], v[84:85], v[10:11] op_sel_hi:[1,0,1]
	v_pk_fma_f32 v[12:13], v[54:55], v[84:85], v[12:13] op_sel_hi:[1,0,1]
	v_pk_fma_f32 v[14:15], v[58:59], v[84:85], v[14:15] op_sel_hi:[1,0,1]
	v_pk_fma_f32 v[16:17], v[62:63], v[84:85], v[16:17] op_sel_hi:[1,0,1]
	v_fmac_f32_e32 v20, v65, v84
	s_cbranch_scc0 .LBB0_820
	ds_write2st64_b32 v18, v10, v11 offset0:144 offset1:146
	ds_write2st64_b32 v18, v12, v13 offset0:148 offset1:150
	ds_write2st64_b32 v18, v14, v15 offset0:152 offset1:154
	ds_write2st64_b32 v18, v16, v17 offset0:156 offset1:158
	ds_write_b32 v18, v20 offset:40960
	s_waitcnt lgkmcnt(0)
	s_barrier
	s_and_saveexec_b64 s[2:3], vcc
	s_cbranch_execz .LBB0_818
	s_mul_i32 s4, s16, 0x1800
	s_add_i32 s4, s4, s10
	v_or_b32_e32 v8, s4, v2
	v_ashrrev_i32_e32 v9, 31, v8
	v_lshl_add_u64 v[8:9], v[8:9], 2, s[8:9]
	global_load_dword v19, v[8:9], off
	ds_read2st64_b32 v[10:11], v3 offset0:144 offset1:146
	ds_read2st64_b32 v[12:13], v3 offset0:160 offset1:162
	ds_read2st64_b32 v[14:15], v3 offset0:180 offset1:182
	ds_read2st64_b32 v[16:17], v3 offset0:196 offset1:198
	ds_read2st64_b32 v[20:21], v3 offset0:164 offset1:166
	ds_read2st64_b32 v[22:23], v3 offset0:200 offset1:202
	ds_read2st64_b32 v[24:25], v3 offset0:148 offset1:150
	ds_read2st64_b32 v[26:27], v3 offset0:184 offset1:186
	ds_read2st64_b32 v[28:29], v3 offset0:168 offset1:170
	ds_read2st64_b32 v[30:31], v3 offset0:204 offset1:206
	ds_read2st64_b32 v[32:33], v3 offset0:152 offset1:154
	ds_read2st64_b32 v[34:35], v3 offset0:188 offset1:190
	ds_read2st64_b32 v[36:37], v3 offset0:172 offset1:174
	ds_read2st64_b32 v[38:39], v3 offset0:208 offset1:210
	ds_read2st64_b32 v[40:41], v3 offset0:156 offset1:158
	ds_read2st64_b32 v[42:43], v3 offset0:192 offset1:194
	ds_read2st64_b32 v[44:45], v3 offset0:176 offset1:178
	ds_read2st64_b32 v[46:47], v3 offset0:212 offset1:214
	s_waitcnt lgkmcnt(14)
	v_add_f32_e32 v10, v10, v13
	s_waitcnt lgkmcnt(13)
	v_add_f32_e32 v11, v11, v20
	s_mul_i32 s12, s16, 9
	v_lshl_add_u64 v[8:9], s[10:11], 2, v[4:5]
	s_waitcnt lgkmcnt(11)
	v_add_f32_e32 v13, v24, v21
	s_waitcnt lgkmcnt(9)
	v_add_f32_e32 v20, v25, v28
	s_waitcnt lgkmcnt(7)
	v_add_f32_e32 v21, v32, v29
	s_waitcnt lgkmcnt(5)
	v_add_f32_e32 v24, v33, v36
	s_waitcnt lgkmcnt(3)
	v_add_f32_e32 v25, v40, v37
	s_waitcnt lgkmcnt(1)
	v_add_f32_e32 v28, v41, v44
	v_add_f32_e32 v10, v10, v14
	v_add_f32_e32 v11, v11, v15
	v_mad_i64_i32 v[48:49], s[4:5], s12, v197, v[8:9]
	v_add_f32_e32 v13, v13, v26
	v_add_f32_e32 v14, v20, v27
	v_add_f32_e32 v15, v21, v34
	v_add_f32_e32 v20, v24, v35
	v_add_f32_e32 v21, v25, v42
	v_add_f32_e32 v24, v28, v43
	v_add_f32_e32 v10, v10, v17
	v_add_f32_e32 v11, v11, v22
	s_add_i32 s4, s12, 1
	s_add_i32 s10, s12, 2
	s_add_i32 s11, s12, 3
	s_add_i32 s13, s12, 4
	s_add_i32 s16, s12, 5
	s_add_i32 s17, s12, 6
	s_add_i32 s18, s12, 7
	v_add_f32_e32 v13, v13, v23
	v_add_f32_e32 v14, v14, v30
	v_add_f32_e32 v15, v15, v31
	v_add_f32_e32 v17, v20, v38
	v_add_f32_e32 v20, v21, v39
	s_waitcnt lgkmcnt(0)
	v_add_f32_e32 v21, v24, v46
	v_mad_i64_i32 v[50:51], s[4:5], s4, v197, v[8:9]
	v_mad_i64_i32 v[52:53], s[4:5], s10, v197, v[8:9]
	v_mad_i64_i32 v[54:55], s[4:5], s11, v197, v[8:9]
	v_mad_i64_i32 v[56:57], s[4:5], s13, v197, v[8:9]
	v_mad_i64_i32 v[58:59], s[4:5], s16, v197, v[8:9]
	v_mad_i64_i32 v[60:61], s[4:5], s17, v197, v[8:9]
	s_add_i32 s12, s12, 8
	s_waitcnt vmcnt(0)
	v_add_f32_e32 v10, v19, v10
	v_add_f32_e32 v11, v19, v11
	v_add_f32_e32 v13, v19, v13
	v_add_f32_e32 v14, v19, v14
	v_add_f32_e32 v15, v19, v15
	v_add_f32_e32 v17, v19, v17
	v_add_f32_e32 v20, v19, v20
	v_add_f32_e32 v21, v19, v21
	global_store_dword v[48:49], v10, off
	global_store_dword v[50:51], v11, off
	global_store_dword v[52:53], v13, off
	global_store_dword v[54:55], v14, off
	global_store_dword v[56:57], v15, off
	global_store_dword v[58:59], v17, off
	global_store_dword v[60:61], v20, off
	v_mad_i64_i32 v[10:11], s[4:5], s18, v197, v[8:9]
	global_store_dword v[10:11], v21, off
	v_add_f32_e32 v10, v12, v45
	v_add_f32_e32 v10, v10, v16
	v_add_f32_e32 v10, v10, v47
	v_add_f32_e32 v10, v19, v10
	v_mad_i64_i32 v[8:9], s[4:5], s12, v197, v[8:9]
	global_store_dword v[8:9], v10, off
	s_branch .LBB0_818

; #define LAS __attribute__((address_space(3)))
; DI unsigned pk2(float lo, float hi) { return f2bf(lo) | (f2bf(hi) << 16); }
; #define BIDX() sgpr_opaque((int)__builtin_amdgcn_workgroup_id_x())
; #define GDIM() sgpr_opaque((int)__ockl_get_num_groups(0))
; DI int tid_opaque() { int t = threadIdx.x; asm volatile("" : "+v"(t)); return t; }
; DI void transpose_tiles(const float* src, int ldw, int Ks, bf16_t* dst, int Nn, int Kd, int kind, LAS float* tile) {
;     const int tid = tid_opaque(), ntn = Nn / 64, ntk = Kd / 64;
;     for (int it = BIDX(); it < ntn * ntk; it += GDIM()) {
;         const int n0 = (it % ntn) * 64, k0 = (it / ntn) * 64;
;         { const int nn = tid & 63, kk = tid >> 6; const int off = colmap(kind, n0 + nn);
; #pragma unroll
;           for (int i = 0; i < 8; ++i) { const int k = k0 + kk + 8 * i; float v = 0.f; if (off >= 0 && k < Ks) v = src[(size_t)k * ldw + off]; tile[(kk + 8 * i) * 65 + nn] = v; } }
;         __syncthreads();
;         { const int nn = tid >> 3, kc = tid & 7; const LAS float* s = tile + (kc * 8) * 65 + nn;
;           u32x4 o; o.x = pk2(s[0], s[65]); o.y = pk2(s[2 * 65], s[3 * 65]); o.z = pk2(s[4 * 65], s[5 * 65]); o.w = pk2(s[6 * 65], s[7 * 65]);
;           *(u32x4*)(dst + (size_t)(n0 + nn) * Kd + k0 + kc * 8) = o; }
;         __syncthreads();
.LBB0_827:
	s_or_b64 exec, exec, s[2:3]
	s_waitcnt vmcnt(0)
	ds_write_b32 v10, v100
	ds_write_b32 v10, v101 offset:2080
	ds_write_b32 v10, v102 offset:4160
	ds_write_b32 v10, v103 offset:6240
	ds_write_b32 v10, v104 offset:8320
	ds_write_b32 v10, v105 offset:10400
	ds_write_b32 v10, v106 offset:12480
	ds_write_b32 v10, v107 offset:14560
	s_waitcnt lgkmcnt(0)
	s_barrier
	ds_read2_b32 v[4:5], v9 offset1:65
	ds_read2_b32 v[14:15], v9 offset0:130 offset1:195
	s_mov_b32 s2, s30
	s_waitcnt lgkmcnt(1)
	v_bfe_u32 v0, v4, 16, 1
	v_add3_u32 v0, v4, v0, s31
	v_bfe_u32 v3, v5, 16, 1
	v_lshrrev_b32_e32 v0, 16, v0
	v_add3_u32 v3, v5, v3, s31
	v_and_or_b32 v12, v3, s0, v0
	v_add_u32_e32 v3, 0x400, v9
	ds_read2_b32 v[4:5], v3 offset0:4 offset1:69
	s_waitcnt lgkmcnt(1)
	v_bfe_u32 v0, v14, 16, 1
	v_add3_u32 v0, v14, v0, s31
	v_bfe_u32 v11, v15, 16, 1
	ds_read2_b32 v[16:17], v3 offset0:134 offset1:199
	v_lshrrev_b32_e32 v0, 16, v0
	v_add3_u32 v11, v15, v11, s31
	v_and_or_b32 v13, v11, s0, v0
	s_waitcnt lgkmcnt(1)
	v_bfe_u32 v0, v4, 16, 1
	v_add3_u32 v0, v4, v0, s31
	v_bfe_u32 v3, v5, 16, 1
	v_lshrrev_b32_e32 v0, 16, v0
	v_add3_u32 v3, v5, v3, s31
	v_add_u32_e32 v4, s15, v8
	v_and_or_b32 v14, v3, s0, v0
	s_waitcnt lgkmcnt(0)
	v_bfe_u32 v0, v16, 16, 1
	v_ashrrev_i32_e32 v5, 31, v4
	v_add3_u32 v0, v16, v0, s31
	v_bfe_u32 v3, v17, 16, 1
	v_lshlrev_b64 v[4:5], 11, v[4:5]
	v_lshrrev_b32_e32 v0, 16, v0
	v_add3_u32 v3, v17, v3, s31
	v_lshl_add_u64 v[4:5], s[12:13], 0, v[4:5]
	s_ashr_i32 s15, s14, 31
	v_and_or_b32 v15, v3, s0, v0
	v_lshl_add_u64 v[4:5], s[14:15], 1, v[4:5]
	v_mov_b32_e32 v3, v1
	v_lshl_add_u64 v[4:5], v[4:5], 0, v[2:3]
	global_store_dwordx4 v[4:5], v[12:15], off
	s_barrier
	s_add_i32 s16, s2, s16
	s_cmpk_lt_i32 s16, 0x300
	s_cbranch_scc0 .LBB0_870
.LBB0_828:
	v_mov_b32_e32 v100, 0
	v_mov_b32_e32 v101, 0
	v_mov_b32_e32 v102, 0
	v_mov_b32_e32 v103, 0
	v_mov_b32_e32 v104, 0
	v_mov_b32_e32 v105, 0
	v_mov_b32_e32 v106, 0
	v_mov_b32_e32 v107, 0
	s_mul_hi_i32 s2, s16, 0x2aaaaaab
	s_lshr_b32 s3, s2, 31
	s_ashr_i32 s14, s2, 3
	s_add_i32 s14, s14, s3
	s_mul_i32 s2, s14, 48
	s_sub_i32 s2, s16, s2
	s_lshl_b32 s15, s2, 6
	v_or_b32_e32 v0, s15, v6
	s_movk_i32 s2, 0x1ff
	v_cmp_lt_i32_e32 vcc, s2, v0
	s_and_saveexec_b64 s[2:3], vcc
	s_cbranch_execz .LBB0_854
	s_cmpk_gt_u32 s15, 0x3ff
	s_mov_b64 s[4:5], -1
	s_cbranch_scc0 .LBB0_851
	s_cmpk_gt_u32 s15, 0x5ff
	s_cbranch_scc0 .LBB0_848
	s_cmpk_gt_u32 s15, 0x7ff
	s_cbranch_scc0 .LBB0_845
	s_cmpk_gt_u32 s15, 0x9ff
	s_cbranch_scc0 .LBB0_842
	s_cmpk_gt_u32 s15, 0xa7f
	s_cbranch_scc0 .LBB0_839
	s_cmpk_gt_u32 s15, 0xaff
	s_cbranch_scc0 .LBB0_836
	s_movk_i32 s4, 0xb10
	v_add_u32_e32 v3, 0xfffffd00, v0
	v_cmp_gt_u32_e32 vcc, s4, v0
	s_mov_b64 s[4:5], 0
	s_nop 0
	v_cndmask_b32_e32 v3, -1, v3, vcc

; DI void transpose_tiles(const float* src, int ldw, int Ks, bf16_t* dst, int Nn, int Kd, int kind, LAS float* tile) {
;     ...
;         { const int nn = tid & 63, kk = tid >> 6; const int off = colmap(kind, n0 + nn);
; #pragma unroll
;           for (int i = 0; i < 8; ++i) { const int k = k0 + kk + 8 * i; float v = 0.f; if (off >= 0 && k < Ks) v = src[(size_t)k * ldw + off]; tile[(kk + 8 * i) * 65 + nn] = v; } }
.LBB0_854:
	s_or_b64 exec, exec, s[2:3]
	s_lshl_b32 s14, s14, 6
	v_add_u32_e32 v3, s14, v7
	s_movk_i32 s2, 0x400
	v_cmp_lt_i32_e32 vcc, -1, v0
	v_cmp_gt_i32_e64 s[4:5], s2, v3
	v_lshl_add_u64 v[4:5], v[0:1], 2, s[10:11]
	s_and_b64 s[4:5], vcc, s[4:5]
	v_mov_b32_e32 v0, 0
	v_mov_b32_e32 v11, 0
	s_and_saveexec_b64 s[2:3], s[4:5]
	s_cbranch_execz .LBB0_856
	s_movk_i32 s4, 0x2c40
	v_mad_i64_i32 v[12:13], s[4:5], v3, s4, v[4:5]
	global_load_dword v100, v[12:13], off
.LBB0_856:
	s_or_b64 exec, exec, s[2:3]
	s_movk_i32 s2, 0x3f8
	v_cmp_gt_i32_e64 s[4:5], s2, v3
	s_and_b64 s[4:5], vcc, s[4:5]
	s_and_saveexec_b64 s[2:3], s[4:5]
	s_cbranch_execz .LBB0_858
	v_add_u32_e32 v0, 8, v3
	s_movk_i32 s4, 0x2c40
	v_mad_i64_i32 v[12:13], s[4:5], v0, s4, v[4:5]
	global_load_dword v101, v[12:13], off
.LBB0_858:
	s_or_b64 exec, exec, s[2:3]
	v_cmp_gt_i32_e64 s[4:5], s1, v3
	s_and_b64 s[4:5], vcc, s[4:5]
	v_mov_b32_e32 v0, 0
	v_mov_b32_e32 v11, 0
	s_and_saveexec_b64 s[2:3], s[4:5]
	s_cbranch_execz .LBB0_860
	v_add_u32_e32 v11, 16, v3
	s_movk_i32 s4, 0x2c40
	v_mad_i64_i32 v[12:13], s[4:5], v11, s4, v[4:5]
	global_load_dword v102, v[12:13], off
.LBB0_860:
	s_or_b64 exec, exec, s[2:3]
	s_movk_i32 s2, 0x3e8
	v_cmp_gt_i32_e64 s[4:5], s2, v3
	s_and_b64 s[4:5], vcc, s[4:5]
	s_and_saveexec_b64 s[2:3], s[4:5]
	s_cbranch_execz .LBB0_862
	v_add_u32_e32 v0, 24, v3
	s_movk_i32 s4, 0x2c40
	v_mad_i64_i32 v[12:13], s[4:5], v0, s4, v[4:5]
	global_load_dword v103, v[12:13], off
.LBB0_862:
	s_or_b64 exec, exec, s[2:3]
	s_movk_i32 s2, 0x3e0
	v_cmp_gt_i32_e64 s[4:5], s2, v3
	s_and_b64 s[4:5], vcc, s[4:5]
	v_mov_b32_e32 v0, 0
	v_mov_b32_e32 v11, 0
	s_and_saveexec_b64 s[2:3], s[4:5]
	s_cbranch_execz .LBB0_864
	v_add_u32_e32 v11, 32, v3
	s_movk_i32 s4, 0x2c40
	v_mad_i64_i32 v[12:13], s[4:5], v11, s4, v[4:5]
	global_load_dword v104, v[12:13], off
.LBB0_864:
	s_or_b64 exec, exec, s[2:3]
	s_movk_i32 s2, 0x3d8
	v_cmp_gt_i32_e64 s[4:5], s2, v3
	s_and_b64 s[4:5], vcc, s[4:5]
	s_and_saveexec_b64 s[2:3], s[4:5]
	s_cbranch_execz .LBB0_866
	v_add_u32_e32 v0, 40, v3
	s_movk_i32 s4, 0x2c40
	v_mad_i64_i32 v[12:13], s[4:5], v0, s4, v[4:5]
	global_load_dword v105, v[12:13], off
.LBB0_866:
	s_or_b64 exec, exec, s[2:3]
	s_movk_i32 s2, 0x3d0
	v_cmp_gt_i32_e64 s[4:5], s2, v3
	s_and_b64 s[4:5], vcc, s[4:5]
	v_mov_b32_e32 v0, 0
	v_mov_b32_e32 v11, 0
	s_and_saveexec_b64 s[2:3], s[4:5]
	s_cbranch_execz .LBB0_868
	v_add_u32_e32 v11, 48, v3
	s_movk_i32 s4, 0x2c40
	v_mad_i64_i32 v[12:13], s[4:5], v11, s4, v[4:5]
	global_load_dword v106, v[12:13], off
.LBB0_868:
	s_or_b64 exec, exec, s[2:3]
	v_cmp_gt_i32_e64 s[4:5], s33, v3
	s_and_b64 s[4:5], vcc, s[4:5]
	s_and_saveexec_b64 s[2:3], s[4:5]
	s_cbranch_execz .LBB0_827
	v_add_u32_e32 v0, 56, v3
	s_movk_i32 s4, 0x2c40
	v_mad_i64_i32 v[4:5], s[4:5], v0, s4, v[4:5]
	global_load_dword v107, v[4:5], off
	s_branch .LBB0_827

; #define LAS __attribute__((address_space(3)))
; DI unsigned pk2(float lo, float hi) { return f2bf(lo) | (f2bf(hi) << 16); }
; #define BIDX() sgpr_opaque((int)__builtin_amdgcn_workgroup_id_x())
; #define GDIM() sgpr_opaque((int)__ockl_get_num_groups(0))
; DI int tid_opaque() { int t = threadIdx.x; asm volatile("" : "+v"(t)); return t; }
; DI void transpose_tiles(const float* src, int ldw, int Ks, bf16_t* dst, int Nn, int Kd, int kind, LAS float* tile) {
;     const int tid = tid_opaque(), ntn = Nn / 64, ntk = Kd / 64;
;     for (int it = BIDX(); it < ntn * ntk; it += GDIM()) {
;         const int n0 = (it % ntn) * 64, k0 = (it / ntn) * 64;
;         { const int nn = tid & 63, kk = tid >> 6; const int off = colmap(kind, n0 + nn);
; #pragma unroll
;           for (int i = 0; i < 8; ++i) { const int k = k0 + kk + 8 * i; float v = 0.f; if (off >= 0 && k < Ks) v = src[(size_t)k * ldw + off]; tile[(kk + 8 * i) * 65 + nn] = v; } }
;         __syncthreads();
;         { const int nn = tid >> 3, kc = tid & 7; const LAS float* s = tile + (kc * 8) * 65 + nn;
;           u32x4 o; o.x = pk2(s[0], s[65]); o.y = pk2(s[2 * 65], s[3 * 65]); o.z = pk2(s[4 * 65], s[5 * 65]); o.w = pk2(s[6 * 65], s[7 * 65]);
;           *(u32x4*)(dst + (size_t)(n0 + nn) * Kd + k0 + kc * 8) = o; }
;         __syncthreads();
.LBB0_872:
	s_or_b64 exec, exec, s[2:3]
	s_waitcnt vmcnt(0)
	ds_write_b32 v12, v100
	ds_write_b32 v12, v101 offset:2080
	ds_write_b32 v12, v102 offset:4160
	ds_write_b32 v12, v103 offset:6240
	ds_write_b32 v12, v104 offset:8320
	ds_write_b32 v12, v105 offset:10400
	ds_write_b32 v12, v106 offset:12480
	ds_write_b32 v12, v107 offset:14560
	s_waitcnt lgkmcnt(0)
	s_barrier
	ds_read2_b32 v[4:5], v11 offset1:65
	ds_read2_b32 v[6:7], v11 offset0:130 offset1:195
	s_mov_b32 s2, s30
	s_waitcnt lgkmcnt(1)
	v_bfe_u32 v0, v4, 16, 1
	v_add3_u32 v0, v4, v0, s31
	v_bfe_u32 v3, v5, 16, 1
	v_lshrrev_b32_e32 v0, 16, v0
	v_add3_u32 v3, v5, v3, s31
	v_and_or_b32 v4, v3, s0, v0
	v_add_u32_e32 v3, 0x400, v11
	ds_read2_b32 v[14:15], v3 offset0:4 offset1:69
	s_waitcnt lgkmcnt(1)
	v_bfe_u32 v0, v6, 16, 1
	v_add3_u32 v0, v6, v0, s31
	v_bfe_u32 v5, v7, 16, 1
	ds_read2_b32 v[16:17], v3 offset0:134 offset1:199
	v_lshrrev_b32_e32 v0, 16, v0
	v_add3_u32 v5, v7, v5, s31
	v_and_or_b32 v5, v5, s0, v0
	s_waitcnt lgkmcnt(1)
	v_bfe_u32 v0, v14, 16, 1
	v_add3_u32 v0, v14, v0, s31
	v_bfe_u32 v3, v15, 16, 1
	v_lshrrev_b32_e32 v0, 16, v0
	v_add3_u32 v3, v15, v3, s31
	v_add_u32_e32 v14, s15, v10
	v_and_or_b32 v6, v3, s0, v0
	s_waitcnt lgkmcnt(0)
	v_bfe_u32 v0, v16, 16, 1
	v_ashrrev_i32_e32 v15, 31, v14
	v_add3_u32 v0, v16, v0, s31
	v_bfe_u32 v3, v17, 16, 1
	v_lshlrev_b64 v[14:15], 11, v[14:15]
	v_lshrrev_b32_e32 v0, 16, v0
	v_add3_u32 v3, v17, v3, s31
	v_lshl_add_u64 v[14:15], s[12:13], 0, v[14:15]
	s_ashr_i32 s15, s14, 31
	v_and_or_b32 v7, v3, s0, v0
	v_lshl_add_u64 v[14:15], s[14:15], 1, v[14:15]
	v_mov_b32_e32 v3, v1
	v_lshl_add_u64 v[14:15], v[14:15], 0, v[2:3]
	global_store_dwordx4 v[14:15], v[4:7], off
	s_barrier
	s_add_i32 s18, s2, s18
	s_cmpk_lt_i32 s18, 0x100
	s_cbranch_scc0 .LBB0_889
.LBB0_873:
	v_mov_b32_e32 v100, 0
	v_mov_b32_e32 v101, 0
	v_mov_b32_e32 v102, 0
	v_mov_b32_e32 v103, 0
	v_mov_b32_e32 v104, 0
	v_mov_b32_e32 v105, 0
	v_mov_b32_e32 v106, 0
	v_mov_b32_e32 v107, 0
	s_ashr_i32 s2, s18, 31
	s_lshr_b32 s2, s2, 28
	s_add_i32 s2, s18, s2
	s_and_b32 s3, s2, -16
	s_sub_i32 s3, s18, s3
	s_lshl_b32 s2, s2, 2
	s_lshl_b32 s15, s3, 6
	s_and_b32 s14, s2, 0xffffffc0
	v_add_u32_e32 v4, s14, v9
	s_cmp_gt_i32 s3, -1
	s_movk_i32 s16, 0x400
	v_or_b32_e32 v0, s15, v8
	s_cselect_b64 s[2:3], -1, 0
	v_cmp_gt_i32_e32 vcc, s16, v4
	v_lshl_add_u64 v[6:7], v[0:1], 2, s[4:5]
	s_and_b64 s[20:21], s[2:3], vcc
	v_mov_b32_e32 v0, 0
	v_ashrrev_i32_e32 v5, 31, v4
	v_mov_b32_e32 v3, 0
	s_and_saveexec_b64 s[16:17], s[20:21]
	s_cbranch_execz .LBB0_875
	v_lshlrev_b64 v[14:15], 12, v[4:5]
	v_lshl_add_u64 v[14:15], v[6:7], 0, v[14:15]
	global_load_dword v100, v[14:15], off
.LBB0_875:
	s_or_b64 exec, exec, s[16:17]
	s_movk_i32 s16, 0x3f8
	v_cmp_gt_i32_e32 vcc, s16, v4
	s_and_b64 s[20:21], s[2:3], vcc
	s_and_saveexec_b64 s[16:17], s[20:21]
	s_cbranch_execz .LBB0_877
	v_lshlrev_b64 v[14:15], 12, v[4:5]
	v_lshl_add_u64 v[14:15], v[6:7], 0, v[14:15]
	v_add_co_u32_e32 v14, vcc, 0x8000, v14
	s_nop 1
	v_addc_co_u32_e32 v15, vcc, 0, v15, vcc
	global_load_dword v101, v[14:15], off
.LBB0_877:
	s_or_b64 exec, exec, s[16:17]
	v_cmp_gt_i32_e32 vcc, s1, v4
	s_and_b64 s[20:21], s[2:3], vcc
	v_mov_b32_e32 v0, 0
	v_mov_b32_e32 v3, 0
	s_and_saveexec_b64 s[16:17], s[20:21]
	s_cbranch_execz .LBB0_879
	v_lshlrev_b64 v[14:15], 12, v[4:5]
	v_lshl_add_u64 v[14:15], v[6:7], 0, v[14:15]
	v_add_co_u32_e32 v14, vcc, 0x10000, v14
	s_nop 1
	v_addc_co_u32_e32 v15, vcc, 0, v15, vcc
	global_load_dword v102, v[14:15], off
.LBB0_879:
	s_or_b64 exec, exec, s[16:17]
	s_movk_i32 s16, 0x3e8
	v_cmp_gt_i32_e32 vcc, s16, v4
	s_and_b64 s[20:21], s[2:3], vcc
	s_and_saveexec_b64 s[16:17], s[20:21]
	s_cbranch_execz .LBB0_881
	v_lshlrev_b64 v[14:15], 12, v[4:5]
	v_lshl_add_u64 v[14:15], v[6:7], 0, v[14:15]
	v_add_co_u32_e32 v14, vcc, 0x18000, v14
	s_nop 1
	v_addc_co_u32_e32 v15, vcc, 0, v15, vcc
	global_load_dword v103, v[14:15], off
.LBB0_881:
	s_or_b64 exec, exec, s[16:17]
	s_movk_i32 s16, 0x3e0
	v_cmp_gt_i32_e32 vcc, s16, v4
	s_and_b64 s[20:21], s[2:3], vcc
	v_mov_b32_e32 v0, 0
	v_mov_b32_e32 v3, 0
	s_and_saveexec_b64 s[16:17], s[20:21]
	s_cbranch_execz .LBB0_883
	v_lshlrev_b64 v[14:15], 12, v[4:5]
	v_lshl_add_u64 v[14:15], v[6:7], 0, v[14:15]
	v_add_co_u32_e32 v14, vcc, 0x20000, v14
	s_nop 1
	v_addc_co_u32_e32 v15, vcc, 0, v15, vcc
	global_load_dword v104, v[14:15], off
.LBB0_883:
	s_or_b64 exec, exec, s[16:17]
	s_movk_i32 s16, 0x3d8
	v_cmp_gt_i32_e32 vcc, s16, v4
	s_and_b64 s[20:21], s[2:3], vcc
	s_and_saveexec_b64 s[16:17], s[20:21]
	s_cbranch_execz .LBB0_885
	v_lshlrev_b64 v[14:15], 12, v[4:5]
	v_lshl_add_u64 v[14:15], v[6:7], 0, v[14:15]
	v_add_co_u32_e32 v14, vcc, 0x28000, v14
	s_nop 1
	v_addc_co_u32_e32 v15, vcc, 0, v15, vcc
	global_load_dword v105, v[14:15], off
.LBB0_885:
	s_or_b64 exec, exec, s[16:17]
	s_movk_i32 s16, 0x3d0
	v_cmp_gt_i32_e32 vcc, s16, v4
	s_and_b64 s[20:21], s[2:3], vcc
	v_mov_b32_e32 v0, 0
	v_mov_b32_e32 v3, 0
	s_and_saveexec_b64 s[16:17], s[20:21]
	s_cbranch_execz .LBB0_887
	v_lshlrev_b64 v[14:15], 12, v[4:5]
	v_lshl_add_u64 v[14:15], v[6:7], 0, v[14:15]
	v_add_co_u32_e32 v14, vcc, 0x30000, v14
	s_nop 1
	v_addc_co_u32_e32 v15, vcc, 0, v15, vcc
	global_load_dword v106, v[14:15], off
.LBB0_887:
	s_or_b64 exec, exec, s[16:17]
	v_cmp_gt_i32_e32 vcc, s33, v4
	s_and_b64 s[16:17], s[2:3], vcc
	s_and_saveexec_b64 s[2:3], s[16:17]
	s_cbranch_execz .LBB0_872
	v_lshlrev_b64 v[4:5], 12, v[4:5]
	v_lshl_add_u64 v[4:5], v[6:7], 0, v[4:5]
	v_add_co_u32_e32 v4, vcc, 0x38000, v4
	s_nop 1
	v_addc_co_u32_e32 v5, vcc, 0, v5, vcc
	global_load_dword v107, v[4:5], off
	s_branch .LBB0_872

; #define LAS __attribute__((address_space(3)))
; DI unsigned pk2(float lo, float hi) { return f2bf(lo) | (f2bf(hi) << 16); }
; #define BIDX() sgpr_opaque((int)__builtin_amdgcn_workgroup_id_x())
; #define GDIM() sgpr_opaque((int)__ockl_get_num_groups(0))
; DI int tid_opaque() { int t = threadIdx.x; asm volatile("" : "+v"(t)); return t; }
; DI void transpose_tiles(const float* src, int ldw, int Ks, bf16_t* dst, int Nn, int Kd, int kind, LAS float* tile) {
;     const int tid = tid_opaque(), ntn = Nn / 64, ntk = Kd / 64;
;     for (int it = BIDX(); it < ntn * ntk; it += GDIM()) {
;         const int n0 = (it % ntn) * 64, k0 = (it / ntn) * 64;
;         { const int nn = tid & 63, kk = tid >> 6; const int off = colmap(kind, n0 + nn);
; #pragma unroll
;           for (int i = 0; i < 8; ++i) { const int k = k0 + kk + 8 * i; float v = 0.f; if (off >= 0 && k < Ks) v = src[(size_t)k * ldw + off]; tile[(kk + 8 * i) * 65 + nn] = v; } }
;         __syncthreads();
;         { const int nn = tid >> 3, kc = tid & 7; const LAS float* s = tile + (kc * 8) * 65 + nn;
;           u32x4 o; o.x = pk2(s[0], s[65]); o.y = pk2(s[2 * 65], s[3 * 65]); o.z = pk2(s[4 * 65], s[5 * 65]); o.w = pk2(s[6 * 65], s[7 * 65]);
;           *(u32x4*)(dst + (size_t)(n0 + nn) * Kd + k0 + kc * 8) = o; }
;         __syncthreads();
.LBB0_891:
	s_or_b64 exec, exec, s[2:3]
	s_waitcnt vmcnt(0)
	ds_write_b32 v12, v100
	ds_write_b32 v12, v101 offset:2080
	ds_write_b32 v12, v102 offset:4160
	ds_write_b32 v12, v103 offset:6240
	ds_write_b32 v12, v104 offset:8320
	ds_write_b32 v12, v105 offset:10400
	ds_write_b32 v12, v106 offset:12480
	ds_write_b32 v12, v107 offset:14560
	s_waitcnt lgkmcnt(0)
	s_barrier
	ds_read2_b32 v[4:5], v11 offset1:65
	ds_read2_b32 v[6:7], v11 offset0:130 offset1:195
	s_mov_b32 s2, s30
	s_waitcnt lgkmcnt(1)
	v_bfe_u32 v0, v4, 16, 1
	v_add3_u32 v0, v4, v0, s31
	v_bfe_u32 v3, v5, 16, 1
	v_lshrrev_b32_e32 v0, 16, v0
	v_add3_u32 v3, v5, v3, s31
	v_and_or_b32 v4, v3, s0, v0
	v_add_u32_e32 v3, 0x400, v11
	ds_read2_b32 v[14:15], v3 offset0:4 offset1:69
	s_waitcnt lgkmcnt(1)
	v_bfe_u32 v0, v6, 16, 1
	v_add3_u32 v0, v6, v0, s31
	v_bfe_u32 v5, v7, 16, 1
	ds_read2_b32 v[16:17], v3 offset0:134 offset1:199
	v_lshrrev_b32_e32 v0, 16, v0
	v_add3_u32 v5, v7, v5, s31
	v_and_or_b32 v5, v5, s0, v0
	s_waitcnt lgkmcnt(1)
	v_bfe_u32 v0, v14, 16, 1
	v_add3_u32 v0, v14, v0, s31
	v_bfe_u32 v3, v15, 16, 1
	v_lshrrev_b32_e32 v0, 16, v0
	v_add3_u32 v3, v15, v3, s31
	v_add_u32_e32 v14, s17, v10
	v_and_or_b32 v6, v3, s0, v0
	s_waitcnt lgkmcnt(0)
	v_bfe_u32 v0, v16, 16, 1
	v_ashrrev_i32_e32 v15, 31, v14
	v_add3_u32 v0, v16, v0, s31
	v_bfe_u32 v3, v17, 16, 1
	v_lshlrev_b64 v[14:15], 11, v[14:15]
	v_lshrrev_b32_e32 v0, 16, v0
	v_add3_u32 v3, v17, v3, s31
	v_lshl_add_u64 v[14:15], s[12:13], 0, v[14:15]
	s_ashr_i32 s17, s16, 31
	v_and_or_b32 v7, v3, s0, v0
	v_lshl_add_u64 v[14:15], s[16:17], 1, v[14:15]
	v_mov_b32_e32 v3, v1
	v_lshl_add_u64 v[14:15], v[14:15], 0, v[2:3]
	global_store_dwordx4 v[14:15], v[4:7], off
	s_barrier
	s_add_i32 s20, s2, s20
	s_cmpk_lt_i32 s20, 0x100
	s_cbranch_scc0 .LBB0_908
.LBB0_892:
	v_mov_b32_e32 v100, 0
	v_mov_b32_e32 v101, 0
	v_mov_b32_e32 v102, 0
	v_mov_b32_e32 v103, 0
	v_mov_b32_e32 v104, 0
	v_mov_b32_e32 v105, 0
	v_mov_b32_e32 v106, 0
	v_mov_b32_e32 v107, 0
	s_ashr_i32 s2, s20, 31
	s_lshr_b32 s2, s2, 28
	s_add_i32 s2, s20, s2
	s_and_b32 s3, s2, -16
	s_sub_i32 s3, s20, s3
	s_lshl_b32 s2, s2, 2
	s_lshl_b32 s17, s3, 6
	s_and_b32 s16, s2, 0xffffffc0
	v_add_u32_e32 v4, s16, v9
	s_cmp_gt_i32 s3, -1
	s_movk_i32 s18, 0x400
	v_or_b32_e32 v0, s17, v8
	s_cselect_b64 s[2:3], -1, 0
	v_cmp_gt_i32_e32 vcc, s18, v4
	v_lshl_add_u64 v[6:7], v[0:1], 2, s[14:15]
	s_and_b64 s[42:43], s[2:3], vcc
	v_mov_b32_e32 v0, 0
	v_ashrrev_i32_e32 v5, 31, v4
	v_mov_b32_e32 v3, 0
	s_and_saveexec_b64 s[18:19], s[42:43]
	s_cbranch_execz .LBB0_894
	v_lshlrev_b64 v[14:15], 12, v[4:5]
	v_lshl_add_u64 v[14:15], v[6:7], 0, v[14:15]
	global_load_dword v100, v[14:15], off
.LBB0_894:
	s_or_b64 exec, exec, s[18:19]
	s_movk_i32 s18, 0x3f8
	v_cmp_gt_i32_e32 vcc, s18, v4
	s_and_b64 s[42:43], s[2:3], vcc
	s_and_saveexec_b64 s[18:19], s[42:43]
	s_cbranch_execz .LBB0_896
	v_lshlrev_b64 v[14:15], 12, v[4:5]
	v_lshl_add_u64 v[14:15], v[6:7], 0, v[14:15]
	v_add_co_u32_e32 v14, vcc, 0x8000, v14
	s_nop 1
	v_addc_co_u32_e32 v15, vcc, 0, v15, vcc
	global_load_dword v101, v[14:15], off
.LBB0_896:
	s_or_b64 exec, exec, s[18:19]
	v_cmp_gt_i32_e32 vcc, s1, v4
	s_and_b64 s[42:43], s[2:3], vcc
	v_mov_b32_e32 v0, 0
	v_mov_b32_e32 v3, 0
	s_and_saveexec_b64 s[18:19], s[42:43]
	s_cbranch_execz .LBB0_898
	v_lshlrev_b64 v[14:15], 12, v[4:5]
	v_lshl_add_u64 v[14:15], v[6:7], 0, v[14:15]
	v_add_co_u32_e32 v14, vcc, 0x10000, v14
	s_nop 1
	v_addc_co_u32_e32 v15, vcc, 0, v15, vcc
	global_load_dword v102, v[14:15], off
.LBB0_898:
	s_or_b64 exec, exec, s[18:19]
	s_movk_i32 s18, 0x3e8
	v_cmp_gt_i32_e32 vcc, s18, v4
	s_and_b64 s[42:43], s[2:3], vcc
	s_and_saveexec_b64 s[18:19], s[42:43]
	s_cbranch_execz .LBB0_900
	v_lshlrev_b64 v[14:15], 12, v[4:5]
	v_lshl_add_u64 v[14:15], v[6:7], 0, v[14:15]
	v_add_co_u32_e32 v14, vcc, 0x18000, v14
	s_nop 1
	v_addc_co_u32_e32 v15, vcc, 0, v15, vcc
	global_load_dword v103, v[14:15], off
.LBB0_900:
	s_or_b64 exec, exec, s[18:19]
	s_movk_i32 s18, 0x3e0
	v_cmp_gt_i32_e32 vcc, s18, v4
	s_and_b64 s[42:43], s[2:3], vcc
	v_mov_b32_e32 v0, 0
	v_mov_b32_e32 v3, 0
	s_and_saveexec_b64 s[18:19], s[42:43]
	s_cbranch_execz .LBB0_902
	v_lshlrev_b64 v[14:15], 12, v[4:5]
	v_lshl_add_u64 v[14:15], v[6:7], 0, v[14:15]
	v_add_co_u32_e32 v14, vcc, 0x20000, v14
	s_nop 1
	v_addc_co_u32_e32 v15, vcc, 0, v15, vcc
	global_load_dword v104, v[14:15], off
.LBB0_902:
	s_or_b64 exec, exec, s[18:19]
	s_movk_i32 s18, 0x3d8
	v_cmp_gt_i32_e32 vcc, s18, v4
	s_and_b64 s[42:43], s[2:3], vcc
	s_and_saveexec_b64 s[18:19], s[42:43]
	s_cbranch_execz .LBB0_904
	v_lshlrev_b64 v[14:15], 12, v[4:5]
	v_lshl_add_u64 v[14:15], v[6:7], 0, v[14:15]
	v_add_co_u32_e32 v14, vcc, 0x28000, v14
	s_nop 1
	v_addc_co_u32_e32 v15, vcc, 0, v15, vcc
	global_load_dword v105, v[14:15], off
.LBB0_904:
	s_or_b64 exec, exec, s[18:19]
	s_movk_i32 s18, 0x3d0
	v_cmp_gt_i32_e32 vcc, s18, v4
	s_and_b64 s[42:43], s[2:3], vcc
	v_mov_b32_e32 v0, 0
	v_mov_b32_e32 v3, 0
	s_and_saveexec_b64 s[18:19], s[42:43]
	s_cbranch_execz .LBB0_906
	v_lshlrev_b64 v[14:15], 12, v[4:5]
	v_lshl_add_u64 v[14:15], v[6:7], 0, v[14:15]
	v_add_co_u32_e32 v14, vcc, 0x30000, v14
	s_nop 1
	v_addc_co_u32_e32 v15, vcc, 0, v15, vcc
	global_load_dword v106, v[14:15], off
.LBB0_906:
	s_or_b64 exec, exec, s[18:19]
	v_cmp_gt_i32_e32 vcc, s33, v4
	s_and_b64 s[18:19], s[2:3], vcc
	s_and_saveexec_b64 s[2:3], s[18:19]
	s_cbranch_execz .LBB0_891
	v_lshlrev_b64 v[4:5], 12, v[4:5]
	v_lshl_add_u64 v[4:5], v[6:7], 0, v[4:5]
	v_add_co_u32_e32 v4, vcc, 0x38000, v4
	s_nop 1
	v_addc_co_u32_e32 v5, vcc, 0, v5, vcc
	global_load_dword v107, v[4:5], off
	s_branch .LBB0_891

; #define LAS __attribute__((address_space(3)))
; DI unsigned pk2(float lo, float hi) { return f2bf(lo) | (f2bf(hi) << 16); }
; #define BIDX() sgpr_opaque((int)__builtin_amdgcn_workgroup_id_x())
; #define GDIM() sgpr_opaque((int)__ockl_get_num_groups(0))
; DI int tid_opaque() { int t = threadIdx.x; asm volatile("" : "+v"(t)); return t; }
; DI void transpose_tiles(const float* src, int ldw, int Ks, bf16_t* dst, int Nn, int Kd, int kind, LAS float* tile) {
;     const int tid = tid_opaque(), ntn = Nn / 64, ntk = Kd / 64;
;     for (int it = BIDX(); it < ntn * ntk; it += GDIM()) {
;         const int n0 = (it % ntn) * 64, k0 = (it / ntn) * 64;
;         { const int nn = tid & 63, kk = tid >> 6; const int off = colmap(kind, n0 + nn);
; #pragma unroll
;           for (int i = 0; i < 8; ++i) { const int k = k0 + kk + 8 * i; float v = 0.f; if (off >= 0 && k < Ks) v = src[(size_t)k * ldw + off]; tile[(kk + 8 * i) * 65 + nn] = v; } }
;         __syncthreads();
;         { const int nn = tid >> 3, kc = tid & 7; const LAS float* s = tile + (kc * 8) * 65 + nn;
;           u32x4 o; o.x = pk2(s[0], s[65]); o.y = pk2(s[2 * 65], s[3 * 65]); o.z = pk2(s[4 * 65], s[5 * 65]); o.w = pk2(s[6 * 65], s[7 * 65]);
;           *(u32x4*)(dst + (size_t)(n0 + nn) * Kd + k0 + kc * 8) = o; }
;         __syncthreads();
.LBB0_910:
	s_or_b64 exec, exec, s[2:3]
	s_waitcnt vmcnt(0)
	ds_write_b32 v12, v100
	ds_write_b32 v12, v101 offset:2080
	ds_write_b32 v12, v102 offset:4160
	ds_write_b32 v12, v103 offset:6240
	ds_write_b32 v12, v104 offset:8320
	ds_write_b32 v12, v105 offset:10400
	ds_write_b32 v12, v106 offset:12480
	ds_write_b32 v12, v107 offset:14560
	s_waitcnt lgkmcnt(0)
	s_barrier
	ds_read2_b32 v[4:5], v11 offset1:65
	ds_read2_b32 v[6:7], v11 offset0:130 offset1:195
	s_mov_b32 s2, s30
	s_waitcnt lgkmcnt(1)
	v_bfe_u32 v0, v4, 16, 1
	v_add3_u32 v0, v4, v0, s31
	v_bfe_u32 v3, v5, 16, 1
	v_lshrrev_b32_e32 v0, 16, v0
	v_add3_u32 v3, v5, v3, s31
	v_and_or_b32 v4, v3, s0, v0
	v_add_u32_e32 v3, 0x400, v11
	ds_read2_b32 v[14:15], v3 offset0:4 offset1:69
	s_waitcnt lgkmcnt(1)
	v_bfe_u32 v0, v6, 16, 1
	v_add3_u32 v0, v6, v0, s31
	v_bfe_u32 v5, v7, 16, 1
	ds_read2_b32 v[16:17], v3 offset0:134 offset1:199
	v_lshrrev_b32_e32 v0, 16, v0
	v_add3_u32 v5, v7, v5, s31
	v_and_or_b32 v5, v5, s0, v0
	s_waitcnt lgkmcnt(1)
	v_bfe_u32 v0, v14, 16, 1
	v_add3_u32 v0, v14, v0, s31
	v_bfe_u32 v3, v15, 16, 1
	v_lshrrev_b32_e32 v0, 16, v0
	v_add3_u32 v3, v15, v3, s31
	v_add_u32_e32 v14, s19, v10
	v_and_or_b32 v6, v3, s0, v0
	s_waitcnt lgkmcnt(0)
	v_bfe_u32 v0, v16, 16, 1
	v_ashrrev_i32_e32 v15, 31, v14
	v_add3_u32 v0, v16, v0, s31
	v_bfe_u32 v3, v17, 16, 1
	v_lshlrev_b64 v[14:15], 11, v[14:15]
	v_lshrrev_b32_e32 v0, 16, v0
	v_add3_u32 v3, v17, v3, s31
	v_lshl_add_u64 v[14:15], s[16:17], 0, v[14:15]
	s_ashr_i32 s19, s18, 31
	v_and_or_b32 v7, v3, s0, v0
	v_lshl_add_u64 v[14:15], s[18:19], 1, v[14:15]
	v_mov_b32_e32 v3, v1
	v_lshl_add_u64 v[14:15], v[14:15], 0, v[2:3]
	global_store_dwordx4 v[14:15], v[4:7], off
	s_barrier
	s_add_i32 s42, s2, s42
	s_cmpk_lt_i32 s42, 0x100
	s_cbranch_scc0 .LBB0_927
.LBB0_911:
	v_mov_b32_e32 v100, 0
	v_mov_b32_e32 v101, 0
	v_mov_b32_e32 v102, 0
	v_mov_b32_e32 v103, 0
	v_mov_b32_e32 v104, 0
	v_mov_b32_e32 v105, 0
	v_mov_b32_e32 v106, 0
	v_mov_b32_e32 v107, 0
	s_ashr_i32 s2, s42, 31
	s_lshr_b32 s2, s2, 28
	s_add_i32 s2, s42, s2
	s_and_b32 s3, s2, -16
	s_sub_i32 s3, s42, s3
	s_lshl_b32 s2, s2, 2
	s_lshl_b32 s19, s3, 6
	s_and_b32 s18, s2, 0xffffffc0
	v_add_u32_e32 v4, s18, v9
	s_cmp_gt_i32 s3, -1
	s_movk_i32 s20, 0x400
	v_or_b32_e32 v0, s19, v8
	s_cselect_b64 s[2:3], -1, 0
	v_cmp_gt_i32_e32 vcc, s20, v4
	v_lshl_add_u64 v[6:7], v[0:1], 2, s[14:15]
	s_and_b64 s[44:45], s[2:3], vcc
	v_mov_b32_e32 v0, 0
	v_ashrrev_i32_e32 v5, 31, v4
	v_mov_b32_e32 v3, 0
	s_and_saveexec_b64 s[20:21], s[44:45]
	s_cbranch_execz .LBB0_913
	v_lshlrev_b64 v[14:15], 12, v[4:5]
	v_lshl_add_u64 v[14:15], v[6:7], 0, v[14:15]
	global_load_dword v100, v[14:15], off
.LBB0_913:
	s_or_b64 exec, exec, s[20:21]
	s_movk_i32 s20, 0x3f8
	v_cmp_gt_i32_e32 vcc, s20, v4
	s_and_b64 s[44:45], s[2:3], vcc
	s_and_saveexec_b64 s[20:21], s[44:45]
	s_cbranch_execz .LBB0_915
	v_lshlrev_b64 v[14:15], 12, v[4:5]
	v_lshl_add_u64 v[14:15], v[6:7], 0, v[14:15]
	v_add_co_u32_e32 v14, vcc, 0x8000, v14
	s_nop 1
	v_addc_co_u32_e32 v15, vcc, 0, v15, vcc
	global_load_dword v101, v[14:15], off
.LBB0_915:
	s_or_b64 exec, exec, s[20:21]
	v_cmp_gt_i32_e32 vcc, s1, v4
	s_and_b64 s[44:45], s[2:3], vcc
	v_mov_b32_e32 v0, 0
	v_mov_b32_e32 v3, 0
	s_and_saveexec_b64 s[20:21], s[44:45]
	s_cbranch_execz .LBB0_917
	v_lshlrev_b64 v[14:15], 12, v[4:5]
	v_lshl_add_u64 v[14:15], v[6:7], 0, v[14:15]
	v_add_co_u32_e32 v14, vcc, 0x10000, v14
	s_nop 1
	v_addc_co_u32_e32 v15, vcc, 0, v15, vcc
	global_load_dword v102, v[14:15], off
.LBB0_917:
	s_or_b64 exec, exec, s[20:21]
	s_movk_i32 s20, 0x3e8
	v_cmp_gt_i32_e32 vcc, s20, v4
	s_and_b64 s[44:45], s[2:3], vcc
	s_and_saveexec_b64 s[20:21], s[44:45]
	s_cbranch_execz .LBB0_919
	v_lshlrev_b64 v[14:15], 12, v[4:5]
	v_lshl_add_u64 v[14:15], v[6:7], 0, v[14:15]
	v_add_co_u32_e32 v14, vcc, 0x18000, v14
	s_nop 1
	v_addc_co_u32_e32 v15, vcc, 0, v15, vcc
	global_load_dword v103, v[14:15], off
.LBB0_919:
	s_or_b64 exec, exec, s[20:21]
	s_movk_i32 s20, 0x3e0
	v_cmp_gt_i32_e32 vcc, s20, v4
	s_and_b64 s[44:45], s[2:3], vcc
	v_mov_b32_e32 v0, 0
	v_mov_b32_e32 v3, 0
	s_and_saveexec_b64 s[20:21], s[44:45]
	s_cbranch_execz .LBB0_921
	v_lshlrev_b64 v[14:15], 12, v[4:5]
	v_lshl_add_u64 v[14:15], v[6:7], 0, v[14:15]
	v_add_co_u32_e32 v14, vcc, 0x20000, v14
	s_nop 1
	v_addc_co_u32_e32 v15, vcc, 0, v15, vcc
	global_load_dword v104, v[14:15], off
.LBB0_921:
	s_or_b64 exec, exec, s[20:21]
	s_movk_i32 s20, 0x3d8
	v_cmp_gt_i32_e32 vcc, s20, v4
	s_and_b64 s[44:45], s[2:3], vcc
	s_and_saveexec_b64 s[20:21], s[44:45]
	s_cbranch_execz .LBB0_923
	v_lshlrev_b64 v[14:15], 12, v[4:5]
	v_lshl_add_u64 v[14:15], v[6:7], 0, v[14:15]
	v_add_co_u32_e32 v14, vcc, 0x28000, v14
	s_nop 1
	v_addc_co_u32_e32 v15, vcc, 0, v15, vcc
	global_load_dword v105, v[14:15], off
.LBB0_923:
	s_or_b64 exec, exec, s[20:21]
	s_movk_i32 s20, 0x3d0
	v_cmp_gt_i32_e32 vcc, s20, v4
	s_and_b64 s[44:45], s[2:3], vcc
	v_mov_b32_e32 v0, 0
	v_mov_b32_e32 v3, 0
	s_and_saveexec_b64 s[20:21], s[44:45]
	s_cbranch_execz .LBB0_925
	v_lshlrev_b64 v[14:15], 12, v[4:5]
	v_lshl_add_u64 v[14:15], v[6:7], 0, v[14:15]
	v_add_co_u32_e32 v14, vcc, 0x30000, v14
	s_nop 1
	v_addc_co_u32_e32 v15, vcc, 0, v15, vcc
	global_load_dword v106, v[14:15], off
.LBB0_925:
	s_or_b64 exec, exec, s[20:21]
	v_cmp_gt_i32_e32 vcc, s33, v4
	s_and_b64 s[20:21], s[2:3], vcc
	s_and_saveexec_b64 s[2:3], s[20:21]
	s_cbranch_execz .LBB0_910
	v_lshlrev_b64 v[4:5], 12, v[4:5]
	v_lshl_add_u64 v[4:5], v[6:7], 0, v[4:5]
	v_add_co_u32_e32 v4, vcc, 0x38000, v4
	s_nop 1
	v_addc_co_u32_e32 v5, vcc, 0, v5, vcc
	global_load_dword v107, v[4:5], off
	s_branch .LBB0_910

; #define LAS __attribute__((address_space(3)))
; DI unsigned pk2(float lo, float hi) { return f2bf(lo) | (f2bf(hi) << 16); }
; #define BIDX() sgpr_opaque((int)__builtin_amdgcn_workgroup_id_x())
; #define GDIM() sgpr_opaque((int)__ockl_get_num_groups(0))
; DI int tid_opaque() { int t = threadIdx.x; asm volatile("" : "+v"(t)); return t; }
; DI void transpose_tiles(const float* src, int ldw, int Ks, bf16_t* dst, int Nn, int Kd, int kind, LAS float* tile) {
;     const int tid = tid_opaque(), ntn = Nn / 64, ntk = Kd / 64;
;     for (int it = BIDX(); it < ntn * ntk; it += GDIM()) {
;         const int n0 = (it % ntn) * 64, k0 = (it / ntn) * 64;
;         { const int nn = tid & 63, kk = tid >> 6; const int off = colmap(kind, n0 + nn);
; #pragma unroll
;           for (int i = 0; i < 8; ++i) { const int k = k0 + kk + 8 * i; float v = 0.f; if (off >= 0 && k < Ks) v = src[(size_t)k * ldw + off]; tile[(kk + 8 * i) * 65 + nn] = v; } }
;         __syncthreads();
;         { const int nn = tid >> 3, kc = tid & 7; const LAS float* s = tile + (kc * 8) * 65 + nn;
;           u32x4 o; o.x = pk2(s[0], s[65]); o.y = pk2(s[2 * 65], s[3 * 65]); o.z = pk2(s[4 * 65], s[5 * 65]); o.w = pk2(s[6 * 65], s[7 * 65]);
;           *(u32x4*)(dst + (size_t)(n0 + nn) * Kd + k0 + kc * 8) = o; }
;         __syncthreads();
.LBB0_929:
	s_or_b64 exec, exec, s[2:3]
	s_waitcnt vmcnt(0)
	ds_write_b32 v12, v100
	ds_write_b32 v12, v101 offset:2080
	ds_write_b32 v12, v102 offset:4160
	ds_write_b32 v12, v103 offset:6240
	ds_write_b32 v12, v104 offset:8320
	ds_write_b32 v12, v105 offset:10400
	ds_write_b32 v12, v106 offset:12480
	ds_write_b32 v12, v107 offset:14560
	s_waitcnt lgkmcnt(0)
	s_barrier
	ds_read2_b32 v[4:5], v11 offset1:65
	ds_read2_b32 v[6:7], v11 offset0:130 offset1:195
	s_mov_b32 s2, s30
	s_waitcnt lgkmcnt(1)
	v_bfe_u32 v0, v4, 16, 1
	v_add3_u32 v0, v4, v0, s31
	v_bfe_u32 v3, v5, 16, 1
	v_lshrrev_b32_e32 v0, 16, v0
	v_add3_u32 v3, v5, v3, s31
	v_and_or_b32 v4, v3, s0, v0
	v_add_u32_e32 v3, 0x400, v11
	ds_read2_b32 v[14:15], v3 offset0:4 offset1:69
	s_waitcnt lgkmcnt(1)
	v_bfe_u32 v0, v6, 16, 1
	v_add3_u32 v0, v6, v0, s31
	v_bfe_u32 v5, v7, 16, 1
	ds_read2_b32 v[16:17], v3 offset0:134 offset1:199
	v_lshrrev_b32_e32 v0, 16, v0
	v_add3_u32 v5, v7, v5, s31
	v_and_or_b32 v5, v5, s0, v0
	s_waitcnt lgkmcnt(1)
	v_bfe_u32 v0, v14, 16, 1
	v_add3_u32 v0, v14, v0, s31
	v_bfe_u32 v3, v15, 16, 1
	v_lshrrev_b32_e32 v0, 16, v0
	v_add3_u32 v3, v15, v3, s31
	v_add_u32_e32 v14, s17, v10
	v_and_or_b32 v6, v3, s0, v0
	s_waitcnt lgkmcnt(0)
	v_bfe_u32 v0, v16, 16, 1
	v_ashrrev_i32_e32 v15, 31, v14
	v_add3_u32 v0, v16, v0, s31
	v_bfe_u32 v3, v17, 16, 1
	v_lshlrev_b64 v[14:15], 11, v[14:15]
	v_lshrrev_b32_e32 v0, 16, v0
	v_add3_u32 v3, v17, v3, s31
	v_lshl_add_u64 v[14:15], s[14:15], 0, v[14:15]
	s_ashr_i32 s17, s16, 31
	v_and_or_b32 v7, v3, s0, v0
	v_lshl_add_u64 v[14:15], s[16:17], 1, v[14:15]
	v_mov_b32_e32 v3, v1
	v_lshl_add_u64 v[14:15], v[14:15], 0, v[2:3]
	global_store_dwordx4 v[14:15], v[4:7], off
	s_barrier
	s_add_i32 s20, s2, s20
	s_cmpk_lt_i32 s20, 0x100
	s_cbranch_scc0 .LBB0_946
.LBB0_930:
	v_mov_b32_e32 v100, 0
	v_mov_b32_e32 v101, 0
	v_mov_b32_e32 v102, 0
	v_mov_b32_e32 v103, 0
	v_mov_b32_e32 v104, 0
	v_mov_b32_e32 v105, 0
	v_mov_b32_e32 v106, 0
	v_mov_b32_e32 v107, 0
	s_ashr_i32 s2, s20, 31
	s_lshr_b32 s2, s2, 28
	s_add_i32 s2, s20, s2
	s_and_b32 s3, s2, -16
	s_sub_i32 s3, s20, s3
	s_lshl_b32 s2, s2, 2
	s_lshl_b32 s17, s3, 6
	s_and_b32 s16, s2, 0xffffffc0
	v_add_u32_e32 v4, s16, v9
	s_cmp_gt_i32 s3, -1
	s_movk_i32 s18, 0x400
	v_or_b32_e32 v0, s17, v8
	s_cselect_b64 s[2:3], -1, 0
	v_cmp_gt_i32_e32 vcc, s18, v4
	v_lshl_add_u64 v[6:7], v[0:1], 2, s[4:5]
	s_and_b64 s[42:43], s[2:3], vcc
	v_mov_b32_e32 v0, 0
	v_ashrrev_i32_e32 v5, 31, v4
	v_mov_b32_e32 v3, 0
	s_and_saveexec_b64 s[18:19], s[42:43]
	s_cbranch_execz .LBB0_932
	v_lshlrev_b64 v[14:15], 12, v[4:5]
	v_lshl_add_u64 v[14:15], v[6:7], 0, v[14:15]
	global_load_dword v100, v[14:15], off

; #define LAS __attribute__((address_space(3)))
; DI unsigned pk2(float lo, float hi) { return f2bf(lo) | (f2bf(hi) << 16); }
; #define BIDX() sgpr_opaque((int)__builtin_amdgcn_workgroup_id_x())
; #define GDIM() sgpr_opaque((int)__ockl_get_num_groups(0))
; DI int tid_opaque() { int t = threadIdx.x; asm volatile("" : "+v"(t)); return t; }
; DI void transpose_tiles(const float* src, int ldw, int Ks, bf16_t* dst, int Nn, int Kd, int kind, LAS float* tile) {
;     const int tid = tid_opaque(), ntn = Nn / 64, ntk = Kd / 64;
;     for (int it = BIDX(); it < ntn * ntk; it += GDIM()) {
;         const int n0 = (it % ntn) * 64, k0 = (it / ntn) * 64;
;         { const int nn = tid & 63, kk = tid >> 6; const int off = colmap(kind, n0 + nn);
; #pragma unroll
;           for (int i = 0; i < 8; ++i) { const int k = k0 + kk + 8 * i; float v = 0.f; if (off >= 0 && k < Ks) v = src[(size_t)k * ldw + off]; tile[(kk + 8 * i) * 65 + nn] = v; } }
;         __syncthreads();
;         { const int nn = tid >> 3, kc = tid & 7; const LAS float* s = tile + (kc * 8) * 65 + nn;
;           u32x4 o; o.x = pk2(s[0], s[65]); o.y = pk2(s[2 * 65], s[3 * 65]); o.z = pk2(s[4 * 65], s[5 * 65]); o.w = pk2(s[6 * 65], s[7 * 65]);
;           *(u32x4*)(dst + (size_t)(n0 + nn) * Kd + k0 + kc * 8) = o; }
;         __syncthreads();
.LBB0_948:
	s_or_b64 exec, exec, s[2:3]
	s_waitcnt vmcnt(0)
	ds_write_b32 v12, v100
	ds_write_b32 v12, v101 offset:2080
	ds_write_b32 v12, v102 offset:4160
	ds_write_b32 v12, v103 offset:6240
	ds_write_b32 v12, v104 offset:8320
	ds_write_b32 v12, v105 offset:10400
	ds_write_b32 v12, v106 offset:12480
	ds_write_b32 v12, v107 offset:14560
	s_waitcnt lgkmcnt(0)
	s_barrier
	ds_read2_b32 v[4:5], v11 offset1:65
	ds_read2_b32 v[6:7], v11 offset0:130 offset1:195
	s_mov_b32 s2, s30
	s_waitcnt lgkmcnt(1)
	v_bfe_u32 v0, v4, 16, 1
	v_add3_u32 v0, v4, v0, s31
	v_bfe_u32 v3, v5, 16, 1
	v_lshrrev_b32_e32 v0, 16, v0
	v_add3_u32 v3, v5, v3, s31
	v_and_or_b32 v4, v3, s0, v0
	v_add_u32_e32 v3, 0x400, v11
	ds_read2_b32 v[14:15], v3 offset0:4 offset1:69
	s_waitcnt lgkmcnt(1)
	v_bfe_u32 v0, v6, 16, 1
	v_add3_u32 v0, v6, v0, s31
	v_bfe_u32 v5, v7, 16, 1
	ds_read2_b32 v[16:17], v3 offset0:134 offset1:199
	v_lshrrev_b32_e32 v0, 16, v0
	v_add3_u32 v5, v7, v5, s31
	v_and_or_b32 v5, v5, s0, v0
	s_waitcnt lgkmcnt(1)
	v_bfe_u32 v0, v14, 16, 1
	v_add3_u32 v0, v14, v0, s31
	v_bfe_u32 v3, v15, 16, 1
	v_lshrrev_b32_e32 v0, 16, v0
	v_add3_u32 v3, v15, v3, s31
	v_add_u32_e32 v14, s21, v10
	v_and_or_b32 v6, v3, s0, v0
	s_waitcnt lgkmcnt(0)
	v_bfe_u32 v0, v16, 16, 1
	v_ashrrev_i32_e32 v15, 31, v14
	v_add3_u32 v0, v16, v0, s31
	v_bfe_u32 v3, v17, 16, 1
	v_lshlrev_b64 v[14:15], 11, v[14:15]
	v_lshrrev_b32_e32 v0, 16, v0
	v_add3_u32 v3, v17, v3, s31
	v_lshl_add_u64 v[14:15], s[18:19], 0, v[14:15]
	s_ashr_i32 s21, s20, 31
	v_and_or_b32 v7, v3, s0, v0
	v_lshl_add_u64 v[14:15], s[20:21], 1, v[14:15]
	v_mov_b32_e32 v3, v1
	v_lshl_add_u64 v[14:15], v[14:15], 0, v[2:3]
	global_store_dwordx4 v[14:15], v[4:7], off
	s_barrier
	s_add_i32 s42, s2, s42
	s_cmp_lt_i32 s42, 64
	s_cbranch_scc0 .LBB0_965
.LBB0_949:
	v_mov_b32_e32 v100, 0
	v_mov_b32_e32 v101, 0
	v_mov_b32_e32 v102, 0
	v_mov_b32_e32 v103, 0
	v_mov_b32_e32 v104, 0
	v_mov_b32_e32 v105, 0
	v_mov_b32_e32 v106, 0
	v_mov_b32_e32 v107, 0
	s_ashr_i32 s2, s42, 31
	s_lshr_b32 s2, s2, 30
	s_add_i32 s2, s42, s2
	s_and_b32 s3, s2, -4
	s_sub_i32 s3, s42, s3
	s_lshl_b32 s21, s3, 6
	s_lshl_b32 s2, s2, 4
	s_and_b32 s20, s2, 0xffffffc0
	v_or_b32_e32 v0, s21, v8
	s_movk_i32 s2, 0x80
	v_lshl_or_b32 v3, s3, 16, v8
	v_cmp_gt_i32_e32 vcc, s2, v0
	v_add_u32_e32 v4, s20, v9
	s_movk_i32 s2, 0x400
	v_cndmask_b32_e32 v0, -1, v3, vcc
	v_cmp_lt_i32_e64 s[4:5], -1, v0
	v_cmp_gt_i32_e32 vcc, s2, v4
	v_lshl_add_u64 v[6:7], v[0:1], 2, s[16:17]
	s_and_b64 s[44:45], s[4:5], vcc
	v_mov_b32_e32 v0, 0
	v_ashrrev_i32_e32 v5, 31, v4
	v_mov_b32_e32 v3, 0
	s_and_saveexec_b64 s[2:3], s[44:45]
	s_cbranch_execz .LBB0_951
	v_lshlrev_b64 v[14:15], 8, v[4:5]
	v_lshl_add_u64 v[14:15], v[6:7], 0, v[14:15]
	global_load_dword v100, v[14:15], off
.LBB0_951:
	s_or_b64 exec, exec, s[2:3]
	s_movk_i32 s2, 0x3f8
	v_cmp_gt_i32_e32 vcc, s2, v4
	s_and_b64 s[44:45], s[4:5], vcc
	s_and_saveexec_b64 s[2:3], s[44:45]
	s_cbranch_execz .LBB0_953
	v_lshlrev_b64 v[14:15], 8, v[4:5]
	v_lshl_add_u64 v[14:15], v[6:7], 0, v[14:15]
	global_load_dword v101, v[14:15], off offset:2048
.LBB0_953:
	s_or_b64 exec, exec, s[2:3]
	v_cmp_gt_i32_e32 vcc, s1, v4
	s_and_b64 s[44:45], s[4:5], vcc
	v_mov_b32_e32 v0, 0
	v_mov_b32_e32 v3, 0
	s_and_saveexec_b64 s[2:3], s[44:45]
	s_cbranch_execz .LBB0_955
	v_lshlrev_b64 v[14:15], 8, v[4:5]
	v_lshl_add_u64 v[14:15], v[6:7], 0, v[14:15]
	v_add_co_u32_e32 v14, vcc, 0x1000, v14
	s_nop 1
	v_addc_co_u32_e32 v15, vcc, 0, v15, vcc
	global_load_dword v102, v[14:15], off
.LBB0_955:
	s_or_b64 exec, exec, s[2:3]
	s_movk_i32 s2, 0x3e8
	v_cmp_gt_i32_e32 vcc, s2, v4
	s_and_b64 s[44:45], s[4:5], vcc
	s_and_saveexec_b64 s[2:3], s[44:45]
	s_cbranch_execz .LBB0_957
	v_lshlrev_b64 v[14:15], 8, v[4:5]
	v_lshl_add_u64 v[14:15], v[6:7], 0, v[14:15]
	v_add_co_u32_e32 v14, vcc, 0x1000, v14
	s_nop 1
	v_addc_co_u32_e32 v15, vcc, 0, v15, vcc
	global_load_dword v103, v[14:15], off offset:2048
.LBB0_957:
	s_or_b64 exec, exec, s[2:3]
	s_movk_i32 s2, 0x3e0
	v_cmp_gt_i32_e32 vcc, s2, v4
	s_and_b64 s[44:45], s[4:5], vcc
	v_mov_b32_e32 v0, 0
	v_mov_b32_e32 v3, 0
	s_and_saveexec_b64 s[2:3], s[44:45]
	s_cbranch_execz .LBB0_959
	v_lshlrev_b64 v[14:15], 8, v[4:5]
	v_lshl_add_u64 v[14:15], v[6:7], 0, v[14:15]
	v_add_co_u32_e32 v14, vcc, 0x2000, v14
	s_nop 1
	v_addc_co_u32_e32 v15, vcc, 0, v15, vcc
	global_load_dword v104, v[14:15], off
.LBB0_959:
	s_or_b64 exec, exec, s[2:3]
	s_movk_i32 s2, 0x3d8
	v_cmp_gt_i32_e32 vcc, s2, v4
	s_and_b64 s[44:45], s[4:5], vcc
	s_and_saveexec_b64 s[2:3], s[44:45]
	s_cbranch_execz .LBB0_961
	v_lshlrev_b64 v[14:15], 8, v[4:5]
	v_lshl_add_u64 v[14:15], v[6:7], 0, v[14:15]
	v_add_co_u32_e32 v14, vcc, 0x2000, v14
	s_nop 1
	v_addc_co_u32_e32 v15, vcc, 0, v15, vcc
	global_load_dword v105, v[14:15], off offset:2048
.LBB0_961:
	s_or_b64 exec, exec, s[2:3]
	s_movk_i32 s2, 0x3d0
	v_cmp_gt_i32_e32 vcc, s2, v4
	s_and_b64 s[44:45], s[4:5], vcc
	v_mov_b32_e32 v0, 0
	v_mov_b32_e32 v3, 0
	s_and_saveexec_b64 s[2:3], s[44:45]
	s_cbranch_execz .LBB0_963
	v_lshlrev_b64 v[14:15], 8, v[4:5]
	v_lshl_add_u64 v[14:15], v[6:7], 0, v[14:15]
	v_add_co_u32_e32 v14, vcc, 0x3000, v14
	s_nop 1
	v_addc_co_u32_e32 v15, vcc, 0, v15, vcc
	global_load_dword v106, v[14:15], off
.LBB0_963:
	s_or_b64 exec, exec, s[2:3]
	v_cmp_gt_i32_e32 vcc, s33, v4
	s_and_b64 s[4:5], s[4:5], vcc
	s_and_saveexec_b64 s[2:3], s[4:5]
	s_cbranch_execz .LBB0_948
	v_lshlrev_b64 v[4:5], 8, v[4:5]
	v_lshl_add_u64 v[4:5], v[6:7], 0, v[4:5]
	v_add_co_u32_e32 v4, vcc, 0x3000, v4
	s_nop 1
	v_addc_co_u32_e32 v5, vcc, 0, v5, vcc
	global_load_dword v107, v[4:5], off offset:2048
	s_branch .LBB0_948

; #define LAS __attribute__((address_space(3)))
; DI unsigned pk2(float lo, float hi) { return f2bf(lo) | (f2bf(hi) << 16); }
; #define BIDX() sgpr_opaque((int)__builtin_amdgcn_workgroup_id_x())
; #define GDIM() sgpr_opaque((int)__ockl_get_num_groups(0))
; DI int tid_opaque() { int t = threadIdx.x; asm volatile("" : "+v"(t)); return t; }
; DI void transpose_tiles(const float* src, int ldw, int Ks, bf16_t* dst, int Nn, int Kd, int kind, LAS float* tile) {
;     const int tid = tid_opaque(), ntn = Nn / 64, ntk = Kd / 64;
;     for (int it = BIDX(); it < ntn * ntk; it += GDIM()) {
;         const int n0 = (it % ntn) * 64, k0 = (it / ntn) * 64;
;         { const int nn = tid & 63, kk = tid >> 6; const int off = colmap(kind, n0 + nn);
; #pragma unroll
;           for (int i = 0; i < 8; ++i) { const int k = k0 + kk + 8 * i; float v = 0.f; if (off >= 0 && k < Ks) v = src[(size_t)k * ldw + off]; tile[(kk + 8 * i) * 65 + nn] = v; } }
;         __syncthreads();
;         { const int nn = tid >> 3, kc = tid & 7; const LAS float* s = tile + (kc * 8) * 65 + nn;
;           u32x4 o; o.x = pk2(s[0], s[65]); o.y = pk2(s[2 * 65], s[3 * 65]); o.z = pk2(s[4 * 65], s[5 * 65]); o.w = pk2(s[6 * 65], s[7 * 65]);
;           *(u32x4*)(dst + (size_t)(n0 + nn) * Kd + k0 + kc * 8) = o; }
;         __syncthreads();
.LBB0_967:
	s_or_b64 exec, exec, s[2:3]
	s_waitcnt vmcnt(0)
	ds_write_b32 v12, v100
	ds_write_b32 v12, v101 offset:2080
	ds_write_b32 v12, v102 offset:4160
	ds_write_b32 v12, v103 offset:6240
	ds_write_b32 v12, v104 offset:8320
	ds_write_b32 v12, v105 offset:10400
	ds_write_b32 v12, v106 offset:12480
	ds_write_b32 v12, v107 offset:14560
	s_waitcnt lgkmcnt(0)
	s_barrier
	ds_read2_b32 v[4:5], v11 offset1:65
	ds_read2_b32 v[6:7], v11 offset0:130 offset1:195
	s_mov_b32 s2, s30
	s_waitcnt lgkmcnt(1)
	v_bfe_u32 v0, v4, 16, 1
	v_add3_u32 v0, v4, v0, s31
	v_bfe_u32 v3, v5, 16, 1
	v_lshrrev_b32_e32 v0, 16, v0
	v_add3_u32 v3, v5, v3, s31
	v_and_or_b32 v4, v3, s0, v0
	v_add_u32_e32 v3, 0x400, v11
	ds_read2_b32 v[14:15], v3 offset0:4 offset1:69
	s_waitcnt lgkmcnt(1)
	v_bfe_u32 v0, v6, 16, 1
	v_add3_u32 v0, v6, v0, s31
	v_bfe_u32 v5, v7, 16, 1
	ds_read2_b32 v[16:17], v3 offset0:134 offset1:199
	v_lshrrev_b32_e32 v0, 16, v0
	v_add3_u32 v5, v7, v5, s31
	v_and_or_b32 v5, v5, s0, v0
	s_waitcnt lgkmcnt(1)
	v_bfe_u32 v0, v14, 16, 1
	v_add3_u32 v0, v14, v0, s31
	v_bfe_u32 v3, v15, 16, 1
	v_lshrrev_b32_e32 v0, 16, v0
	v_add3_u32 v3, v15, v3, s31
	v_add_u32_e32 v14, s19, v10
	v_and_or_b32 v6, v3, s0, v0
	s_waitcnt lgkmcnt(0)
	v_bfe_u32 v0, v16, 16, 1
	v_ashrrev_i32_e32 v15, 31, v14
	v_add3_u32 v0, v16, v0, s31
	v_bfe_u32 v3, v17, 16, 1
	v_lshlrev_b64 v[14:15], 11, v[14:15]
	v_lshrrev_b32_e32 v0, 16, v0
	v_add3_u32 v3, v17, v3, s31
	v_lshl_add_u64 v[14:15], s[16:17], 0, v[14:15]
	s_ashr_i32 s19, s18, 31
	v_and_or_b32 v7, v3, s0, v0
	v_lshl_add_u64 v[14:15], s[18:19], 1, v[14:15]
	v_mov_b32_e32 v3, v1
	v_lshl_add_u64 v[14:15], v[14:15], 0, v[2:3]
	global_store_dwordx4 v[14:15], v[4:7], off
	s_barrier
	s_add_i32 s20, s2, s20
	s_cmp_lt_i32 s20, 64
	s_cbranch_scc0 .LBB0_984
.LBB0_968:
	v_mov_b32_e32 v100, 0
	v_mov_b32_e32 v101, 0
	v_mov_b32_e32 v102, 0
	v_mov_b32_e32 v103, 0
	v_mov_b32_e32 v104, 0
	v_mov_b32_e32 v105, 0
	v_mov_b32_e32 v106, 0
	v_mov_b32_e32 v107, 0
	s_ashr_i32 s2, s20, 31
	s_lshr_b32 s2, s2, 30
	s_add_i32 s2, s20, s2
	s_and_b32 s3, s2, -4
	s_sub_i32 s3, s20, s3
	s_lshl_b32 s19, s3, 6
	s_lshl_b32 s2, s2, 4
	s_and_b32 s18, s2, 0xffffffc0
	v_or_b32_e32 v0, s19, v8
	s_movk_i32 s2, 0x80
	v_lshl_or_b32 v3, s3, 16, v8
	v_cmp_gt_i32_e32 vcc, s2, v0
	v_add_u32_e32 v4, s18, v9
	s_movk_i32 s2, 0x400
	v_cndmask_b32_e32 v0, -1, v3, vcc
	v_cmp_lt_i32_e64 s[4:5], -1, v0
	v_cmp_gt_i32_e32 vcc, s2, v4
	v_lshl_add_u64 v[6:7], v[0:1], 2, s[14:15]
	s_and_b64 s[42:43], s[4:5], vcc
	v_mov_b32_e32 v0, 0
	v_ashrrev_i32_e32 v5, 31, v4
	v_mov_b32_e32 v3, 0
	s_and_saveexec_b64 s[2:3], s[42:43]
	s_cbranch_execz .LBB0_970
	v_lshlrev_b64 v[14:15], 8, v[4:5]
	v_lshl_add_u64 v[14:15], v[6:7], 0, v[14:15]
	global_load_dword v100, v[14:15], off
.LBB0_970:
	s_or_b64 exec, exec, s[2:3]
	s_movk_i32 s2, 0x3f8
	v_cmp_gt_i32_e32 vcc, s2, v4
	s_and_b64 s[42:43], s[4:5], vcc
	s_and_saveexec_b64 s[2:3], s[42:43]
	s_cbranch_execz .LBB0_972
	v_lshlrev_b64 v[14:15], 8, v[4:5]
	v_lshl_add_u64 v[14:15], v[6:7], 0, v[14:15]
	global_load_dword v101, v[14:15], off offset:2048
.LBB0_972:
	s_or_b64 exec, exec, s[2:3]
	v_cmp_gt_i32_e32 vcc, s1, v4
	s_and_b64 s[42:43], s[4:5], vcc
	v_mov_b32_e32 v0, 0
	v_mov_b32_e32 v3, 0
	s_and_saveexec_b64 s[2:3], s[42:43]
	s_cbranch_execz .LBB0_974
	v_lshlrev_b64 v[14:15], 8, v[4:5]
	v_lshl_add_u64 v[14:15], v[6:7], 0, v[14:15]
	v_add_co_u32_e32 v14, vcc, 0x1000, v14
	s_nop 1
	v_addc_co_u32_e32 v15, vcc, 0, v15, vcc
	global_load_dword v102, v[14:15], off
.LBB0_974:
	s_or_b64 exec, exec, s[2:3]
	s_movk_i32 s2, 0x3e8
	v_cmp_gt_i32_e32 vcc, s2, v4
	s_and_b64 s[42:43], s[4:5], vcc
	s_and_saveexec_b64 s[2:3], s[42:43]
	s_cbranch_execz .LBB0_976
	v_lshlrev_b64 v[14:15], 8, v[4:5]
	v_lshl_add_u64 v[14:15], v[6:7], 0, v[14:15]
	v_add_co_u32_e32 v14, vcc, 0x1000, v14
	s_nop 1
	v_addc_co_u32_e32 v15, vcc, 0, v15, vcc
	global_load_dword v103, v[14:15], off offset:2048
.LBB0_976:
	s_or_b64 exec, exec, s[2:3]
	s_movk_i32 s2, 0x3e0
	v_cmp_gt_i32_e32 vcc, s2, v4
	s_and_b64 s[42:43], s[4:5], vcc
	v_mov_b32_e32 v0, 0
	v_mov_b32_e32 v3, 0
	s_and_saveexec_b64 s[2:3], s[42:43]
	s_cbranch_execz .LBB0_978
	v_lshlrev_b64 v[14:15], 8, v[4:5]
	v_lshl_add_u64 v[14:15], v[6:7], 0, v[14:15]
	v_add_co_u32_e32 v14, vcc, 0x2000, v14
	s_nop 1
	v_addc_co_u32_e32 v15, vcc, 0, v15, vcc
	global_load_dword v104, v[14:15], off
.LBB0_978:
	s_or_b64 exec, exec, s[2:3]
	s_movk_i32 s2, 0x3d8
	v_cmp_gt_i32_e32 vcc, s2, v4
	s_and_b64 s[42:43], s[4:5], vcc
	s_and_saveexec_b64 s[2:3], s[42:43]
	s_cbranch_execz .LBB0_980
	v_lshlrev_b64 v[14:15], 8, v[4:5]
	v_lshl_add_u64 v[14:15], v[6:7], 0, v[14:15]
	v_add_co_u32_e32 v14, vcc, 0x2000, v14
	s_nop 1
	v_addc_co_u32_e32 v15, vcc, 0, v15, vcc
	global_load_dword v105, v[14:15], off offset:2048
.LBB0_980:
	s_or_b64 exec, exec, s[2:3]
	s_movk_i32 s2, 0x3d0
	v_cmp_gt_i32_e32 vcc, s2, v4
	s_and_b64 s[42:43], s[4:5], vcc
	v_mov_b32_e32 v0, 0
	v_mov_b32_e32 v3, 0
	s_and_saveexec_b64 s[2:3], s[42:43]
	s_cbranch_execz .LBB0_982
	v_lshlrev_b64 v[14:15], 8, v[4:5]
	v_lshl_add_u64 v[14:15], v[6:7], 0, v[14:15]
	v_add_co_u32_e32 v14, vcc, 0x3000, v14
	s_nop 1
	v_addc_co_u32_e32 v15, vcc, 0, v15, vcc
	global_load_dword v106, v[14:15], off

; #define LAS __attribute__((address_space(3)))
; DI unsigned pk2(float lo, float hi) { return f2bf(lo) | (f2bf(hi) << 16); }
; #define BIDX() sgpr_opaque((int)__builtin_amdgcn_workgroup_id_x())
; #define GDIM() sgpr_opaque((int)__ockl_get_num_groups(0))
; DI int tid_opaque() { int t = threadIdx.x; asm volatile("" : "+v"(t)); return t; }
; DI void transpose_tiles(const float* src, int ldw, int Ks, bf16_t* dst, int Nn, int Kd, int kind, LAS float* tile) {
;     const int tid = tid_opaque(), ntn = Nn / 64, ntk = Kd / 64;
;     for (int it = BIDX(); it < ntn * ntk; it += GDIM()) {
;         const int n0 = (it % ntn) * 64, k0 = (it / ntn) * 64;
;         { const int nn = tid & 63, kk = tid >> 6; const int off = colmap(kind, n0 + nn);
; #pragma unroll
;           for (int i = 0; i < 8; ++i) { const int k = k0 + kk + 8 * i; float v = 0.f; if (off >= 0 && k < Ks) v = src[(size_t)k * ldw + off]; tile[(kk + 8 * i) * 65 + nn] = v; } }
;         __syncthreads();
;         { const int nn = tid >> 3, kc = tid & 7; const LAS float* s = tile + (kc * 8) * 65 + nn;
;           u32x4 o; o.x = pk2(s[0], s[65]); o.y = pk2(s[2 * 65], s[3 * 65]); o.z = pk2(s[4 * 65], s[5 * 65]); o.w = pk2(s[6 * 65], s[7 * 65]);
;           *(u32x4*)(dst + (size_t)(n0 + nn) * Kd + k0 + kc * 8) = o; }
;         __syncthreads();
.LBB0_986:
	s_or_b64 exec, exec, s[2:3]
	s_waitcnt vmcnt(0)
	ds_write_b32 v10, v100
	ds_write_b32 v10, v101 offset:2080
	ds_write_b32 v10, v102 offset:4160
	ds_write_b32 v10, v103 offset:6240
	ds_write_b32 v10, v104 offset:8320
	ds_write_b32 v10, v105 offset:10400
	ds_write_b32 v10, v106 offset:12480
	ds_write_b32 v10, v107 offset:14560
	s_waitcnt lgkmcnt(0)
	s_barrier
	ds_read2_b32 v[4:5], v9 offset1:65
	ds_read2_b32 v[14:15], v9 offset0:130 offset1:195
	s_mov_b32 s2, s30
	s_waitcnt lgkmcnt(1)
	v_bfe_u32 v0, v4, 16, 1
	v_add3_u32 v0, v4, v0, s31
	v_bfe_u32 v3, v5, 16, 1
	v_lshrrev_b32_e32 v0, 16, v0
	v_add3_u32 v3, v5, v3, s31
	v_and_or_b32 v12, v3, s0, v0
	v_add_u32_e32 v3, 0x400, v9
	ds_read2_b32 v[4:5], v3 offset0:4 offset1:69
	s_waitcnt lgkmcnt(1)
	v_bfe_u32 v0, v14, 16, 1
	v_add3_u32 v0, v14, v0, s31
	v_bfe_u32 v11, v15, 16, 1
	ds_read2_b32 v[16:17], v3 offset0:134 offset1:199
	v_lshrrev_b32_e32 v0, 16, v0
	v_add3_u32 v11, v15, v11, s31
	v_and_or_b32 v13, v11, s0, v0
	s_waitcnt lgkmcnt(1)
	v_bfe_u32 v0, v4, 16, 1
	v_add3_u32 v0, v4, v0, s31
	v_bfe_u32 v3, v5, 16, 1
	v_lshrrev_b32_e32 v0, 16, v0
	v_add3_u32 v3, v5, v3, s31
	v_add_u32_e32 v4, s17, v8
	v_and_or_b32 v14, v3, s0, v0
	s_waitcnt lgkmcnt(0)
	v_bfe_u32 v0, v16, 16, 1
	v_ashrrev_i32_e32 v5, 31, v4
	v_add3_u32 v0, v16, v0, s31
	v_bfe_u32 v3, v17, 16, 1
	v_lshlrev_b64 v[4:5], 11, v[4:5]
	v_lshrrev_b32_e32 v0, 16, v0
	v_add3_u32 v3, v17, v3, s31
	v_lshl_add_u64 v[4:5], s[12:13], 0, v[4:5]
	s_ashr_i32 s17, s16, 31
	v_and_or_b32 v15, v3, s0, v0
	v_lshl_add_u64 v[4:5], s[16:17], 1, v[4:5]
	v_mov_b32_e32 v3, v1
	v_lshl_add_u64 v[4:5], v[4:5], 0, v[2:3]
	global_store_dwordx4 v[4:5], v[12:15], off
	s_barrier
	s_add_i32 s18, s2, s18
	s_cmp_lt_i32 s18, 64
	s_cbranch_scc0 .LBB0_1003
.LBB0_987:
	v_mov_b32_e32 v100, 0
	v_mov_b32_e32 v101, 0
	v_mov_b32_e32 v102, 0
	v_mov_b32_e32 v103, 0
	v_mov_b32_e32 v104, 0
	v_mov_b32_e32 v105, 0
	v_mov_b32_e32 v106, 0
	v_mov_b32_e32 v107, 0
	s_ashr_i32 s2, s18, 31
	s_lshr_b32 s2, s2, 30
	s_add_i32 s2, s18, s2
	s_and_b32 s3, s2, 0x3fffffc
	s_sub_i32 s3, s18, s3
	s_lshl_b32 s17, s3, 6
	s_lshl_b32 s2, s2, 4
	s_and_b32 s16, s2, 0xffffffc0
	v_or_b32_e32 v0, s17, v6
	s_movk_i32 s2, 0xa0
	v_cmp_gt_i32_e32 vcc, s2, v0
	v_add_u32_e32 v3, s16, v7
	s_movk_i32 s2, 0x400
	v_cndmask_b32_e32 v0, -1, v0, vcc
	v_cmp_lt_i32_e32 vcc, -1, v0
	v_cmp_gt_i32_e64 s[4:5], s2, v3
	v_lshl_add_u64 v[4:5], v[0:1], 2, s[14:15]
	s_and_b64 s[4:5], vcc, s[4:5]
	v_mov_b32_e32 v0, 0
	v_mov_b32_e32 v11, 0
	s_and_saveexec_b64 s[2:3], s[4:5]
	s_cbranch_execz .LBB0_989
	s_movk_i32 s4, 0x280
	v_mad_i64_i32 v[12:13], s[4:5], v3, s4, v[4:5]
	global_load_dword v100, v[12:13], off
.LBB0_989:
	s_or_b64 exec, exec, s[2:3]
	s_movk_i32 s2, 0x3f8
	v_cmp_gt_i32_e64 s[4:5], s2, v3
	s_and_b64 s[4:5], vcc, s[4:5]
	s_and_saveexec_b64 s[2:3], s[4:5]
	s_cbranch_execz .LBB0_991
	v_add_u32_e32 v0, 8, v3
	s_movk_i32 s4, 0x280
	v_mad_i64_i32 v[12:13], s[4:5], v0, s4, v[4:5]
	global_load_dword v101, v[12:13], off
.LBB0_991:
	s_or_b64 exec, exec, s[2:3]
	v_cmp_gt_i32_e64 s[4:5], s1, v3
	s_and_b64 s[4:5], vcc, s[4:5]
	v_mov_b32_e32 v0, 0
	v_mov_b32_e32 v11, 0
	s_and_saveexec_b64 s[2:3], s[4:5]
	s_cbranch_execz .LBB0_993
	v_add_u32_e32 v11, 16, v3
	s_movk_i32 s4, 0x280
	v_mad_i64_i32 v[12:13], s[4:5], v11, s4, v[4:5]
	global_load_dword v102, v[12:13], off
.LBB0_993:
	s_or_b64 exec, exec, s[2:3]
	s_movk_i32 s2, 0x3e8
	v_cmp_gt_i32_e64 s[4:5], s2, v3
	s_and_b64 s[4:5], vcc, s[4:5]
	s_and_saveexec_b64 s[2:3], s[4:5]
	s_cbranch_execz .LBB0_995
	v_add_u32_e32 v0, 24, v3
	s_movk_i32 s4, 0x280
	v_mad_i64_i32 v[12:13], s[4:5], v0, s4, v[4:5]
	global_load_dword v103, v[12:13], off
.LBB0_995:
	s_or_b64 exec, exec, s[2:3]
	s_movk_i32 s2, 0x3e0
	v_cmp_gt_i32_e64 s[4:5], s2, v3
	s_and_b64 s[4:5], vcc, s[4:5]
	v_mov_b32_e32 v0, 0
	v_mov_b32_e32 v11, 0
	s_and_saveexec_b64 s[2:3], s[4:5]
	s_cbranch_execz .LBB0_997
	v_add_u32_e32 v11, 32, v3
	s_movk_i32 s4, 0x280
	v_mad_i64_i32 v[12:13], s[4:5], v11, s4, v[4:5]
	global_load_dword v104, v[12:13], off
.LBB0_997:
	s_or_b64 exec, exec, s[2:3]
	s_movk_i32 s2, 0x3d8
	v_cmp_gt_i32_e64 s[4:5], s2, v3
	s_and_b64 s[4:5], vcc, s[4:5]
	s_and_saveexec_b64 s[2:3], s[4:5]
	s_cbranch_execz .LBB0_999
	v_add_u32_e32 v0, 40, v3
	s_movk_i32 s4, 0x280
	v_mad_i64_i32 v[12:13], s[4:5], v0, s4, v[4:5]
	global_load_dword v105, v[12:13], off
.LBB0_999:
	s_or_b64 exec, exec, s[2:3]
	s_movk_i32 s2, 0x3d0
	v_cmp_gt_i32_e64 s[4:5], s2, v3
	s_and_b64 s[4:5], vcc, s[4:5]
	v_mov_b32_e32 v0, 0
	v_mov_b32_e32 v11, 0
	s_and_saveexec_b64 s[2:3], s[4:5]
	s_cbranch_execz .LBB0_1001
	v_add_u32_e32 v11, 48, v3
	s_movk_i32 s4, 0x280
	v_mad_i64_i32 v[12:13], s[4:5], v11, s4, v[4:5]
	global_load_dword v106, v[12:13], off
.LBB0_1001:
	s_or_b64 exec, exec, s[2:3]
	v_cmp_gt_i32_e64 s[4:5], s33, v3
	s_and_b64 s[4:5], vcc, s[4:5]
	s_and_saveexec_b64 s[2:3], s[4:5]
	s_cbranch_execz .LBB0_986
	v_add_u32_e32 v0, 56, v3
	s_movk_i32 s4, 0x280
	v_mad_i64_i32 v[4:5], s[4:5], v0, s4, v[4:5]
	global_load_dword v107, v[4:5], off
	s_branch .LBB0_986

; #define LAS __attribute__((address_space(3)))
; DI unsigned pk2(float lo, float hi) { return f2bf(lo) | (f2bf(hi) << 16); }
; #define BIDX() sgpr_opaque((int)__builtin_amdgcn_workgroup_id_x())
; #define GDIM() sgpr_opaque((int)__ockl_get_num_groups(0))
; DI int tid_opaque() { int t = threadIdx.x; asm volatile("" : "+v"(t)); return t; }
; DI void transpose_tiles(const float* src, int ldw, int Ks, bf16_t* dst, int Nn, int Kd, int kind, LAS float* tile) {
;     const int tid = tid_opaque(), ntn = Nn / 64, ntk = Kd / 64;
;     for (int it = BIDX(); it < ntn * ntk; it += GDIM()) {
;         const int n0 = (it % ntn) * 64, k0 = (it / ntn) * 64;
;         { const int nn = tid & 63, kk = tid >> 6; const int off = colmap(kind, n0 + nn);
; #pragma unroll
;           for (int i = 0; i < 8; ++i) { const int k = k0 + kk + 8 * i; float v = 0.f; if (off >= 0 && k < Ks) v = src[(size_t)k * ldw + off]; tile[(kk + 8 * i) * 65 + nn] = v; } }
;         __syncthreads();
;         { const int nn = tid >> 3, kc = tid & 7; const LAS float* s = tile + (kc * 8) * 65 + nn;
;           u32x4 o; o.x = pk2(s[0], s[65]); o.y = pk2(s[2 * 65], s[3 * 65]); o.z = pk2(s[4 * 65], s[5 * 65]); o.w = pk2(s[6 * 65], s[7 * 65]);
;           *(u32x4*)(dst + (size_t)(n0 + nn) * Kd + k0 + kc * 8) = o; }
;         __syncthreads();
.LBB0_1005:
	s_or_b64 exec, exec, s[2:3]
	s_waitcnt vmcnt(0)
	ds_write_b32 v12, v100
	ds_write_b32 v12, v101 offset:2080
	ds_write_b32 v12, v102 offset:4160
	ds_write_b32 v12, v103 offset:6240
	ds_write_b32 v12, v104 offset:8320
	ds_write_b32 v12, v105 offset:10400
	ds_write_b32 v12, v106 offset:12480
	ds_write_b32 v12, v107 offset:14560
	s_waitcnt lgkmcnt(0)
	s_barrier
	ds_read2_b32 v[4:5], v11 offset1:65
	ds_read2_b32 v[6:7], v11 offset0:130 offset1:195
	s_mov_b32 s2, s30
	s_waitcnt lgkmcnt(1)
	v_bfe_u32 v0, v4, 16, 1
	v_add3_u32 v0, v4, v0, s31
	v_bfe_u32 v3, v5, 16, 1
	v_lshrrev_b32_e32 v0, 16, v0
	v_add3_u32 v3, v5, v3, s31
	v_and_or_b32 v4, v3, s0, v0
	v_add_u32_e32 v3, 0x400, v11
	ds_read2_b32 v[14:15], v3 offset0:4 offset1:69
	s_waitcnt lgkmcnt(1)
	v_bfe_u32 v0, v6, 16, 1
	v_add3_u32 v0, v6, v0, s31
	v_bfe_u32 v5, v7, 16, 1
	ds_read2_b32 v[16:17], v3 offset0:134 offset1:199
	v_lshrrev_b32_e32 v0, 16, v0
	v_add3_u32 v5, v7, v5, s31
	v_and_or_b32 v5, v5, s0, v0
	s_waitcnt lgkmcnt(1)
	v_bfe_u32 v0, v14, 16, 1
	v_add3_u32 v0, v14, v0, s31
	v_bfe_u32 v3, v15, 16, 1
	v_lshrrev_b32_e32 v0, 16, v0
	v_add3_u32 v3, v15, v3, s31
	v_add_u32_e32 v14, s17, v10
	v_and_or_b32 v6, v3, s0, v0
	s_waitcnt lgkmcnt(0)
	v_bfe_u32 v0, v16, 16, 1
	v_ashrrev_i32_e32 v15, 31, v14
	v_add3_u32 v0, v16, v0, s31
	v_bfe_u32 v3, v17, 16, 1
	v_lshlrev_b64 v[14:15], 7, v[14:15]
	v_lshrrev_b32_e32 v0, 16, v0
	v_add3_u32 v3, v17, v3, s31
	v_lshl_add_u64 v[14:15], s[14:15], 0, v[14:15]
	s_ashr_i32 s17, s16, 31
	v_and_or_b32 v7, v3, s0, v0
	v_lshl_add_u64 v[14:15], s[16:17], 1, v[14:15]
	v_mov_b32_e32 v3, v1
	v_lshl_add_u64 v[14:15], v[14:15], 0, v[2:3]
	global_store_dwordx4 v[14:15], v[4:7], off
	s_barrier
	s_add_i32 s21, s2, s21
	s_cmp_lt_i32 s21, 16
	s_cbranch_scc0 .LBB0_1022
.LBB0_1006:
	v_mov_b32_e32 v100, 0
	v_mov_b32_e32 v101, 0
	v_mov_b32_e32 v102, 0
	v_mov_b32_e32 v103, 0
	v_mov_b32_e32 v104, 0
	v_mov_b32_e32 v105, 0
	v_mov_b32_e32 v106, 0
	v_mov_b32_e32 v107, 0
	s_ashr_i32 s2, s21, 31
	s_lshr_b32 s2, s2, 28
	s_add_i32 s2, s21, s2
	s_and_b32 s3, s2, -16
	s_sub_i32 s3, s21, s3
	s_lshl_b32 s2, s2, 2
	s_lshl_b32 s17, s3, 6
	s_and_b32 s16, s2, 0xffffffc0
	v_add_u32_e32 v4, s16, v9
	s_cmp_gt_i32 s3, -1
	v_or_b32_e32 v0, s17, v8
	s_cselect_b64 s[2:3], -1, 0
	v_cmp_gt_i32_e32 vcc, 64, v4
	v_lshl_add_u64 v[6:7], v[0:1], 2, s[12:13]
	s_and_b64 s[42:43], s[2:3], vcc
	v_mov_b32_e32 v0, 0
	v_ashrrev_i32_e32 v5, 31, v4
	v_mov_b32_e32 v3, 0
	s_and_saveexec_b64 s[18:19], s[42:43]
	s_cbranch_execz .LBB0_1008
	v_lshlrev_b64 v[14:15], 12, v[4:5]
	v_lshl_add_u64 v[14:15], v[6:7], 0, v[14:15]
	global_load_dword v100, v[14:15], off
.LBB0_1008:
	s_or_b64 exec, exec, s[18:19]
	v_cmp_gt_i32_e32 vcc, 56, v4
	s_and_b64 s[42:43], s[2:3], vcc
	s_and_saveexec_b64 s[18:19], s[42:43]
	s_cbranch_execz .LBB0_1010
	v_lshlrev_b64 v[14:15], 12, v[4:5]
	v_lshl_add_u64 v[14:15], v[6:7], 0, v[14:15]
	v_add_co_u32_e32 v14, vcc, 0x8000, v14
	s_nop 1
	v_addc_co_u32_e32 v15, vcc, 0, v15, vcc
	global_load_dword v101, v[14:15], off
.LBB0_1010:
	s_or_b64 exec, exec, s[18:19]
	v_cmp_gt_i32_e32 vcc, 48, v4
	s_and_b64 s[42:43], s[2:3], vcc
	v_mov_b32_e32 v0, 0
	v_mov_b32_e32 v3, 0
	s_and_saveexec_b64 s[18:19], s[42:43]
	s_cbranch_execz .LBB0_1012
	v_lshlrev_b64 v[14:15], 12, v[4:5]
	v_lshl_add_u64 v[14:15], v[6:7], 0, v[14:15]
	v_add_co_u32_e32 v14, vcc, 0x10000, v14
	s_nop 1
	v_addc_co_u32_e32 v15, vcc, 0, v15, vcc
	global_load_dword v102, v[14:15], off
.LBB0_1012:
	s_or_b64 exec, exec, s[18:19]
	v_cmp_gt_i32_e32 vcc, 40, v4
	s_and_b64 s[42:43], s[2:3], vcc
	s_and_saveexec_b64 s[18:19], s[42:43]
	s_cbranch_execz .LBB0_1014
	v_lshlrev_b64 v[14:15], 12, v[4:5]
	v_lshl_add_u64 v[14:15], v[6:7], 0, v[14:15]
	v_add_co_u32_e32 v14, vcc, 0x18000, v14
	s_nop 1
	v_addc_co_u32_e32 v15, vcc, 0, v15, vcc
	global_load_dword v103, v[14:15], off
.LBB0_1014:
	s_or_b64 exec, exec, s[18:19]
	v_cmp_gt_i32_e32 vcc, 32, v4
	s_and_b64 s[42:43], s[2:3], vcc
	v_mov_b32_e32 v0, 0
	v_mov_b32_e32 v3, 0
	s_and_saveexec_b64 s[18:19], s[42:43]
	s_cbranch_execz .LBB0_1016
	v_lshlrev_b64 v[14:15], 12, v[4:5]
	v_lshl_add_u64 v[14:15], v[6:7], 0, v[14:15]
	v_add_co_u32_e32 v14, vcc, 0x20000, v14
	s_nop 1
	v_addc_co_u32_e32 v15, vcc, 0, v15, vcc
	global_load_dword v104, v[14:15], off
.LBB0_1016:
	s_or_b64 exec, exec, s[18:19]
	v_cmp_gt_i32_e32 vcc, 24, v4
	s_and_b64 s[42:43], s[2:3], vcc
	s_and_saveexec_b64 s[18:19], s[42:43]
	s_cbranch_execz .LBB0_1018
	v_lshlrev_b64 v[14:15], 12, v[4:5]
	v_lshl_add_u64 v[14:15], v[6:7], 0, v[14:15]
	v_add_co_u32_e32 v14, vcc, 0x28000, v14
	s_nop 1
	v_addc_co_u32_e32 v15, vcc, 0, v15, vcc
	global_load_dword v105, v[14:15], off
.LBB0_1018:
	s_or_b64 exec, exec, s[18:19]
	v_cmp_gt_i32_e32 vcc, 16, v4
	s_and_b64 s[42:43], s[2:3], vcc
	v_mov_b32_e32 v0, 0
	v_mov_b32_e32 v3, 0
	s_and_saveexec_b64 s[18:19], s[42:43]
	s_cbranch_execz .LBB0_1020
	v_lshlrev_b64 v[14:15], 12, v[4:5]
	v_lshl_add_u64 v[14:15], v[6:7], 0, v[14:15]
	v_add_co_u32_e32 v14, vcc, 0x30000, v14
	s_nop 1
	v_addc_co_u32_e32 v15, vcc, 0, v15, vcc
	global_load_dword v106, v[14:15], off
.LBB0_1020:
	s_or_b64 exec, exec, s[18:19]
	v_cmp_gt_i32_e32 vcc, 8, v4
	s_and_b64 s[18:19], s[2:3], vcc
	s_and_saveexec_b64 s[2:3], s[18:19]
	s_cbranch_execz .LBB0_1005
	v_lshlrev_b64 v[4:5], 12, v[4:5]
	v_lshl_add_u64 v[4:5], v[6:7], 0, v[4:5]
	v_add_co_u32_e32 v4, vcc, 0x38000, v4
	s_nop 1
	v_addc_co_u32_e32 v5, vcc, 0, v5, vcc
	global_load_dword v107, v[4:5], off
	s_branch .LBB0_1005

; #define LAS __attribute__((address_space(3)))
; DI unsigned pk2(float lo, float hi) { return f2bf(lo) | (f2bf(hi) << 16); }
; #define BIDX() sgpr_opaque((int)__builtin_amdgcn_workgroup_id_x())
; #define GDIM() sgpr_opaque((int)__ockl_get_num_groups(0))
; DI int tid_opaque() { int t = threadIdx.x; asm volatile("" : "+v"(t)); return t; }
; DI void transpose_tiles(const float* src, int ldw, int Ks, bf16_t* dst, int Nn, int Kd, int kind, LAS float* tile) {
;     const int tid = tid_opaque(), ntn = Nn / 64, ntk = Kd / 64;
;     for (int it = BIDX(); it < ntn * ntk; it += GDIM()) {
;         const int n0 = (it % ntn) * 64, k0 = (it / ntn) * 64;
;         { const int nn = tid & 63, kk = tid >> 6; const int off = colmap(kind, n0 + nn);
; #pragma unroll
;           for (int i = 0; i < 8; ++i) { const int k = k0 + kk + 8 * i; float v = 0.f; if (off >= 0 && k < Ks) v = src[(size_t)k * ldw + off]; tile[(kk + 8 * i) * 65 + nn] = v; } }
;         __syncthreads();
;         { const int nn = tid >> 3, kc = tid & 7; const LAS float* s = tile + (kc * 8) * 65 + nn;
;           u32x4 o; o.x = pk2(s[0], s[65]); o.y = pk2(s[2 * 65], s[3 * 65]); o.z = pk2(s[4 * 65], s[5 * 65]); o.w = pk2(s[6 * 65], s[7 * 65]);
;           *(u32x4*)(dst + (size_t)(n0 + nn) * Kd + k0 + kc * 8) = o; }
;         __syncthreads();
.LBB0_1024:
	s_or_b64 exec, exec, s[2:3]
	s_waitcnt vmcnt(0)
	ds_write_b32 v12, v100
	ds_write_b32 v12, v101 offset:2080
	ds_write_b32 v12, v102 offset:4160
	ds_write_b32 v12, v103 offset:6240
	ds_write_b32 v12, v104 offset:8320
	ds_write_b32 v12, v105 offset:10400
	ds_write_b32 v12, v106 offset:12480
	ds_write_b32 v12, v107 offset:14560
	s_waitcnt lgkmcnt(0)
	s_barrier
	ds_read2_b32 v[4:5], v11 offset1:65
	ds_read2_b32 v[6:7], v11 offset0:130 offset1:195
	s_ashr_i32 s17, s16, 31
	s_mov_b32 s2, s30
	s_waitcnt lgkmcnt(1)
	v_bfe_u32 v0, v4, 16, 1
	v_add3_u32 v0, v4, v0, s31
	v_bfe_u32 v3, v5, 16, 1
	v_lshrrev_b32_e32 v0, 16, v0
	v_add3_u32 v3, v5, v3, s31
	v_and_or_b32 v4, v3, s0, v0
	v_add_u32_e32 v3, 0x400, v11
	ds_read2_b32 v[14:15], v3 offset0:4 offset1:69
	s_waitcnt lgkmcnt(1)
	v_bfe_u32 v0, v6, 16, 1
	v_add3_u32 v0, v6, v0, s31
	v_bfe_u32 v5, v7, 16, 1
	ds_read2_b32 v[16:17], v3 offset0:134 offset1:199
	v_lshrrev_b32_e32 v0, 16, v0
	v_add3_u32 v5, v7, v5, s31
	v_and_or_b32 v5, v5, s0, v0
	s_waitcnt lgkmcnt(1)
	v_bfe_u32 v0, v14, 16, 1
	v_add3_u32 v0, v14, v0, s31
	v_bfe_u32 v3, v15, 16, 1
	v_lshrrev_b32_e32 v0, 16, v0
	v_add3_u32 v3, v15, v3, s31
	v_add_u32_e32 v14, s5, v10
	v_and_or_b32 v6, v3, s0, v0
	s_waitcnt lgkmcnt(0)
	v_bfe_u32 v0, v16, 16, 1
	v_ashrrev_i32_e32 v15, 31, v14
	v_add3_u32 v0, v16, v0, s31
	v_bfe_u32 v3, v17, 16, 1
	v_lshlrev_b64 v[14:15], 7, v[14:15]
	v_lshrrev_b32_e32 v0, 16, v0
	v_add3_u32 v3, v17, v3, s31
	v_lshl_add_u64 v[14:15], s[14:15], 0, v[14:15]
	v_and_or_b32 v7, v3, s0, v0
	v_lshl_add_u64 v[14:15], s[16:17], 1, v[14:15]
	v_mov_b32_e32 v3, v1
	v_lshl_add_u64 v[14:15], v[14:15], 0, v[2:3]
	global_store_dwordx4 v[14:15], v[4:7], off
	s_barrier
	s_add_i32 s21, s2, s21
	s_cmp_lt_i32 s21, 16
	s_cbranch_scc0 .LBB0_1041
.LBB0_1025:
	v_mov_b32_e32 v100, 0
	v_mov_b32_e32 v101, 0
	v_mov_b32_e32 v102, 0
	v_mov_b32_e32 v103, 0
	v_mov_b32_e32 v104, 0
	v_mov_b32_e32 v105, 0
	v_mov_b32_e32 v106, 0
	v_mov_b32_e32 v107, 0
	s_ashr_i32 s2, s21, 31
	s_lshr_b32 s2, s2, 28
	s_add_i32 s2, s21, s2
	s_and_b32 s3, s2, -16
	s_sub_i32 s3, s21, s3
	s_lshl_b32 s2, s2, 2
	s_lshl_b32 s5, s3, 6
	s_and_b32 s16, s2, 0xffffffc0
	v_add_u32_e32 v4, s16, v9
	s_cmp_gt_i32 s3, -1
	v_or_b32_e32 v0, s5, v8
	s_cselect_b64 s[2:3], -1, 0
	v_cmp_gt_i32_e32 vcc, 64, v4
	v_lshl_add_u64 v[6:7], v[0:1], 2, s[12:13]
	s_and_b64 s[42:43], s[2:3], vcc
	v_mov_b32_e32 v0, 0
	v_ashrrev_i32_e32 v5, 31, v4
	v_mov_b32_e32 v3, 0
	s_and_saveexec_b64 s[18:19], s[42:43]
	s_cbranch_execz .LBB0_1027
	v_lshlrev_b64 v[14:15], 12, v[4:5]
	v_lshl_add_u64 v[14:15], v[6:7], 0, v[14:15]
	global_load_dword v100, v[14:15], off

; #define LAS __attribute__((address_space(3)))
; DI unsigned pk2(float lo, float hi) { return f2bf(lo) | (f2bf(hi) << 16); }
; #define BIDX() sgpr_opaque((int)__builtin_amdgcn_workgroup_id_x())
; #define GDIM() sgpr_opaque((int)__ockl_get_num_groups(0))
; DI int tid_opaque() { int t = threadIdx.x; asm volatile("" : "+v"(t)); return t; }
; DI void transpose_tiles(const float* src, int ldw, int Ks, bf16_t* dst, int Nn, int Kd, int kind, LAS float* tile) {
;     const int tid = tid_opaque(), ntn = Nn / 64, ntk = Kd / 64;
;     for (int it = BIDX(); it < ntn * ntk; it += GDIM()) {
;         const int n0 = (it % ntn) * 64, k0 = (it / ntn) * 64;
;         { const int nn = tid & 63, kk = tid >> 6; const int off = colmap(kind, n0 + nn);
; #pragma unroll
;           for (int i = 0; i < 8; ++i) { const int k = k0 + kk + 8 * i; float v = 0.f; if (off >= 0 && k < Ks) v = src[(size_t)k * ldw + off]; tile[(kk + 8 * i) * 65 + nn] = v; } }
;         __syncthreads();
;         { const int nn = tid >> 3, kc = tid & 7; const LAS float* s = tile + (kc * 8) * 65 + nn;
;           u32x4 o; o.x = pk2(s[0], s[65]); o.y = pk2(s[2 * 65], s[3 * 65]); o.z = pk2(s[4 * 65], s[5 * 65]); o.w = pk2(s[6 * 65], s[7 * 65]);
;           *(u32x4*)(dst + (size_t)(n0 + nn) * Kd + k0 + kc * 8) = o; }
;         __syncthreads();
.LBB0_1062:
	s_or_b64 exec, exec, s[2:3]
	s_waitcnt vmcnt(0)
	ds_write_b32 v12, v100
	ds_write_b32 v12, v101 offset:2080
	ds_write_b32 v12, v102 offset:4160
	ds_write_b32 v12, v103 offset:6240
	ds_write_b32 v12, v104 offset:8320
	ds_write_b32 v12, v105 offset:10400
	ds_write_b32 v12, v106 offset:12480
	ds_write_b32 v12, v107 offset:14560
	s_waitcnt lgkmcnt(0)
	s_barrier
	ds_read2_b32 v[4:5], v11 offset1:65
	ds_read2_b32 v[6:7], v11 offset0:130 offset1:195
	s_mov_b32 s2, s30
	s_waitcnt lgkmcnt(1)
	v_bfe_u32 v0, v4, 16, 1
	v_add3_u32 v0, v4, v0, s31
	v_bfe_u32 v3, v5, 16, 1
	v_lshrrev_b32_e32 v0, 16, v0
	v_add3_u32 v3, v5, v3, s31
	v_and_or_b32 v4, v3, s0, v0
	v_add_u32_e32 v3, 0x400, v11
	ds_read2_b32 v[14:15], v3 offset0:4 offset1:69
	s_waitcnt lgkmcnt(1)
	v_bfe_u32 v0, v6, 16, 1
	v_add3_u32 v0, v6, v0, s31
	v_bfe_u32 v5, v7, 16, 1
	ds_read2_b32 v[16:17], v3 offset0:134 offset1:199
	v_lshrrev_b32_e32 v0, 16, v0
	v_add3_u32 v5, v7, v5, s31
	v_and_or_b32 v5, v5, s0, v0
	s_waitcnt lgkmcnt(1)
	v_bfe_u32 v0, v14, 16, 1
	v_add3_u32 v0, v14, v0, s31
	v_bfe_u32 v3, v15, 16, 1
	v_lshrrev_b32_e32 v0, 16, v0
	v_add3_u32 v3, v15, v3, s31
	v_add_u32_e32 v14, s15, v10
	v_and_or_b32 v6, v3, s0, v0
	s_waitcnt lgkmcnt(0)
	v_bfe_u32 v0, v16, 16, 1
	v_ashrrev_i32_e32 v15, 31, v14
	v_add3_u32 v0, v16, v0, s31
	v_bfe_u32 v3, v17, 16, 1
	v_lshlrev_b64 v[14:15], 7, v[14:15]
	v_lshrrev_b32_e32 v0, 16, v0
	v_add3_u32 v3, v17, v3, s31
	v_lshl_add_u64 v[14:15], s[4:5], 0, v[14:15]
	s_ashr_i32 s15, s14, 31
	v_and_or_b32 v7, v3, s0, v0
	v_lshl_add_u64 v[14:15], s[14:15], 1, v[14:15]
	v_mov_b32_e32 v3, v1
	v_lshl_add_u64 v[14:15], v[14:15], 0, v[2:3]
	global_store_dwordx4 v[14:15], v[4:7], off
	s_barrier
	s_add_i32 s18, s2, s18
	s_cmp_lt_i32 s18, 16
	s_cbranch_scc0 .LBB0_1079
.LBB0_1063:
	v_mov_b32_e32 v100, 0
	v_mov_b32_e32 v101, 0
	v_mov_b32_e32 v102, 0
	v_mov_b32_e32 v103, 0
	v_mov_b32_e32 v104, 0
	v_mov_b32_e32 v105, 0
	v_mov_b32_e32 v106, 0
	v_mov_b32_e32 v107, 0
	s_ashr_i32 s2, s18, 31
	s_lshr_b32 s2, s2, 28
	s_add_i32 s2, s18, s2
	s_and_b32 s3, s2, -16
	s_sub_i32 s3, s18, s3
	s_lshl_b32 s2, s2, 2
	s_lshl_b32 s15, s3, 6
	s_and_b32 s14, s2, 0xffffffc0
	v_add_u32_e32 v4, s14, v9
	s_cmp_gt_i32 s3, -1
	v_or_b32_e32 v0, s15, v8
	s_cselect_b64 s[2:3], -1, 0
	v_cmp_gt_i32_e32 vcc, 64, v4
	v_lshl_add_u64 v[6:7], v[0:1], 2, s[12:13]
	s_and_b64 s[42:43], s[2:3], vcc
	v_mov_b32_e32 v0, 0
	v_ashrrev_i32_e32 v5, 31, v4
	v_mov_b32_e32 v3, 0
	s_and_saveexec_b64 s[16:17], s[42:43]
	s_cbranch_execz .LBB0_1065
	v_lshlrev_b64 v[14:15], 12, v[4:5]
	v_lshl_add_u64 v[14:15], v[6:7], 0, v[14:15]
	global_load_dword v100, v[14:15], off
.LBB0_1065:
	s_or_b64 exec, exec, s[16:17]
	v_cmp_gt_i32_e32 vcc, 56, v4
	s_and_b64 s[42:43], s[2:3], vcc
	s_and_saveexec_b64 s[16:17], s[42:43]
	s_cbranch_execz .LBB0_1067
	v_lshlrev_b64 v[14:15], 12, v[4:5]
	v_lshl_add_u64 v[14:15], v[6:7], 0, v[14:15]
	v_add_co_u32_e32 v14, vcc, 0x8000, v14
	s_nop 1
	v_addc_co_u32_e32 v15, vcc, 0, v15, vcc
	global_load_dword v101, v[14:15], off
.LBB0_1067:
	s_or_b64 exec, exec, s[16:17]
	v_cmp_gt_i32_e32 vcc, 48, v4
	s_and_b64 s[42:43], s[2:3], vcc
	v_mov_b32_e32 v0, 0
	v_mov_b32_e32 v3, 0
	s_and_saveexec_b64 s[16:17], s[42:43]
	s_cbranch_execz .LBB0_1069
	v_lshlrev_b64 v[14:15], 12, v[4:5]
	v_lshl_add_u64 v[14:15], v[6:7], 0, v[14:15]
	v_add_co_u32_e32 v14, vcc, 0x10000, v14
	s_nop 1
	v_addc_co_u32_e32 v15, vcc, 0, v15, vcc
	global_load_dword v102, v[14:15], off
.LBB0_1069:
	s_or_b64 exec, exec, s[16:17]
	v_cmp_gt_i32_e32 vcc, 40, v4
	s_and_b64 s[42:43], s[2:3], vcc
	s_and_saveexec_b64 s[16:17], s[42:43]
	s_cbranch_execz .LBB0_1071
	v_lshlrev_b64 v[14:15], 12, v[4:5]
	v_lshl_add_u64 v[14:15], v[6:7], 0, v[14:15]
	v_add_co_u32_e32 v14, vcc, 0x18000, v14
	s_nop 1
	v_addc_co_u32_e32 v15, vcc, 0, v15, vcc
	global_load_dword v103, v[14:15], off
.LBB0_1071:
	s_or_b64 exec, exec, s[16:17]
	v_cmp_gt_i32_e32 vcc, 32, v4
	s_and_b64 s[42:43], s[2:3], vcc
	v_mov_b32_e32 v0, 0
	v_mov_b32_e32 v3, 0
	s_and_saveexec_b64 s[16:17], s[42:43]
	s_cbranch_execz .LBB0_1073
	v_lshlrev_b64 v[14:15], 12, v[4:5]
	v_lshl_add_u64 v[14:15], v[6:7], 0, v[14:15]
	v_add_co_u32_e32 v14, vcc, 0x20000, v14
	s_nop 1
	v_addc_co_u32_e32 v15, vcc, 0, v15, vcc
	global_load_dword v104, v[14:15], off
.LBB0_1073:
	s_or_b64 exec, exec, s[16:17]
	v_cmp_gt_i32_e32 vcc, 24, v4
	s_and_b64 s[42:43], s[2:3], vcc
	s_and_saveexec_b64 s[16:17], s[42:43]
	s_cbranch_execz .LBB0_1075
	v_lshlrev_b64 v[14:15], 12, v[4:5]
	v_lshl_add_u64 v[14:15], v[6:7], 0, v[14:15]
	v_add_co_u32_e32 v14, vcc, 0x28000, v14
	s_nop 1
	v_addc_co_u32_e32 v15, vcc, 0, v15, vcc
	global_load_dword v105, v[14:15], off
.LBB0_1075:
	s_or_b64 exec, exec, s[16:17]
	v_cmp_gt_i32_e32 vcc, 16, v4
	s_and_b64 s[42:43], s[2:3], vcc
	v_mov_b32_e32 v0, 0
	v_mov_b32_e32 v3, 0
	s_and_saveexec_b64 s[16:17], s[42:43]
	s_cbranch_execz .LBB0_1077
	v_lshlrev_b64 v[14:15], 12, v[4:5]
	v_lshl_add_u64 v[14:15], v[6:7], 0, v[14:15]
	v_add_co_u32_e32 v14, vcc, 0x30000, v14
	s_nop 1
	v_addc_co_u32_e32 v15, vcc, 0, v15, vcc
	global_load_dword v106, v[14:15], off
.LBB0_1077:
	s_or_b64 exec, exec, s[16:17]
	v_cmp_gt_i32_e32 vcc, 8, v4
	s_and_b64 s[16:17], s[2:3], vcc
	s_and_saveexec_b64 s[2:3], s[16:17]
	s_cbranch_execz .LBB0_1062
	v_lshlrev_b64 v[4:5], 12, v[4:5]
	v_lshl_add_u64 v[4:5], v[6:7], 0, v[4:5]
	v_add_co_u32_e32 v4, vcc, 0x38000, v4
	s_nop 1
	v_addc_co_u32_e32 v5, vcc, 0, v5, vcc
	global_load_dword v107, v[4:5], off
	s_branch .LBB0_1062

; #define LAS __attribute__((address_space(3)))
; DI unsigned pk2(float lo, float hi) { return f2bf(lo) | (f2bf(hi) << 16); }
; #define BIDX() sgpr_opaque((int)__builtin_amdgcn_workgroup_id_x())
; #define GDIM() sgpr_opaque((int)__ockl_get_num_groups(0))
; DI int tid_opaque() { int t = threadIdx.x; asm volatile("" : "+v"(t)); return t; }
; DI void transpose_tiles(const float* src, int ldw, int Ks, bf16_t* dst, int Nn, int Kd, int kind, LAS float* tile) {
;     const int tid = tid_opaque(), ntn = Nn / 64, ntk = Kd / 64;
;     for (int it = BIDX(); it < ntn * ntk; it += GDIM()) {
;         const int n0 = (it % ntn) * 64, k0 = (it / ntn) * 64;
;         { const int nn = tid & 63, kk = tid >> 6; const int off = colmap(kind, n0 + nn);
; #pragma unroll
;           for (int i = 0; i < 8; ++i) { const int k = k0 + kk + 8 * i; float v = 0.f; if (off >= 0 && k < Ks) v = src[(size_t)k * ldw + off]; tile[(kk + 8 * i) * 65 + nn] = v; } }
;         __syncthreads();
;         { const int nn = tid >> 3, kc = tid & 7; const LAS float* s = tile + (kc * 8) * 65 + nn;
;           u32x4 o; o.x = pk2(s[0], s[65]); o.y = pk2(s[2 * 65], s[3 * 65]); o.z = pk2(s[4 * 65], s[5 * 65]); o.w = pk2(s[6 * 65], s[7 * 65]);
;           *(u32x4*)(dst + (size_t)(n0 + nn) * Kd + k0 + kc * 8) = o; }
;         __syncthreads();
;     }
; }
.LBB0_1081:
	s_or_b64 exec, exec, s[2:3]
	s_waitcnt vmcnt(0)
	ds_write_b32 v12, v100
	ds_write_b32 v12, v101 offset:2080
	ds_write_b32 v12, v102 offset:4160
	ds_write_b32 v12, v103 offset:6240
	ds_write_b32 v12, v104 offset:8320
	ds_write_b32 v12, v105 offset:10400
	ds_write_b32 v12, v106 offset:12480
	ds_write_b32 v12, v107 offset:14560
	s_waitcnt lgkmcnt(0)
	s_barrier
	ds_read2_b32 v[4:5], v11 offset1:65
	ds_read2_b32 v[6:7], v11 offset0:130 offset1:195
	s_movk_i32 s2, 0x180
	s_waitcnt lgkmcnt(1)
	v_bfe_u32 v0, v4, 16, 1
	v_add3_u32 v0, v4, v0, s31
	v_bfe_u32 v3, v5, 16, 1
	v_lshrrev_b32_e32 v0, 16, v0
	v_add3_u32 v3, v5, v3, s31
	v_and_or_b32 v4, v3, s0, v0
	v_add_u32_e32 v3, 0x400, v11
	ds_read2_b32 v[14:15], v3 offset0:4 offset1:69
	s_waitcnt lgkmcnt(1)
	v_bfe_u32 v0, v6, 16, 1
	v_add3_u32 v0, v6, v0, s31
	v_bfe_u32 v5, v7, 16, 1
	ds_read2_b32 v[16:17], v3 offset0:134 offset1:199
	v_lshrrev_b32_e32 v0, 16, v0
	v_add3_u32 v5, v7, v5, s31
	v_and_or_b32 v5, v5, s0, v0
	s_waitcnt lgkmcnt(1)
	v_bfe_u32 v0, v14, 16, 1
	v_add3_u32 v0, v14, v0, s31
	v_bfe_u32 v3, v15, 16, 1
	v_lshrrev_b32_e32 v0, 16, v0
	v_add3_u32 v3, v15, v3, s31
	v_and_or_b32 v6, v3, s0, v0
	s_waitcnt lgkmcnt(0)
	v_bfe_u32 v0, v16, 16, 1
	v_add3_u32 v0, v16, v0, s31
	v_bfe_u32 v3, v17, 16, 1
	v_lshrrev_b32_e32 v0, 16, v0
	v_add3_u32 v3, v17, v3, s31
	v_and_or_b32 v7, v3, s0, v0
	v_add_u32_e32 v0, s15, v10
	v_mov_b64_e32 v[14:15], s[12:13]
	v_mad_i64_i32 v[14:15], s[2:3], v0, s2, v[14:15]
	s_ashr_i32 s15, s14, 31
	v_lshl_add_u64 v[14:15], s[14:15], 1, v[14:15]
	v_mov_b32_e32 v3, v1
	v_lshl_add_u64 v[14:15], v[14:15], 0, v[2:3]
	s_mov_b32 s2, s30
	global_store_dwordx4 v[14:15], v[4:7], off
	s_barrier
	s_add_i32 s18, s2, s18
	s_cmp_lt_i32 s18, 48
	s_cbranch_scc0 .LBB0_1098
.LBB0_1082:
	v_mov_b32_e32 v100, 0
	v_mov_b32_e32 v101, 0
	v_mov_b32_e32 v102, 0
	v_mov_b32_e32 v103, 0
	v_mov_b32_e32 v104, 0
	v_mov_b32_e32 v105, 0
	v_mov_b32_e32 v106, 0
	v_mov_b32_e32 v107, 0
	s_ashr_i32 s2, s18, 31
	s_lshr_b32 s2, s2, 28
	s_add_i32 s2, s18, s2
	s_and_b32 s3, s2, -16
	s_sub_i32 s3, s18, s3
	s_lshl_b32 s2, s2, 2
	s_lshl_b32 s15, s3, 6
	s_and_b32 s14, s2, 0xffffffc0
	v_add_u32_e32 v4, s14, v9
	s_cmp_gt_i32 s3, -1
	s_movk_i32 s16, 0xa0
	v_or_b32_e32 v0, s15, v8
	s_cselect_b64 s[2:3], -1, 0
	v_cmp_gt_i32_e32 vcc, s16, v4
	v_lshl_add_u64 v[6:7], v[0:1], 2, s[4:5]
	s_and_b64 s[20:21], s[2:3], vcc
	v_mov_b32_e32 v0, 0
	v_ashrrev_i32_e32 v5, 31, v4
	v_mov_b32_e32 v3, 0
	s_and_saveexec_b64 s[16:17], s[20:21]
	s_cbranch_execz .LBB0_1084
	v_lshlrev_b64 v[14:15], 12, v[4:5]
	v_lshl_add_u64 v[14:15], v[6:7], 0, v[14:15]
	global_load_dword v100, v[14:15], off
.LBB0_1084:
	s_or_b64 exec, exec, s[16:17]
	s_movk_i32 s16, 0x98
	v_cmp_gt_i32_e32 vcc, s16, v4
	s_and_b64 s[20:21], s[2:3], vcc
	s_and_saveexec_b64 s[16:17], s[20:21]
	s_cbranch_execz .LBB0_1086
	v_lshlrev_b64 v[14:15], 12, v[4:5]
	v_lshl_add_u64 v[14:15], v[6:7], 0, v[14:15]
	v_add_co_u32_e32 v14, vcc, 0x8000, v14
	s_nop 1
	v_addc_co_u32_e32 v15, vcc, 0, v15, vcc
	global_load_dword v101, v[14:15], off
.LBB0_1086:
	s_or_b64 exec, exec, s[16:17]
	s_movk_i32 s16, 0x90
	v_cmp_gt_i32_e32 vcc, s16, v4
	s_and_b64 s[20:21], s[2:3], vcc
	v_mov_b32_e32 v0, 0
	v_mov_b32_e32 v3, 0
	s_and_saveexec_b64 s[16:17], s[20:21]
	s_cbranch_execz .LBB0_1088
	v_lshlrev_b64 v[14:15], 12, v[4:5]
	v_lshl_add_u64 v[14:15], v[6:7], 0, v[14:15]
	v_add_co_u32_e32 v14, vcc, 0x10000, v14
	s_nop 1
	v_addc_co_u32_e32 v15, vcc, 0, v15, vcc
	global_load_dword v102, v[14:15], off
.LBB0_1088:
	s_or_b64 exec, exec, s[16:17]
	s_movk_i32 s16, 0x88
	v_cmp_gt_i32_e32 vcc, s16, v4
	s_and_b64 s[20:21], s[2:3], vcc
	s_and_saveexec_b64 s[16:17], s[20:21]
	s_cbranch_execz .LBB0_1090
	v_lshlrev_b64 v[14:15], 12, v[4:5]
	v_lshl_add_u64 v[14:15], v[6:7], 0, v[14:15]
	v_add_co_u32_e32 v14, vcc, 0x18000, v14
	s_nop 1
	v_addc_co_u32_e32 v15, vcc, 0, v15, vcc
	global_load_dword v103, v[14:15], off
.LBB0_1090:
	s_or_b64 exec, exec, s[16:17]
	s_movk_i32 s16, 0x80
	v_cmp_gt_i32_e32 vcc, s16, v4
	s_and_b64 s[20:21], s[2:3], vcc
	v_mov_b32_e32 v0, 0
	v_mov_b32_e32 v3, 0
	s_and_saveexec_b64 s[16:17], s[20:21]
	s_cbranch_execz .LBB0_1092
	v_lshlrev_b64 v[14:15], 12, v[4:5]
	v_lshl_add_u64 v[14:15], v[6:7], 0, v[14:15]
	v_add_co_u32_e32 v14, vcc, 0x20000, v14
	s_nop 1
	v_addc_co_u32_e32 v15, vcc, 0, v15, vcc
	global_load_dword v104, v[14:15], off
.LBB0_1092:
	s_or_b64 exec, exec, s[16:17]
	s_movk_i32 s16, 0x78
	v_cmp_gt_i32_e32 vcc, s16, v4
	s_and_b64 s[20:21], s[2:3], vcc
	s_and_saveexec_b64 s[16:17], s[20:21]
	s_cbranch_execz .LBB0_1094
	v_lshlrev_b64 v[14:15], 12, v[4:5]
	v_lshl_add_u64 v[14:15], v[6:7], 0, v[14:15]
	v_add_co_u32_e32 v14, vcc, 0x28000, v14
	s_nop 1
	v_addc_co_u32_e32 v15, vcc, 0, v15, vcc
	global_load_dword v105, v[14:15], off
.LBB0_1094:
	s_or_b64 exec, exec, s[16:17]
	s_movk_i32 s16, 0x70
	v_cmp_gt_i32_e32 vcc, s16, v4
	s_and_b64 s[20:21], s[2:3], vcc
	v_mov_b32_e32 v0, 0
	v_mov_b32_e32 v3, 0
	s_and_saveexec_b64 s[16:17], s[20:21]
	s_cbranch_execz .LBB0_1096
	v_lshlrev_b64 v[14:15], 12, v[4:5]
	v_lshl_add_u64 v[14:15], v[6:7], 0, v[14:15]
	v_add_co_u32_e32 v14, vcc, 0x30000, v14
	s_nop 1
	v_addc_co_u32_e32 v15, vcc, 0, v15, vcc
	global_load_dword v106, v[14:15], off
.LBB0_1096:
	s_or_b64 exec, exec, s[16:17]
	s_movk_i32 s16, 0x68
	v_cmp_gt_i32_e32 vcc, s16, v4
	s_and_b64 s[16:17], s[2:3], vcc
	s_and_saveexec_b64 s[2:3], s[16:17]
	s_cbranch_execz .LBB0_1081
	v_lshlrev_b64 v[4:5], 12, v[4:5]
	v_lshl_add_u64 v[4:5], v[6:7], 0, v[4:5]
	v_add_co_u32_e32 v4, vcc, 0x38000, v4
	s_nop 1
	v_addc_co_u32_e32 v5, vcc, 0, v5, vcc
	global_load_dword v107, v[4:5], off
	s_branch .LBB0_1081

; #define LAS __attribute__((address_space(3)))
; DI unsigned pk2(float lo, float hi) { return f2bf(lo) | (f2bf(hi) << 16); }
; #define BIDX() sgpr_opaque((int)__builtin_amdgcn_workgroup_id_x())
; #define GDIM() sgpr_opaque((int)__ockl_get_num_groups(0))
; DI int tid_opaque() { int t = threadIdx.x; asm volatile("" : "+v"(t)); return t; }
; DI void transpose_tiles(const float* src, int ldw, int Ks, bf16_t* dst, int Nn, int Kd, int kind, LAS float* tile) {
;     const int tid = tid_opaque(), ntn = Nn / 64, ntk = Kd / 64;
;     for (int it = BIDX(); it < ntn * ntk; it += GDIM()) {
;         const int n0 = (it % ntn) * 64, k0 = (it / ntn) * 64;
;         { const int nn = tid & 63, kk = tid >> 6; const int off = colmap(kind, n0 + nn);
; #pragma unroll
;           for (int i = 0; i < 8; ++i) { const int k = k0 + kk + 8 * i; float v = 0.f; if (off >= 0 && k < Ks) v = src[(size_t)k * ldw + off]; tile[(kk + 8 * i) * 65 + nn] = v; } }
;         __syncthreads();
;         { const int nn = tid >> 3, kc = tid & 7; const LAS float* s = tile + (kc * 8) * 65 + nn;
;           u32x4 o; o.x = pk2(s[0], s[65]); o.y = pk2(s[2 * 65], s[3 * 65]); o.z = pk2(s[4 * 65], s[5 * 65]); o.w = pk2(s[6 * 65], s[7 * 65]);
;           *(u32x4*)(dst + (size_t)(n0 + nn) * Kd + k0 + kc * 8) = o; }
;         __syncthreads();
;     }
; }
.LBB0_1100:
	s_or_b64 exec, exec, s[2:3]
	s_waitcnt vmcnt(0)
	ds_write_b32 v12, v100
	ds_write_b32 v12, v101 offset:2080
	ds_write_b32 v12, v102 offset:4160
	ds_write_b32 v12, v103 offset:6240
	ds_write_b32 v12, v104 offset:8320
	ds_write_b32 v12, v105 offset:10400
	ds_write_b32 v12, v106 offset:12480
	ds_write_b32 v12, v107 offset:14560
	s_waitcnt lgkmcnt(0)
	s_barrier
	ds_read2_b32 v[4:5], v11 offset1:65
	ds_read2_b32 v[6:7], v11 offset0:130 offset1:195
	s_mov_b32 s2, s30
	s_waitcnt lgkmcnt(1)
	v_bfe_u32 v0, v4, 16, 1
	v_add3_u32 v0, v4, v0, s31
	v_bfe_u32 v3, v5, 16, 1
	v_lshrrev_b32_e32 v0, 16, v0
	v_add3_u32 v3, v5, v3, s31
	v_and_or_b32 v4, v3, s0, v0
	v_add_u32_e32 v3, 0x400, v11
	ds_read2_b32 v[14:15], v3 offset0:4 offset1:69
	s_waitcnt lgkmcnt(1)
	v_bfe_u32 v0, v6, 16, 1
	v_add3_u32 v0, v6, v0, s31
	v_bfe_u32 v5, v7, 16, 1
	ds_read2_b32 v[16:17], v3 offset0:134 offset1:199
	v_lshrrev_b32_e32 v0, 16, v0
	v_add3_u32 v5, v7, v5, s31
	v_and_or_b32 v5, v5, s0, v0
	s_waitcnt lgkmcnt(1)
	v_bfe_u32 v0, v14, 16, 1
	v_add3_u32 v0, v14, v0, s31
	v_bfe_u32 v3, v15, 16, 1
	v_lshrrev_b32_e32 v0, 16, v0
	v_add3_u32 v3, v15, v3, s31
	v_add_u32_e32 v14, s13, v10
	v_and_or_b32 v6, v3, s0, v0
	s_waitcnt lgkmcnt(0)
	v_bfe_u32 v0, v16, 16, 1
	v_ashrrev_i32_e32 v15, 31, v14
	v_add3_u32 v0, v16, v0, s31
	v_bfe_u32 v3, v17, 16, 1
	v_lshlrev_b64 v[14:15], 11, v[14:15]
	v_lshrrev_b32_e32 v0, 16, v0
	v_add3_u32 v3, v17, v3, s31
	v_lshl_add_u64 v[14:15], s[10:11], 0, v[14:15]
	s_ashr_i32 s13, s12, 31
	v_and_or_b32 v7, v3, s0, v0
	v_lshl_add_u64 v[14:15], s[12:13], 1, v[14:15]
	v_mov_b32_e32 v3, v1
	v_lshl_add_u64 v[14:15], v[14:15], 0, v[2:3]
	global_store_dwordx4 v[14:15], v[4:7], off
	s_barrier
	s_add_i32 s16, s2, s16
	s_cmpk_lt_i32 s16, 0x100
	s_cbranch_scc0 .LBB0_824
.LBB0_1101:
	v_mov_b32_e32 v100, 0
	v_mov_b32_e32 v101, 0
	v_mov_b32_e32 v102, 0
	v_mov_b32_e32 v103, 0
	v_mov_b32_e32 v104, 0
	v_mov_b32_e32 v105, 0
	v_mov_b32_e32 v106, 0
	v_mov_b32_e32 v107, 0
	s_ashr_i32 s2, s16, 31
	s_lshr_b32 s2, s2, 28
	s_add_i32 s2, s16, s2
	s_and_b32 s3, s2, -16
	s_sub_i32 s3, s16, s3
	s_lshl_b32 s2, s2, 2
	s_lshl_b32 s13, s3, 6
	s_and_b32 s12, s2, 0xffffffc0
	v_add_u32_e32 v4, s12, v9
	s_cmp_gt_i32 s3, -1
	s_movk_i32 s14, 0x400
	v_or_b32_e32 v0, s13, v8
	s_cselect_b64 s[2:3], -1, 0
	v_cmp_gt_i32_e32 vcc, s14, v4
	v_lshl_add_u64 v[6:7], v[0:1], 2, s[4:5]
	s_and_b64 s[18:19], s[2:3], vcc
	v_mov_b32_e32 v0, 0
	v_ashrrev_i32_e32 v5, 31, v4
	v_mov_b32_e32 v3, 0
	s_and_saveexec_b64 s[14:15], s[18:19]
	s_cbranch_execz .LBB0_1103
	v_lshlrev_b64 v[14:15], 12, v[4:5]
	v_lshl_add_u64 v[14:15], v[6:7], 0, v[14:15]
	global_load_dword v100, v[14:15], off
.LBB0_1103:
	s_or_b64 exec, exec, s[14:15]
	s_movk_i32 s14, 0x3f8
	v_cmp_gt_i32_e32 vcc, s14, v4
	s_and_b64 s[18:19], s[2:3], vcc
	s_and_saveexec_b64 s[14:15], s[18:19]
	s_cbranch_execz .LBB0_1105
	v_lshlrev_b64 v[14:15], 12, v[4:5]
	v_lshl_add_u64 v[14:15], v[6:7], 0, v[14:15]
	v_add_co_u32_e32 v14, vcc, 0x8000, v14
	s_nop 1
	v_addc_co_u32_e32 v15, vcc, 0, v15, vcc
	global_load_dword v101, v[14:15], off
.LBB0_1105:
	s_or_b64 exec, exec, s[14:15]
	v_cmp_gt_i32_e32 vcc, s1, v4
	s_and_b64 s[18:19], s[2:3], vcc
	v_mov_b32_e32 v0, 0
	v_mov_b32_e32 v3, 0
	s_and_saveexec_b64 s[14:15], s[18:19]
	s_cbranch_execz .LBB0_1107
	v_lshlrev_b64 v[14:15], 12, v[4:5]
	v_lshl_add_u64 v[14:15], v[6:7], 0, v[14:15]
	v_add_co_u32_e32 v14, vcc, 0x10000, v14
	s_nop 1
	v_addc_co_u32_e32 v15, vcc, 0, v15, vcc
	global_load_dword v102, v[14:15], off
.LBB0_1107:
	s_or_b64 exec, exec, s[14:15]
	s_movk_i32 s14, 0x3e8
	v_cmp_gt_i32_e32 vcc, s14, v4
	s_and_b64 s[18:19], s[2:3], vcc
	s_and_saveexec_b64 s[14:15], s[18:19]
	s_cbranch_execz .LBB0_1109
	v_lshlrev_b64 v[14:15], 12, v[4:5]
	v_lshl_add_u64 v[14:15], v[6:7], 0, v[14:15]
	v_add_co_u32_e32 v14, vcc, 0x18000, v14
	s_nop 1
	v_addc_co_u32_e32 v15, vcc, 0, v15, vcc
	global_load_dword v103, v[14:15], off
.LBB0_1109:
	s_or_b64 exec, exec, s[14:15]
	s_movk_i32 s14, 0x3e0
	v_cmp_gt_i32_e32 vcc, s14, v4
	s_and_b64 s[18:19], s[2:3], vcc
	v_mov_b32_e32 v0, 0
	v_mov_b32_e32 v3, 0
	s_and_saveexec_b64 s[14:15], s[18:19]
	s_cbranch_execz .LBB0_1111
	v_lshlrev_b64 v[14:15], 12, v[4:5]
	v_lshl_add_u64 v[14:15], v[6:7], 0, v[14:15]
	v_add_co_u32_e32 v14, vcc, 0x20000, v14
	s_nop 1
	v_addc_co_u32_e32 v15, vcc, 0, v15, vcc
	global_load_dword v104, v[14:15], off
.LBB0_1111:
	s_or_b64 exec, exec, s[14:15]
	s_movk_i32 s14, 0x3d8
	v_cmp_gt_i32_e32 vcc, s14, v4
	s_and_b64 s[18:19], s[2:3], vcc
	s_and_saveexec_b64 s[14:15], s[18:19]
	s_cbranch_execz .LBB0_1113
	v_lshlrev_b64 v[14:15], 12, v[4:5]
	v_lshl_add_u64 v[14:15], v[6:7], 0, v[14:15]
	v_add_co_u32_e32 v14, vcc, 0x28000, v14
	s_nop 1
	v_addc_co_u32_e32 v15, vcc, 0, v15, vcc
	global_load_dword v105, v[14:15], off
.LBB0_1113:
	s_or_b64 exec, exec, s[14:15]
	s_movk_i32 s14, 0x3d0
	v_cmp_gt_i32_e32 vcc, s14, v4
	s_and_b64 s[18:19], s[2:3], vcc
	v_mov_b32_e32 v0, 0
	v_mov_b32_e32 v3, 0
	s_and_saveexec_b64 s[14:15], s[18:19]
	s_cbranch_execz .LBB0_1115
	v_lshlrev_b64 v[14:15], 12, v[4:5]
	v_lshl_add_u64 v[14:15], v[6:7], 0, v[14:15]
	v_add_co_u32_e32 v14, vcc, 0x30000, v14
	s_nop 1
	v_addc_co_u32_e32 v15, vcc, 0, v15, vcc
	global_load_dword v106, v[14:15], off
.LBB0_1115:
	s_or_b64 exec, exec, s[14:15]
	v_cmp_gt_i32_e32 vcc, s33, v4
	s_and_b64 s[14:15], s[2:3], vcc
	s_and_saveexec_b64 s[2:3], s[14:15]
	s_cbranch_execz .LBB0_1100
	v_lshlrev_b64 v[4:5], 12, v[4:5]
	v_lshl_add_u64 v[4:5], v[6:7], 0, v[4:5]
	v_add_co_u32_e32 v4, vcc, 0x38000, v4
	s_nop 1
	v_addc_co_u32_e32 v5, vcc, 0, v5, vcc
	global_load_dword v107, v[4:5], off
	s_branch .LBB0_1100

; #define LAS __attribute__((address_space(3)))
; DI unsigned pk2(float lo, float hi) { return f2bf(lo) | (f2bf(hi) << 16); }
; #define BIDX() sgpr_opaque((int)__builtin_amdgcn_workgroup_id_x())
; #define GDIM() sgpr_opaque((int)__ockl_get_num_groups(0))
; DI int tid_opaque() { int t = threadIdx.x; asm volatile("" : "+v"(t)); return t; }
; DI void transpose_tiles(const float* src, int ldw, int Ks, bf16_t* dst, int Nn, int Kd, int kind, LAS float* tile) {
;     const int tid = tid_opaque(), ntn = Nn / 64, ntk = Kd / 64;
;     for (int it = BIDX(); it < ntn * ntk; it += GDIM()) {
;         const int n0 = (it % ntn) * 64, k0 = (it / ntn) * 64;
;         { const int nn = tid & 63, kk = tid >> 6; const int off = colmap(kind, n0 + nn);
; #pragma unroll
;           for (int i = 0; i < 8; ++i) { const int k = k0 + kk + 8 * i; float v = 0.f; if (off >= 0 && k < Ks) v = src[(size_t)k * ldw + off]; tile[(kk + 8 * i) * 65 + nn] = v; } }
;         __syncthreads();
;         { const int nn = tid >> 3, kc = tid & 7; const LAS float* s = tile + (kc * 8) * 65 + nn;
;           u32x4 o; o.x = pk2(s[0], s[65]); o.y = pk2(s[2 * 65], s[3 * 65]); o.z = pk2(s[4 * 65], s[5 * 65]); o.w = pk2(s[6 * 65], s[7 * 65]);
;           *(u32x4*)(dst + (size_t)(n0 + nn) * Kd + k0 + kc * 8) = o; }
;         __syncthreads();
;     }
; }
.LBB0_1121:
	s_or_b64 exec, exec, s[2:3]
	s_waitcnt vmcnt(0)
	ds_write_b32 v12, v100
	ds_write_b32 v12, v101 offset:2080
	ds_write_b32 v12, v102 offset:4160
	ds_write_b32 v12, v103 offset:6240
	ds_write_b32 v12, v104 offset:8320
	ds_write_b32 v12, v105 offset:10400
	ds_write_b32 v12, v106 offset:12480
	ds_write_b32 v12, v107 offset:14560
	s_waitcnt lgkmcnt(0)
	s_barrier
	ds_read2_b32 v[4:5], v11 offset1:65
	ds_read2_b32 v[6:7], v11 offset0:130 offset1:195
	s_mov_b32 s2, s30
	s_waitcnt lgkmcnt(1)
	v_bfe_u32 v0, v4, 16, 1
	v_add3_u32 v0, v4, v0, s31
	v_bfe_u32 v3, v5, 16, 1
	v_lshrrev_b32_e32 v0, 16, v0
	v_add3_u32 v3, v5, v3, s31
	v_and_or_b32 v4, v3, s0, v0
	v_add_u32_e32 v3, 0x400, v11
	ds_read2_b32 v[14:15], v3 offset0:4 offset1:69
	s_waitcnt lgkmcnt(1)
	v_bfe_u32 v0, v6, 16, 1
	v_add3_u32 v0, v6, v0, s31
	v_bfe_u32 v5, v7, 16, 1
	ds_read2_b32 v[16:17], v3 offset0:134 offset1:199
	v_lshrrev_b32_e32 v0, 16, v0
	v_add3_u32 v5, v7, v5, s31
	v_and_or_b32 v5, v5, s0, v0
	s_waitcnt lgkmcnt(1)
	v_bfe_u32 v0, v14, 16, 1
	v_add3_u32 v0, v14, v0, s31
	v_bfe_u32 v3, v15, 16, 1
	v_lshrrev_b32_e32 v0, 16, v0
	v_add3_u32 v3, v15, v3, s31
	v_add_u32_e32 v14, s9, v10
	v_and_or_b32 v6, v3, s0, v0
	s_waitcnt lgkmcnt(0)
	v_bfe_u32 v0, v16, 16, 1
	v_ashrrev_i32_e32 v15, 31, v14
	v_add3_u32 v0, v16, v0, s31
	v_bfe_u32 v3, v17, 16, 1
	v_lshlrev_b64 v[14:15], 11, v[14:15]
	v_lshrrev_b32_e32 v0, 16, v0
	v_add3_u32 v3, v17, v3, s31
	v_lshl_add_u64 v[14:15], s[6:7], 0, v[14:15]
	s_ashr_i32 s9, s8, 31
	v_and_or_b32 v7, v3, s0, v0
	v_lshl_add_u64 v[14:15], s[8:9], 1, v[14:15]
	v_mov_b32_e32 v3, v1
	v_lshl_add_u64 v[14:15], v[14:15], 0, v[2:3]
	global_store_dwordx4 v[14:15], v[4:7], off
	s_barrier
	s_add_i32 s17, s2, s17
	s_cmpk_lt_i32 s17, 0x400
	s_cbranch_scc0 .LBB0_1138
.LBB0_1122:
	v_mov_b32_e32 v100, 0
	v_mov_b32_e32 v101, 0
	v_mov_b32_e32 v102, 0
	v_mov_b32_e32 v103, 0
	v_mov_b32_e32 v104, 0
	v_mov_b32_e32 v105, 0
	v_mov_b32_e32 v106, 0
	v_mov_b32_e32 v107, 0
	s_ashr_i32 s2, s17, 31
	s_lshr_b32 s2, s2, 26
	s_add_i32 s2, s17, s2
	s_and_b32 s8, s2, 0xffffffc0
	s_sub_i32 s2, s17, s8
	s_lshl_b32 s9, s2, 6
	v_add_u32_e32 v4, s8, v9
	s_cmp_gt_i32 s2, -1
	s_movk_i32 s10, 0x400
	v_or_b32_e32 v0, s9, v8
	s_cselect_b64 s[2:3], -1, 0
	v_cmp_gt_i32_e32 vcc, s10, v4
	v_lshl_add_u64 v[6:7], v[0:1], 2, s[4:5]
	s_and_b64 s[18:19], s[2:3], vcc
	v_mov_b32_e32 v0, 0
	v_ashrrev_i32_e32 v5, 31, v4
	v_mov_b32_e32 v3, 0
	s_and_saveexec_b64 s[10:11], s[18:19]
	s_cbranch_execz .LBB0_1124
	v_lshlrev_b64 v[14:15], 14, v[4:5]
	v_lshl_add_u64 v[14:15], v[6:7], 0, v[14:15]
	global_load_dword v100, v[14:15], off
.LBB0_1124:
	s_or_b64 exec, exec, s[10:11]
	s_movk_i32 s10, 0x3f8
	v_cmp_gt_i32_e32 vcc, s10, v4
	s_and_b64 s[18:19], s[2:3], vcc
	s_and_saveexec_b64 s[10:11], s[18:19]
	s_cbranch_execz .LBB0_1126
	v_lshlrev_b64 v[14:15], 14, v[4:5]
	v_lshl_add_u64 v[14:15], v[6:7], 0, v[14:15]
	v_add_co_u32_e32 v14, vcc, 0x20000, v14
	s_nop 1
	v_addc_co_u32_e32 v15, vcc, 0, v15, vcc
	global_load_dword v101, v[14:15], off
.LBB0_1126:
	s_or_b64 exec, exec, s[10:11]
	v_cmp_gt_i32_e32 vcc, s1, v4
	s_and_b64 s[18:19], s[2:3], vcc
	v_mov_b32_e32 v0, 0
	v_mov_b32_e32 v3, 0
	s_and_saveexec_b64 s[10:11], s[18:19]
	s_cbranch_execz .LBB0_1128
	v_lshlrev_b64 v[14:15], 14, v[4:5]
	v_lshl_add_u64 v[14:15], v[6:7], 0, v[14:15]
	v_add_co_u32_e32 v14, vcc, 0x40000, v14
	s_nop 1
	v_addc_co_u32_e32 v15, vcc, 0, v15, vcc
	global_load_dword v102, v[14:15], off
.LBB0_1128:
	s_or_b64 exec, exec, s[10:11]
	s_movk_i32 s10, 0x3e8
	v_cmp_gt_i32_e32 vcc, s10, v4
	s_and_b64 s[18:19], s[2:3], vcc
	s_and_saveexec_b64 s[10:11], s[18:19]
	s_cbranch_execz .LBB0_1130
	v_lshlrev_b64 v[14:15], 14, v[4:5]
	v_lshl_add_u64 v[14:15], v[6:7], 0, v[14:15]
	v_add_co_u32_e32 v14, vcc, 0x60000, v14
	s_nop 1
	v_addc_co_u32_e32 v15, vcc, 0, v15, vcc
	global_load_dword v103, v[14:15], off
.LBB0_1130:
	s_or_b64 exec, exec, s[10:11]
	s_movk_i32 s10, 0x3e0
	v_cmp_gt_i32_e32 vcc, s10, v4
	s_and_b64 s[18:19], s[2:3], vcc
	v_mov_b32_e32 v0, 0
	v_mov_b32_e32 v3, 0
	s_and_saveexec_b64 s[10:11], s[18:19]
	s_cbranch_execz .LBB0_1132
	v_lshlrev_b64 v[14:15], 14, v[4:5]
	v_lshl_add_u64 v[14:15], v[6:7], 0, v[14:15]
	v_add_co_u32_e32 v14, vcc, 0x80000, v14
	s_nop 1
	v_addc_co_u32_e32 v15, vcc, 0, v15, vcc
	global_load_dword v104, v[14:15], off
.LBB0_1132:
	s_or_b64 exec, exec, s[10:11]
	s_movk_i32 s10, 0x3d8
	v_cmp_gt_i32_e32 vcc, s10, v4
	s_and_b64 s[18:19], s[2:3], vcc
	s_and_saveexec_b64 s[10:11], s[18:19]
	s_cbranch_execz .LBB0_1134
	v_lshlrev_b64 v[14:15], 14, v[4:5]
	v_lshl_add_u64 v[14:15], v[6:7], 0, v[14:15]
	v_add_co_u32_e32 v14, vcc, 0xa0000, v14
	s_nop 1
	v_addc_co_u32_e32 v15, vcc, 0, v15, vcc
	global_load_dword v105, v[14:15], off
.LBB0_1134:
	s_or_b64 exec, exec, s[10:11]
	s_movk_i32 s10, 0x3d0
	v_cmp_gt_i32_e32 vcc, s10, v4
	s_and_b64 s[18:19], s[2:3], vcc
	v_mov_b32_e32 v0, 0
	v_mov_b32_e32 v3, 0
	s_and_saveexec_b64 s[10:11], s[18:19]
	s_cbranch_execz .LBB0_1136
	v_lshlrev_b64 v[14:15], 14, v[4:5]
	v_lshl_add_u64 v[14:15], v[6:7], 0, v[14:15]
	v_add_co_u32_e32 v14, vcc, 0xc0000, v14
	s_nop 1
	v_addc_co_u32_e32 v15, vcc, 0, v15, vcc
	global_load_dword v106, v[14:15], off
.LBB0_1136:
	s_or_b64 exec, exec, s[10:11]
	v_cmp_gt_i32_e32 vcc, s33, v4
	s_and_b64 s[10:11], s[2:3], vcc
	s_and_saveexec_b64 s[2:3], s[10:11]
	s_cbranch_execz .LBB0_1121
	v_lshlrev_b64 v[4:5], 14, v[4:5]
	v_lshl_add_u64 v[4:5], v[6:7], 0, v[4:5]
	v_add_co_u32_e32 v4, vcc, 0xe0000, v4
	s_nop 1
	v_addc_co_u32_e32 v5, vcc, 0, v5, vcc
	global_load_dword v107, v[4:5], off
	s_branch .LBB0_1121

; #define LAS __attribute__((address_space(3)))
; DI unsigned pk2(float lo, float hi) { return f2bf(lo) | (f2bf(hi) << 16); }
; #define BIDX() sgpr_opaque((int)__builtin_amdgcn_workgroup_id_x())
; #define GDIM() sgpr_opaque((int)__ockl_get_num_groups(0))
; DI int tid_opaque() { int t = threadIdx.x; asm volatile("" : "+v"(t)); return t; }
; DI void transpose_tiles(const float* src, int ldw, int Ks, bf16_t* dst, int Nn, int Kd, int kind, LAS float* tile) {
;     const int tid = tid_opaque(), ntn = Nn / 64, ntk = Kd / 64;
;     for (int it = BIDX(); it < ntn * ntk; it += GDIM()) {
;         const int n0 = (it % ntn) * 64, k0 = (it / ntn) * 64;
;         { const int nn = tid & 63, kk = tid >> 6; const int off = colmap(kind, n0 + nn);
; #pragma unroll
;           for (int i = 0; i < 8; ++i) { const int k = k0 + kk + 8 * i; float v = 0.f; if (off >= 0 && k < Ks) v = src[(size_t)k * ldw + off]; tile[(kk + 8 * i) * 65 + nn] = v; } }
;         __syncthreads();
;         { const int nn = tid >> 3, kc = tid & 7; const LAS float* s = tile + (kc * 8) * 65 + nn;
;           u32x4 o; o.x = pk2(s[0], s[65]); o.y = pk2(s[2 * 65], s[3 * 65]); o.z = pk2(s[4 * 65], s[5 * 65]); o.w = pk2(s[6 * 65], s[7 * 65]);
;           *(u32x4*)(dst + (size_t)(n0 + nn) * Kd + k0 + kc * 8) = o; }
;         __syncthreads();
;     }
; }
.LBB0_1140:
	s_or_b64 exec, exec, s[2:3]
	s_waitcnt vmcnt(0)
	ds_write_b32 v12, v100
	ds_write_b32 v12, v101 offset:2080
	ds_write_b32 v12, v102 offset:4160
	ds_write_b32 v12, v103 offset:6240
	ds_write_b32 v12, v104 offset:8320
	ds_write_b32 v12, v105 offset:10400
	ds_write_b32 v12, v106 offset:12480
	ds_write_b32 v12, v107 offset:14560
	s_waitcnt lgkmcnt(0)
	s_barrier
	ds_read2_b32 v[4:5], v11 offset1:65
	ds_read2_b32 v[6:7], v11 offset0:130 offset1:195
	s_mov_b32 s2, s30
	s_waitcnt lgkmcnt(1)
	v_bfe_u32 v0, v4, 16, 1
	v_add3_u32 v0, v4, v0, s31
	v_bfe_u32 v3, v5, 16, 1
	v_lshrrev_b32_e32 v0, 16, v0
	v_add3_u32 v3, v5, v3, s31
	v_and_or_b32 v4, v3, s0, v0
	v_add_u32_e32 v3, 0x400, v11
	ds_read2_b32 v[14:15], v3 offset0:4 offset1:69
	s_waitcnt lgkmcnt(1)
	v_bfe_u32 v0, v6, 16, 1
	v_add3_u32 v0, v6, v0, s31
	v_bfe_u32 v5, v7, 16, 1
	ds_read2_b32 v[16:17], v3 offset0:134 offset1:199
	v_lshrrev_b32_e32 v0, 16, v0
	v_add3_u32 v5, v7, v5, s31
	v_and_or_b32 v5, v5, s0, v0
	s_waitcnt lgkmcnt(1)
	v_bfe_u32 v0, v14, 16, 1
	v_add3_u32 v0, v14, v0, s31
	v_bfe_u32 v3, v15, 16, 1
	v_lshrrev_b32_e32 v0, 16, v0
	v_add3_u32 v3, v15, v3, s31
	v_add_u32_e32 v14, s9, v10
	v_and_or_b32 v6, v3, s0, v0
	s_waitcnt lgkmcnt(0)
	v_bfe_u32 v0, v16, 16, 1
	v_ashrrev_i32_e32 v15, 31, v14
	v_add3_u32 v0, v16, v0, s31
	v_bfe_u32 v3, v17, 16, 1
	v_lshlrev_b64 v[14:15], 13, v[14:15]
	v_lshrrev_b32_e32 v0, 16, v0
	v_add3_u32 v3, v17, v3, s31
	v_lshl_add_u64 v[14:15], s[6:7], 0, v[14:15]
	s_ashr_i32 s9, s8, 31
	v_and_or_b32 v7, v3, s0, v0
	v_lshl_add_u64 v[14:15], s[8:9], 1, v[14:15]
	v_mov_b32_e32 v3, v1
	v_lshl_add_u64 v[14:15], v[14:15], 0, v[2:3]
	global_store_dwordx4 v[14:15], v[4:7], off
	s_barrier
	s_add_i32 s17, s2, s17
	s_cmpk_lt_i32 s17, 0x400
	s_cbranch_scc0 .LBB0_1118
.LBB0_1141:
	v_mov_b32_e32 v100, 0
	v_mov_b32_e32 v101, 0
	v_mov_b32_e32 v102, 0
	v_mov_b32_e32 v103, 0
	v_mov_b32_e32 v104, 0
	v_mov_b32_e32 v105, 0
	v_mov_b32_e32 v106, 0
	v_mov_b32_e32 v107, 0
	s_ashr_i32 s2, s17, 31
	s_lshr_b32 s2, s2, 28
	s_add_i32 s2, s17, s2
	s_and_b32 s3, s2, -16
	s_sub_i32 s3, s17, s3
	s_lshl_b32 s2, s2, 2
	s_lshl_b32 s9, s3, 6
	s_and_b32 s8, s2, 0xffffffc0
	v_add_u32_e32 v4, s8, v9
	s_cmp_gt_i32 s3, -1
	s_movk_i32 s10, 0x1000
	v_or_b32_e32 v0, s9, v8
	s_cselect_b64 s[2:3], -1, 0
	v_cmp_gt_i32_e32 vcc, s10, v4
	v_lshl_add_u64 v[6:7], v[0:1], 2, s[4:5]
	s_and_b64 s[18:19], s[2:3], vcc
	v_mov_b32_e32 v0, 0
	v_ashrrev_i32_e32 v5, 31, v4
	v_mov_b32_e32 v3, 0
	s_and_saveexec_b64 s[10:11], s[18:19]
	s_cbranch_execz .LBB0_1143
	v_lshlrev_b64 v[14:15], 12, v[4:5]
	v_lshl_add_u64 v[14:15], v[6:7], 0, v[14:15]
	global_load_dword v100, v[14:15], off
.LBB0_1143:
	s_or_b64 exec, exec, s[10:11]
	s_movk_i32 s10, 0xff8
	v_cmp_gt_i32_e32 vcc, s10, v4
	s_and_b64 s[18:19], s[2:3], vcc
	s_and_saveexec_b64 s[10:11], s[18:19]
	s_cbranch_execz .LBB0_1145
	v_lshlrev_b64 v[14:15], 12, v[4:5]
	v_lshl_add_u64 v[14:15], v[6:7], 0, v[14:15]
	v_add_co_u32_e32 v14, vcc, 0x8000, v14
	s_nop 1
	v_addc_co_u32_e32 v15, vcc, 0, v15, vcc
	global_load_dword v101, v[14:15], off
.LBB0_1145:
	s_or_b64 exec, exec, s[10:11]
	s_movk_i32 s10, 0xff0
	v_cmp_gt_i32_e32 vcc, s10, v4
	s_and_b64 s[18:19], s[2:3], vcc
	v_mov_b32_e32 v0, 0
	v_mov_b32_e32 v3, 0
	s_and_saveexec_b64 s[10:11], s[18:19]
	s_cbranch_execz .LBB0_1147
	v_lshlrev_b64 v[14:15], 12, v[4:5]
	v_lshl_add_u64 v[14:15], v[6:7], 0, v[14:15]
	v_add_co_u32_e32 v14, vcc, 0x10000, v14
	s_nop 1
	v_addc_co_u32_e32 v15, vcc, 0, v15, vcc
	global_load_dword v102, v[14:15], off
.LBB0_1147:
	s_or_b64 exec, exec, s[10:11]
	s_movk_i32 s10, 0xfe8
	v_cmp_gt_i32_e32 vcc, s10, v4
	s_and_b64 s[18:19], s[2:3], vcc
	s_and_saveexec_b64 s[10:11], s[18:19]
	s_cbranch_execz .LBB0_1149
	v_lshlrev_b64 v[14:15], 12, v[4:5]
	v_lshl_add_u64 v[14:15], v[6:7], 0, v[14:15]
	v_add_co_u32_e32 v14, vcc, 0x18000, v14
	s_nop 1
	v_addc_co_u32_e32 v15, vcc, 0, v15, vcc
	global_load_dword v103, v[14:15], off
.LBB0_1149:
	s_or_b64 exec, exec, s[10:11]
	s_movk_i32 s10, 0xfe0
	v_cmp_gt_i32_e32 vcc, s10, v4
	s_and_b64 s[18:19], s[2:3], vcc
	v_mov_b32_e32 v0, 0
	v_mov_b32_e32 v3, 0
	s_and_saveexec_b64 s[10:11], s[18:19]
	s_cbranch_execz .LBB0_1151
	v_lshlrev_b64 v[14:15], 12, v[4:5]
	v_lshl_add_u64 v[14:15], v[6:7], 0, v[14:15]
	v_add_co_u32_e32 v14, vcc, 0x20000, v14
	s_nop 1
	v_addc_co_u32_e32 v15, vcc, 0, v15, vcc
	global_load_dword v104, v[14:15], off
.LBB0_1151:
	s_or_b64 exec, exec, s[10:11]
	s_movk_i32 s10, 0xfd8
	v_cmp_gt_i32_e32 vcc, s10, v4
	s_and_b64 s[18:19], s[2:3], vcc
	s_and_saveexec_b64 s[10:11], s[18:19]
	s_cbranch_execz .LBB0_1153
	v_lshlrev_b64 v[14:15], 12, v[4:5]
	v_lshl_add_u64 v[14:15], v[6:7], 0, v[14:15]
	v_add_co_u32_e32 v14, vcc, 0x28000, v14
	s_nop 1
	v_addc_co_u32_e32 v15, vcc, 0, v15, vcc
	global_load_dword v105, v[14:15], off
.LBB0_1153:
	s_or_b64 exec, exec, s[10:11]
	s_movk_i32 s10, 0xfd0
	v_cmp_gt_i32_e32 vcc, s10, v4
	s_and_b64 s[18:19], s[2:3], vcc
	v_mov_b32_e32 v0, 0
	v_mov_b32_e32 v3, 0
	s_and_saveexec_b64 s[10:11], s[18:19]
	s_cbranch_execz .LBB0_1155
	v_lshlrev_b64 v[14:15], 12, v[4:5]
	v_lshl_add_u64 v[14:15], v[6:7], 0, v[14:15]
	v_add_co_u32_e32 v14, vcc, 0x30000, v14
	s_nop 1
	v_addc_co_u32_e32 v15, vcc, 0, v15, vcc
	global_load_dword v106, v[14:15], off
.LBB0_1155:
	s_or_b64 exec, exec, s[10:11]
	s_movk_i32 s10, 0xfc8
	v_cmp_gt_i32_e32 vcc, s10, v4
	s_and_b64 s[10:11], s[2:3], vcc
	s_and_saveexec_b64 s[2:3], s[10:11]
	s_cbranch_execz .LBB0_1140
	v_lshlrev_b64 v[4:5], 12, v[4:5]
	v_lshl_add_u64 v[4:5], v[6:7], 0, v[4:5]
	v_add_co_u32_e32 v4, vcc, 0x38000, v4
	s_nop 1
	v_addc_co_u32_e32 v5, vcc, 0, v5, vcc
	global_load_dword v107, v[4:5], off
	s_branch .LBB0_1140
